# speedup vs baseline: 1.0326x; 1.0119x over previous
; #define G_STAGE(bufoff, gbase, voff) do { _Pragma("unroll") for (int _i = 0; _i < 2; ++_i) \
;     __builtin_amdgcn_global_load_lds((const unsigned*)((const char*)(gbase) + (voff)[_i]), (LAS unsigned*)(lds + (bufoff) + ldsw + _i * 8192), 16, 0, 0); } while (0)
; #define G_LDA(dst, b, h) do { _Pragma("unroll") for (int m = 0; m < 4; ++m) _Pragma("unroll") for (int k = 0; k < 2; ++k) dst[m][k] = *(const LAS bf16x8*)(lds + G_SA(b, h) + aoff + m * 2048 + k * 1024); } while (0)
; #define G_LDB(dst, b, h) do { _Pragma("unroll") for (int n = 0; n < 2; ++n) _Pragma("unroll") for (int k = 0; k < 2; ++k) dst[n][k] = *(const LAS bf16x8*)(lds + G_SB(b, h) + boff + n * 2048 + k * 1024); } while (0)
; #define WAIT_V(n) asm volatile("s_waitcnt vmcnt(" #n ")" ::: "memory")
; #define WAIT_L(n) asm volatile("s_waitcnt lgkmcnt(" #n ")" ::: "memory")
; #define BAR __builtin_amdgcn_s_barrier()
; #define SCHED __builtin_amdgcn_sched_barrier(0)
; template <class Epi>
; __device__ __forceinline__ void gemm_phase(const bf16_t* __restrict__ A, int lda, const bf16_t* __restrict__ Bt, int ldb, int K, int nM, int nN, const Epi& epi, LAS unsigned char* lds, int wv) {
;     ...
;         for (int t = 0; t < nt; t += 2) {
;             const bool last = (t == nt - 2);
;             const char* a1 = cA + (size_t)(t + 1) * kstep;
;             const char* a2 = last ? nA : cA + (size_t)(t + 2) * kstep; const char* b2 = last ? nB : cB + (size_t)(t + 2) * kstep;
;             const char* a3 = a2 + kstep; const char* b3 = b2 + kstep;
;             G_LDB(B0, 0, 0); G_LDB(B1, 0, 1); SCHED; G_LDA(At, 0, 0); G_STAGE(G_SA(1, 1), a1 + hstep, voffA);
;             WAIT_V(8); WAIT_L(0); BAR; G_MMA(0, 0, At, B0); G_MMA(0, 1, At, B1); BAR; SCHED;
;             G_LDA(At, 0, 1); G_STAGE(G_SB(0, 0), b2, voffA); G_STAGE(G_SB(0, 1), b2 + hstep, voffA); G_STAGE(G_SA(0, 0), a2, voffA);
;             WAIT_V(8); WAIT_L(0); BAR; G_MMA(1, 0, At, B0); G_MMA(1, 1, At, B1); BAR; SCHED;
;             G_LDB(B0, 1, 0); G_LDB(B1, 1, 1); SCHED; G_LDA(At, 1, 0); G_STAGE(G_SA(0, 1), a2 + hstep, voffA);
;             WAIT_V(8); WAIT_L(0); BAR; G_MMA(0, 0, At, B0); G_MMA(0, 1, At, B1); BAR; SCHED;
;             G_LDA(At, 1, 1); G_STAGE(G_SB(1, 0), b3, voffA); G_STAGE(G_SB(1, 1), b3 + hstep, voffA); G_STAGE(G_SA(1, 0), a3, voffA);
;             WAIT_V(8); WAIT_L(0); BAR; G_MMA(1, 0, At, B0); G_MMA(1, 1, At, B1); BAR; SCHED;
.LBB0_54:
	s_add_u32 s40, s60, 0x100
	s_addc_u32 s41, s61, 0
	s_add_i32 s30, 0, 0x10000
	s_cmp_eq_u32 vcc_hi, 40
	s_cselect_b32 s69, s57, s41
	s_cselect_b32 s68, s56, s40
	s_cselect_b32 s63, s9, vcc_lo
	s_cselect_b32 s62, s8, s66
	s_add_i32 s46, 0, 0x14000
	v_add_u32_e32 v140, s30, v164
	v_add_u32_e32 v166, s46, v164
	ds_read_b128 v[128:131], v140
	ds_read_b128 v[132:135], v140 offset:1024
	ds_read_b128 v[136:139], v140 offset:2048
	ds_read_b128 v[140:143], v140 offset:3072
	ds_read_b128 v[150:153], v166
	ds_read_b128 v[154:157], v166 offset:1024
	ds_read_b128 v[158:161], v166 offset:2048
	ds_read_b128 v[166:169], v166 offset:3072
	v_lshl_add_u64 v[190:191], s[60:61], 0, v[148:149]
	s_add_i32 m0, s7, 0xc000
	ds_read_b128 v[170:173], v165
	ds_read_b128 v[174:177], v165 offset:1024
	ds_read_b128 v[178:181], v165 offset:2048
	ds_read_b128 v[182:185], v165 offset:3072
	ds_read_b128 v[186:189], v165 offset:4096
	ds_read_b128 v[194:197], v165 offset:5120
	ds_read_b128 v[198:201], v165 offset:6144
	ds_read_b128 v[202:205], v165 offset:7168
	global_load_lds_dwordx4 v[190:191], off
	v_lshl_add_u64 v[190:191], s[60:61], 0, v[146:147]
	s_add_i32 m0, s7, 0xe000
	s_nop 0
	global_load_lds_dwordx4 v[190:191], off
	s_waitcnt vmcnt(8)
	s_waitcnt lgkmcnt(0)
	s_barrier
	s_setprio 1
	s_waitcnt lgkmcnt(0)
	v_mfma_f32_16x16x32_bf16 v[124:127], v[128:131], v[170:173], v[124:127]
	v_mfma_f32_16x16x32_bf16 v[120:123], v[136:139], v[170:173], v[120:123]
	v_mfma_f32_16x16x32_bf16 v[108:111], v[128:131], v[178:181], v[108:111]
	v_mfma_f32_16x16x32_bf16 v[104:107], v[136:139], v[178:181], v[104:107]
	v_mfma_f32_16x16x32_bf16 v[92:95], v[128:131], v[186:189], v[92:95]
	v_mfma_f32_16x16x32_bf16 v[88:91], v[136:139], v[186:189], v[88:91]
	v_mfma_f32_16x16x32_bf16 v[76:79], v[128:131], v[198:201], v[76:79]
	v_mfma_f32_16x16x32_bf16 v[72:75], v[136:139], v[198:201], v[72:75]
	v_mfma_f32_16x16x32_bf16 v[124:127], v[132:135], v[174:177], v[124:127]
	v_mfma_f32_16x16x32_bf16 v[120:123], v[140:143], v[174:177], v[120:123]
	v_mfma_f32_16x16x32_bf16 v[108:111], v[132:135], v[182:185], v[108:111]
	v_mfma_f32_16x16x32_bf16 v[104:107], v[140:143], v[182:185], v[104:107]
	v_mfma_f32_16x16x32_bf16 v[92:95], v[132:135], v[194:197], v[92:95]
	v_mfma_f32_16x16x32_bf16 v[88:91], v[140:143], v[194:197], v[88:91]
	v_mfma_f32_16x16x32_bf16 v[76:79], v[132:135], v[202:205], v[76:79]
	v_mfma_f32_16x16x32_bf16 v[72:75], v[140:143], v[202:205], v[72:75]
	s_setprio 0
	s_setprio 1
	v_mfma_f32_16x16x32_bf16 v[116:119], v[150:153], v[170:173], v[116:119]
	v_mfma_f32_16x16x32_bf16 v[112:115], v[158:161], v[170:173], v[112:115]
	v_mfma_f32_16x16x32_bf16 v[100:103], v[150:153], v[178:181], v[100:103]
	v_mfma_f32_16x16x32_bf16 v[96:99], v[158:161], v[178:181], v[96:99]
	v_mfma_f32_16x16x32_bf16 v[84:87], v[150:153], v[186:189], v[84:87]
	v_mfma_f32_16x16x32_bf16 v[80:83], v[158:161], v[186:189], v[80:83]
	v_mfma_f32_16x16x32_bf16 v[68:71], v[150:153], v[198:201], v[68:71]
	v_mfma_f32_16x16x32_bf16 v[64:67], v[158:161], v[198:201], v[64:67]
	v_mfma_f32_16x16x32_bf16 v[116:119], v[154:157], v[174:177], v[116:119]
	v_mfma_f32_16x16x32_bf16 v[112:115], v[166:169], v[174:177], v[112:115]
	v_mfma_f32_16x16x32_bf16 v[100:103], v[154:157], v[182:185], v[100:103]
	v_mfma_f32_16x16x32_bf16 v[96:99], v[166:169], v[182:185], v[96:99]
	v_mfma_f32_16x16x32_bf16 v[84:87], v[154:157], v[194:197], v[84:87]
	v_mfma_f32_16x16x32_bf16 v[80:83], v[166:169], v[194:197], v[80:83]
	v_mfma_f32_16x16x32_bf16 v[68:71], v[154:157], v[202:205], v[68:71]
	v_mfma_f32_16x16x32_bf16 v[64:67], v[166:169], v[202:205], v[64:67]
	s_setprio 0
	s_barrier
	s_add_i32 s30, s30, s33
	v_lshl_add_u64 v[190:191], s[62:63], 0, v[192:193]
	s_mov_b32 m0, s30
	ds_read_b128 v[170:173], v165 offset:16384
	ds_read_b128 v[174:177], v165 offset:17408
	ds_read_b128 v[178:181], v165 offset:18432
	ds_read_b128 v[182:185], v165 offset:19456
	ds_read_b128 v[186:189], v165 offset:20480
	ds_read_b128 v[194:197], v165 offset:21504
	ds_read_b128 v[198:201], v165 offset:22528
	ds_read_b128 v[202:205], v165 offset:23552
	global_load_lds_dwordx4 v[190:191], off
	s_add_i32 m0, s30, 0x2000
	s_add_u32 s30, s62, 0xb0000
	v_lshl_add_u64 v[206:207], s[62:63], 0, v[144:145]
	s_addc_u32 s31, s63, 0
	s_add_i32 s46, s46, s33
	global_load_lds_dwordx4 v[206:207], off
	v_lshl_add_u64 v[208:209], s[30:31], 0, v[192:193]
	s_mov_b32 m0, s46
	v_lshl_add_u64 v[210:211], s[68:69], 0, v[144:145]
	global_load_lds_dwordx4 v[208:209], off
	v_lshl_add_u64 v[208:209], s[30:31], 0, v[144:145]
	s_add_i32 m0, s46, 0x2000
	s_nop 0
	global_load_lds_dwordx4 v[208:209], off
	v_lshl_add_u64 v[208:209], s[68:69], 0, v[192:193]
	s_mov_b32 m0, s7
	s_nop 0
	global_load_lds_dwordx4 v[208:209], off
	s_mov_b32 m0, s29
	s_nop 0
	global_load_lds_dwordx4 v[210:211], off
	s_waitcnt vmcnt(8)
	s_waitcnt lgkmcnt(0)
	s_barrier
; #define G_STAGE(bufoff, gbase, voff) do { _Pragma("unroll") for (int _i = 0; _i < 2; ++_i) \
;     __builtin_amdgcn_global_load_lds((const unsigned*)((const char*)(gbase) + (voff)[_i]), (LAS unsigned*)(lds + (bufoff) + ldsw + _i * 8192), 16, 0, 0); } while (0)
; #define G_LDA(dst, b, h) do { _Pragma("unroll") for (int m = 0; m < 4; ++m) _Pragma("unroll") for (int k = 0; k < 2; ++k) dst[m][k] = *(const LAS bf16x8*)(lds + G_SA(b, h) + aoff + m * 2048 + k * 1024); } while (0)
; #define G_LDB(dst, b, h) do { _Pragma("unroll") for (int n = 0; n < 2; ++n) _Pragma("unroll") for (int k = 0; k < 2; ++k) dst[n][k] = *(const LAS bf16x8*)(lds + G_SB(b, h) + boff + n * 2048 + k * 1024); } while (0)
; #define G_MMA(ai, bj, At, Bt) do { __builtin_amdgcn_s_setprio(1); _Pragma("unroll") for (int m = 0; m < 4; ++m) _Pragma("unroll") for (int n = 0; n < 2; ++n) _Pragma("unroll") for (int k = 0; k < 2; ++k) \
;     acc[ai][bj][m][n] = __builtin_amdgcn_mfma_f32_16x16x32_bf16(Bt[n][k], At[m][k], acc[ai][bj][m][n], 0, 0, 0); __builtin_amdgcn_s_setprio(0); } while (0)
; #define WAIT_V(n) asm volatile("s_waitcnt vmcnt(" #n ")" ::: "memory")
; #define WAIT_L(n) asm volatile("s_waitcnt lgkmcnt(" #n ")" ::: "memory")
; #define BAR __builtin_amdgcn_s_barrier()
; #define SCHED __builtin_amdgcn_sched_barrier(0)
; template <class Epi>
; __device__ __forceinline__ void gemm_phase(const bf16_t* __restrict__ A, int lda, const bf16_t* __restrict__ Bt, int ldb, int K, int nM, int nN, const Epi& epi, LAS unsigned char* lds, int wv) {
;     ...
;             G_LDB(B0, 0, 0); G_LDB(B1, 0, 1); SCHED; G_LDA(At, 0, 0); G_STAGE(G_SA(1, 1), a1 + hstep, voffA);
;             WAIT_V(8); WAIT_L(0); BAR; G_MMA(0, 0, At, B0); G_MMA(0, 1, At, B1); BAR; SCHED;
;             G_LDA(At, 0, 1); G_STAGE(G_SB(0, 0), b2, voffA); G_STAGE(G_SB(0, 1), b2 + hstep, voffA); G_STAGE(G_SA(0, 0), a2, voffA);
;             WAIT_V(8); WAIT_L(0); BAR; G_MMA(1, 0, At, B0); G_MMA(1, 1, At, B1); BAR; SCHED;
;             G_LDB(B0, 1, 0); G_LDB(B1, 1, 1); SCHED; G_LDA(At, 1, 0); G_STAGE(G_SA(0, 1), a2 + hstep, voffA);
;             WAIT_V(8); WAIT_L(0); BAR; G_MMA(0, 0, At, B0); G_MMA(0, 1, At, B1); BAR; SCHED;
;             G_LDA(At, 1, 1); G_STAGE(G_SB(1, 0), b3, voffA); G_STAGE(G_SB(1, 1), b3 + hstep, voffA); G_STAGE(G_SA(1, 0), a3, voffA);
;             WAIT_V(8); WAIT_L(0); BAR; G_MMA(1, 0, At, B0); G_MMA(1, 1, At, B1); BAR; SCHED;
	s_setprio 1
	s_waitcnt lgkmcnt(0)
	v_mfma_f32_16x16x32_bf16 v[60:63], v[128:131], v[170:173], v[60:63]
	v_mfma_f32_16x16x32_bf16 v[56:59], v[136:139], v[170:173], v[56:59]
	v_mfma_f32_16x16x32_bf16 v[44:47], v[128:131], v[178:181], v[44:47]
	v_mfma_f32_16x16x32_bf16 v[40:43], v[136:139], v[178:181], v[40:43]
	v_mfma_f32_16x16x32_bf16 v[28:31], v[128:131], v[186:189], v[28:31]
	v_mfma_f32_16x16x32_bf16 v[24:27], v[136:139], v[186:189], v[24:27]
	v_mfma_f32_16x16x32_bf16 v[12:15], v[128:131], v[198:201], v[12:15]
	v_mfma_f32_16x16x32_bf16 v[8:11], v[136:139], v[198:201], v[8:11]
	v_mfma_f32_16x16x32_bf16 v[60:63], v[132:135], v[174:177], v[60:63]
	v_mfma_f32_16x16x32_bf16 v[56:59], v[140:143], v[174:177], v[56:59]
	v_mfma_f32_16x16x32_bf16 v[44:47], v[132:135], v[182:185], v[44:47]
	v_mfma_f32_16x16x32_bf16 v[40:43], v[140:143], v[182:185], v[40:43]
	v_mfma_f32_16x16x32_bf16 v[28:31], v[132:135], v[194:197], v[28:31]
	v_mfma_f32_16x16x32_bf16 v[24:27], v[140:143], v[194:197], v[24:27]
	v_mfma_f32_16x16x32_bf16 v[12:15], v[132:135], v[202:205], v[12:15]
	v_mfma_f32_16x16x32_bf16 v[8:11], v[140:143], v[202:205], v[8:11]
	s_setprio 0
	s_setprio 1
	v_mfma_f32_16x16x32_bf16 v[52:55], v[150:153], v[170:173], v[52:55]
	v_mfma_f32_16x16x32_bf16 v[48:51], v[158:161], v[170:173], v[48:51]
	v_mfma_f32_16x16x32_bf16 v[36:39], v[150:153], v[178:181], v[36:39]
	v_mfma_f32_16x16x32_bf16 v[32:35], v[158:161], v[178:181], v[32:35]
	v_mfma_f32_16x16x32_bf16 v[20:23], v[150:153], v[186:189], v[20:23]
	v_mfma_f32_16x16x32_bf16 v[16:19], v[158:161], v[186:189], v[16:19]
	v_mfma_f32_16x16x32_bf16 v[4:7], v[150:153], v[198:201], v[4:7]
	v_mfma_f32_16x16x32_bf16 v[0:3], v[158:161], v[198:201], v[0:3]
	v_mfma_f32_16x16x32_bf16 v[52:55], v[154:157], v[174:177], v[52:55]
	v_mfma_f32_16x16x32_bf16 v[48:51], v[166:169], v[174:177], v[48:51]
	v_mfma_f32_16x16x32_bf16 v[36:39], v[154:157], v[182:185], v[36:39]
	v_mfma_f32_16x16x32_bf16 v[32:35], v[166:169], v[182:185], v[32:35]
	v_mfma_f32_16x16x32_bf16 v[20:23], v[154:157], v[194:197], v[20:23]
	v_mfma_f32_16x16x32_bf16 v[16:19], v[166:169], v[194:197], v[16:19]
	v_mfma_f32_16x16x32_bf16 v[4:7], v[154:157], v[202:205], v[4:7]
	v_mfma_f32_16x16x32_bf16 v[0:3], v[166:169], v[202:205], v[0:3]
	s_setprio 0
	s_barrier
	s_add_i32 s46, 0, 0x18000
	s_add_i32 s47, 0, 0x1c000
	v_add_u32_e32 v140, s46, v164
	v_add_u32_e32 v166, s47, v164
	ds_read_b128 v[128:131], v140
	ds_read_b128 v[132:135], v140 offset:1024
	ds_read_b128 v[136:139], v140 offset:2048
	ds_read_b128 v[140:143], v140 offset:3072
	ds_read_b128 v[150:153], v166
	ds_read_b128 v[154:157], v166 offset:1024
	ds_read_b128 v[158:161], v166 offset:2048
	ds_read_b128 v[166:169], v166 offset:3072
	s_add_u32 s30, s68, 0xb0000
	s_addc_u32 s31, s69, 0
	s_mov_b32 m0, s38
	v_lshl_add_u64 v[212:213], s[30:31], 0, v[192:193]
	ds_read_b128 v[170:173], v165 offset:32768
	ds_read_b128 v[174:177], v165 offset:33792
	ds_read_b128 v[178:181], v165 offset:34816
	ds_read_b128 v[182:185], v165 offset:35840
	ds_read_b128 v[186:189], v165 offset:36864
	ds_read_b128 v[194:197], v165 offset:37888
	ds_read_b128 v[198:201], v165 offset:38912
	ds_read_b128 v[202:205], v165 offset:39936
	global_load_lds_dwordx4 v[212:213], off
	v_lshl_add_u64 v[212:213], s[30:31], 0, v[144:145]
	s_mov_b32 m0, s39
	s_nop 0
	global_load_lds_dwordx4 v[212:213], off
	s_waitcnt vmcnt(8)
	s_waitcnt lgkmcnt(0)
	s_barrier
	s_setprio 1
	s_waitcnt lgkmcnt(0)
	v_mfma_f32_16x16x32_bf16 v[124:127], v[128:131], v[170:173], v[124:127]
	v_mfma_f32_16x16x32_bf16 v[120:123], v[136:139], v[170:173], v[120:123]
	v_mfma_f32_16x16x32_bf16 v[108:111], v[128:131], v[178:181], v[108:111]
	v_mfma_f32_16x16x32_bf16 v[104:107], v[136:139], v[178:181], v[104:107]
	v_mfma_f32_16x16x32_bf16 v[92:95], v[128:131], v[186:189], v[92:95]
	v_mfma_f32_16x16x32_bf16 v[88:91], v[136:139], v[186:189], v[88:91]
	v_mfma_f32_16x16x32_bf16 v[76:79], v[128:131], v[198:201], v[76:79]
	v_mfma_f32_16x16x32_bf16 v[72:75], v[136:139], v[198:201], v[72:75]
	v_mfma_f32_16x16x32_bf16 v[124:127], v[132:135], v[174:177], v[124:127]
	v_mfma_f32_16x16x32_bf16 v[120:123], v[140:143], v[174:177], v[120:123]
	v_mfma_f32_16x16x32_bf16 v[108:111], v[132:135], v[182:185], v[108:111]
	v_mfma_f32_16x16x32_bf16 v[104:107], v[140:143], v[182:185], v[104:107]
	v_mfma_f32_16x16x32_bf16 v[92:95], v[132:135], v[194:197], v[92:95]
	v_mfma_f32_16x16x32_bf16 v[88:91], v[140:143], v[194:197], v[88:91]
	v_mfma_f32_16x16x32_bf16 v[76:79], v[132:135], v[202:205], v[76:79]
	v_mfma_f32_16x16x32_bf16 v[72:75], v[140:143], v[202:205], v[72:75]
	s_setprio 0
	s_setprio 1
	v_mfma_f32_16x16x32_bf16 v[116:119], v[150:153], v[170:173], v[116:119]
	v_mfma_f32_16x16x32_bf16 v[112:115], v[158:161], v[170:173], v[112:115]
	v_mfma_f32_16x16x32_bf16 v[100:103], v[150:153], v[178:181], v[100:103]
	v_mfma_f32_16x16x32_bf16 v[96:99], v[158:161], v[178:181], v[96:99]
	v_mfma_f32_16x16x32_bf16 v[84:87], v[150:153], v[186:189], v[84:87]
	v_mfma_f32_16x16x32_bf16 v[80:83], v[158:161], v[186:189], v[80:83]
	v_mfma_f32_16x16x32_bf16 v[68:71], v[150:153], v[198:201], v[68:71]
	v_mfma_f32_16x16x32_bf16 v[64:67], v[158:161], v[198:201], v[64:67]
	v_mfma_f32_16x16x32_bf16 v[116:119], v[154:157], v[174:177], v[116:119]
	v_mfma_f32_16x16x32_bf16 v[112:115], v[166:169], v[174:177], v[112:115]
	v_mfma_f32_16x16x32_bf16 v[100:103], v[154:157], v[182:185], v[100:103]
	v_mfma_f32_16x16x32_bf16 v[96:99], v[166:169], v[182:185], v[96:99]
	v_mfma_f32_16x16x32_bf16 v[84:87], v[154:157], v[194:197], v[84:87]
	v_mfma_f32_16x16x32_bf16 v[80:83], v[166:169], v[194:197], v[80:83]
	v_mfma_f32_16x16x32_bf16 v[68:71], v[154:157], v[202:205], v[68:71]
	v_mfma_f32_16x16x32_bf16 v[64:67], v[166:169], v[202:205], v[64:67]
	s_setprio 0
	s_barrier
; #define WAIT_V(n) asm volatile("s_waitcnt vmcnt(" #n ")" ::: "memory")
; template <class Epi>
; __device__ __forceinline__ void gemm_phase(const bf16_t* __restrict__ A, int lda, const bf16_t* __restrict__ Bt, int ldb, int K, int nM, int nN, const Epi& epi, LAS unsigned char* lds, int wv) {
;     ...
;             WAIT_V(8); WAIT_L(0); BAR; G_MMA(1, 0, At, B0); G_MMA(1, 1, At, B1); BAR; SCHED;
;             G_LDB(B0, 1, 0); G_LDB(B1, 1, 1); SCHED; G_LDA(At, 1, 0); G_STAGE(G_SA(0, 1), a2 + hstep, voffA);
;             WAIT_V(8); WAIT_L(0); BAR; G_MMA(0, 0, At, B0); G_MMA(0, 1, At, B1); BAR; SCHED;
;             G_LDA(At, 1, 1); G_STAGE(G_SB(1, 0), b3, voffA); G_STAGE(G_SB(1, 1), b3 + hstep, voffA); G_STAGE(G_SA(1, 0), a3, voffA);
;             WAIT_V(8); WAIT_L(0); BAR; G_MMA(1, 0, At, B0); G_MMA(1, 1, At, B1); BAR; SCHED;
;         }
;         { int efr = fr, efq = fq; asm volatile("" : "+v"(efr), "+v"(efq));
;           epi(acc, pm, pn, wr, wc, efr, efq); }
;     __device__ __forceinline__ void operator()(AccRef acc, int pm, int pn, int wr, int wc, int fr, int fq) const {
;     ...
;             for (int m = 0; m < 4; ++m) { const int row = EPI_ROW(ai, m); const float* gp = gate + (size_t)(row >> 12) * 9216; const size_t ro = (size_t)row * 1024;
; #pragma unroll
;                 for (int bj = 0; bj < 2; ++bj) { const int col = pn * 256 + wc * 64 + bj * 32 + 8 * fq;
;                     const f32x4 g0 = *(const f32x4*)(gp + col), g1 = *(const f32x4*)(gp + col + 4);
;                     f32x4 x0, x1;
;                     if (mode == 0) { x0 = *(const f32x4*)(xin_f + ro + col); x1 = *(const f32x4*)(xin_f + ro + col + 4); }
;                     else { const h16x8 h = *(const h16x8*)(xh + ro + col); x0 = (f32x4){(float)h[0], (float)h[1], (float)h[2], (float)h[3]}; x1 = (f32x4){(float)h[4], (float)h[5], (float)h[6], (float)h[7]}; }
;                     const f32x4 y0 = x0 + gs * g0 * acc[ai][bj][m][0], y1 = x1 + gs * g1 * acc[ai][bj][m][1];
;                     if (mode == 2) { *(f32x4*)(xout_f + ro + col) = y0; *(f32x4*)(xout_f + ro + col + 4) = y1; }
;                     else { h16x8 h; h[0] = (_Float16)y0[0]; h[1] = (_Float16)y0[1]; h[2] = (_Float16)y0[2]; h[3] = (_Float16)y0[3]; h[4] = (_Float16)y1[0]; h[5] = (_Float16)y1[1]; h[6] = (_Float16)y1[2]; h[7] = (_Float16)y1[3];
;                         *(h16x8*)(xh + ro + col) = h; } } }
	s_add_i32 s30, s46, s33
	v_lshl_add_u64 v[190:191], v[190:191], 0, s[10:11]
	s_mov_b32 m0, s30
	ds_read_b128 v[170:173], v165 offset:49152
	ds_read_b128 v[174:177], v165 offset:50176
	ds_read_b128 v[178:181], v165 offset:51200
	ds_read_b128 v[182:185], v165 offset:52224
	ds_read_b128 v[186:189], v165 offset:53248
	ds_read_b128 v[194:197], v165 offset:54272
	ds_read_b128 v[198:201], v165 offset:55296
	ds_read_b128 v[202:205], v165 offset:56320
	global_load_lds_dwordx4 v[190:191], off
	s_add_i32 m0, s30, 0x2000
	s_add_u32 s30, s62, 0xb0080
	v_lshl_add_u64 v[190:191], v[206:207], 0, s[10:11]
	s_addc_u32 s31, s63, 0
	s_add_i32 s46, s47, s33
	global_load_lds_dwordx4 v[190:191], off
	v_lshl_add_u64 v[190:191], s[30:31], 0, v[192:193]
	s_mov_b32 m0, s46
	s_nop 0
	global_load_lds_dwordx4 v[190:191], off
	v_lshl_add_u64 v[190:191], s[30:31], 0, v[144:145]
	s_add_i32 m0, s46, 0x2000
	s_nop 0
	global_load_lds_dwordx4 v[190:191], off
	v_lshl_add_u64 v[190:191], v[208:209], 0, s[10:11]
	s_mov_b32 m0, s71
	s_nop 0
	global_load_lds_dwordx4 v[190:191], off
	v_lshl_add_u64 v[190:191], v[210:211], 0, s[10:11]
	s_mov_b32 m0, s72
	s_nop 0
	global_load_lds_dwordx4 v[190:191], off
	s_waitcnt vmcnt(8)
	s_waitcnt lgkmcnt(0)
	s_barrier
	s_setprio 1
	s_waitcnt lgkmcnt(0)
	v_mfma_f32_16x16x32_bf16 v[60:63], v[128:131], v[170:173], v[60:63]
	v_mfma_f32_16x16x32_bf16 v[56:59], v[136:139], v[170:173], v[56:59]
	v_mfma_f32_16x16x32_bf16 v[44:47], v[128:131], v[178:181], v[44:47]
	v_mfma_f32_16x16x32_bf16 v[40:43], v[136:139], v[178:181], v[40:43]
	v_mfma_f32_16x16x32_bf16 v[28:31], v[128:131], v[186:189], v[28:31]
	v_mfma_f32_16x16x32_bf16 v[24:27], v[136:139], v[186:189], v[24:27]
	v_mfma_f32_16x16x32_bf16 v[12:15], v[128:131], v[198:201], v[12:15]
	v_mfma_f32_16x16x32_bf16 v[8:11], v[136:139], v[198:201], v[8:11]
	v_mfma_f32_16x16x32_bf16 v[60:63], v[132:135], v[174:177], v[60:63]
	v_mfma_f32_16x16x32_bf16 v[56:59], v[140:143], v[174:177], v[56:59]
	v_mfma_f32_16x16x32_bf16 v[44:47], v[132:135], v[182:185], v[44:47]
	v_mfma_f32_16x16x32_bf16 v[40:43], v[140:143], v[182:185], v[40:43]
	v_mfma_f32_16x16x32_bf16 v[28:31], v[132:135], v[194:197], v[28:31]
	v_mfma_f32_16x16x32_bf16 v[24:27], v[140:143], v[194:197], v[24:27]
	v_mfma_f32_16x16x32_bf16 v[12:15], v[132:135], v[202:205], v[12:15]
	v_mfma_f32_16x16x32_bf16 v[8:11], v[140:143], v[202:205], v[8:11]
	s_setprio 0
	s_setprio 1
	v_mfma_f32_16x16x32_bf16 v[52:55], v[150:153], v[170:173], v[52:55]
	v_mfma_f32_16x16x32_bf16 v[48:51], v[158:161], v[170:173], v[48:51]
	v_mfma_f32_16x16x32_bf16 v[36:39], v[150:153], v[178:181], v[36:39]
	v_mfma_f32_16x16x32_bf16 v[32:35], v[158:161], v[178:181], v[32:35]
	v_mfma_f32_16x16x32_bf16 v[20:23], v[150:153], v[186:189], v[20:23]
	v_mfma_f32_16x16x32_bf16 v[16:19], v[158:161], v[186:189], v[16:19]
	v_mfma_f32_16x16x32_bf16 v[4:7], v[150:153], v[198:201], v[4:7]
	v_mfma_f32_16x16x32_bf16 v[0:3], v[158:161], v[198:201], v[0:3]
	v_mfma_f32_16x16x32_bf16 v[52:55], v[154:157], v[174:177], v[52:55]
	v_mfma_f32_16x16x32_bf16 v[48:51], v[166:169], v[174:177], v[48:51]
	v_mfma_f32_16x16x32_bf16 v[36:39], v[154:157], v[182:185], v[36:39]
	v_mfma_f32_16x16x32_bf16 v[32:35], v[166:169], v[182:185], v[32:35]
	v_mfma_f32_16x16x32_bf16 v[20:23], v[154:157], v[194:197], v[20:23]
	v_mfma_f32_16x16x32_bf16 v[16:19], v[166:169], v[194:197], v[16:19]
	v_mfma_f32_16x16x32_bf16 v[4:7], v[154:157], v[202:205], v[4:7]
	v_mfma_f32_16x16x32_bf16 v[0:3], v[166:169], v[202:205], v[0:3]
	s_setprio 0
	s_barrier
	s_add_i32 vcc_hi, vcc_hi, 2
	s_add_u32 s66, s66, 0x100
	s_addc_u32 vcc_lo, vcc_lo, 0
	s_cmp_gt_u32 vcc_hi, 41
	s_mov_b64 s[60:61], s[40:41]
	s_cbranch_scc0 .LBB0_54
	s_lshl_b32 s8, s94, 8
	v_readlane_b32 s9, v253, 5
	v_mov_b32_e32 v128, v163
	v_mov_b32_e32 v129, v162
	s_add_i32 s8, s8, s9
	v_readlane_b32 s9, v253, 19
	v_add_u32_e32 v152, s8, v129
	s_lshl_b32 s8, s95, 8
	s_or_b32 s8, s8, s9
	v_lshl_add_u32 v150, v128, 3, s8
	s_andn2_b64 vcc, exec, s[52:53]
	s_cbranch_vccnz .Lepi_ffo_m2
	s_and_b64 vcc, exec, s[36:37]
	s_cbranch_vccnz .Lepi_ffo_m0
	v_ashrrev_i32_e32 v154, 12, v152
	v_mul_hi_i32_i24_e32 v155, 0x9000, v154
	v_mul_i32_i24_e32 v154, 0x9000, v154
	v_lshl_add_u64 v[154:155], s[50:51], 0, v[154:155]
	v_ashrrev_i32_e32 v151, 31, v150
	v_lshl_add_u64 v[158:159], v[150:151], 2, v[154:155]
	global_load_dwordx4 v[128:131], v[158:159], off
	global_load_dwordx4 v[132:135], v[158:159], off offset:16
	global_load_dwordx4 v[136:139], v[158:159], off offset:128
	global_load_dwordx4 v[140:143], v[158:159], off offset:144
	v_lshlrev_b32_e32 v153, 11, v152
	v_lshl_add_u32 v153, v150, 1, v153
	v_lshlrev_b32_e32 v156, 12, v152
	v_lshl_add_u32 v156, v150, 2, v156
	s_movk_i32 s66, 0x3ff
	global_load_dwordx4 v[166:169], v153, s[26:27]
	global_load_dwordx4 v[170:173], v153, s[26:27] offset:64
	v_add_u32_e32 v154, 0x8000, v153
	global_load_dwordx4 v[174:177], v154, s[26:27]
	v_add_u32_e32 v154, 0x8000, v153
	global_load_dwordx4 v[178:181], v154, s[26:27] offset:64
	v_add_u32_e32 v154, 0x10000, v153
	global_load_dwordx4 v[182:185], v154, s[26:27]
	v_add_u32_e32 v154, 0x10000, v153
	global_load_dwordx4 v[186:189], v154, s[26:27] offset:64
	v_add_u32_e32 v154, 0x18000, v153
	global_load_dwordx4 v[194:197], v154, s[26:27]
	v_add_u32_e32 v154, 0x18000, v153
	global_load_dwordx4 v[198:201], v154, s[26:27] offset:64
	s_waitcnt vmcnt(8)
	v_pk_mul_f32 v[128:129], v[128:129], 0.5 op_sel_hi:[1,0]
	v_pk_mul_f32 v[130:131], v[130:131], 0.5 op_sel_hi:[1,0]
	v_pk_mul_f32 v[132:133], v[132:133], 0.5 op_sel_hi:[1,0]
	v_pk_mul_f32 v[134:135], v[134:135], 0.5 op_sel_hi:[1,0]
	v_pk_mul_f32 v[136:137], v[136:137], 0.5 op_sel_hi:[1,0]
	v_pk_mul_f32 v[138:139], v[138:139], 0.5 op_sel_hi:[1,0]
	v_pk_mul_f32 v[140:141], v[140:141], 0.5 op_sel_hi:[1,0]
	v_pk_mul_f32 v[142:143], v[142:143], 0.5 op_sel_hi:[1,0]
	s_waitcnt vmcnt(7)
;     __device__ __forceinline__ void operator()(AccRef acc, int pm, int pn, int wr, int wc, int fr, int fq) const {
;     ...
;             for (int m = 0; m < 4; ++m) { const int row = EPI_ROW(ai, m); const float* gp = gate + (size_t)(row >> 12) * 9216; const size_t ro = (size_t)row * 1024;
; #pragma unroll
;                 for (int bj = 0; bj < 2; ++bj) { const int col = pn * 256 + wc * 64 + bj * 32 + 8 * fq;
;                     const f32x4 g0 = *(const f32x4*)(gp + col), g1 = *(const f32x4*)(gp + col + 4);
;                     f32x4 x0, x1;
;                     if (mode == 0) { x0 = *(const f32x4*)(xin_f + ro + col); x1 = *(const f32x4*)(xin_f + ro + col + 4); }
;                     else { const h16x8 h = *(const h16x8*)(xh + ro + col); x0 = (f32x4){(float)h[0], (float)h[1], (float)h[2], (float)h[3]}; x1 = (f32x4){(float)h[4], (float)h[5], (float)h[6], (float)h[7]}; }
;                     const f32x4 y0 = x0 + gs * g0 * acc[ai][bj][m][0], y1 = x1 + gs * g1 * acc[ai][bj][m][1];
;                     if (mode == 2) { *(f32x4*)(xout_f + ro + col) = y0; *(f32x4*)(xout_f + ro + col + 4) = y1; }
;                     else { h16x8 h; h[0] = (_Float16)y0[0]; h[1] = (_Float16)y0[1]; h[2] = (_Float16)y0[2]; h[3] = (_Float16)y0[3]; h[4] = (_Float16)y1[0]; h[5] = (_Float16)y1[1]; h[6] = (_Float16)y1[2]; h[7] = (_Float16)y1[3];
;                         *(h16x8*)(xh + ro + col) = h; } } }
	v_cvt_f32_f16_e32 v202, v166
	v_cvt_f32_f16_sdwa v203, v166 dst_sel:DWORD dst_unused:UNUSED_PAD src0_sel:WORD_1
	v_cvt_f32_f16_e32 v204, v167
	v_cvt_f32_f16_sdwa v205, v167 dst_sel:DWORD dst_unused:UNUSED_PAD src0_sel:WORD_1
	v_cvt_f32_f16_e32 v206, v168
	v_cvt_f32_f16_sdwa v207, v168 dst_sel:DWORD dst_unused:UNUSED_PAD src0_sel:WORD_1
	v_cvt_f32_f16_e32 v208, v169
	v_cvt_f32_f16_sdwa v209, v169 dst_sel:DWORD dst_unused:UNUSED_PAD src0_sel:WORD_1
	v_pk_fma_f32 v[126:127], v[126:127], v[130:131], v[204:205]
	v_pk_fma_f32 v[124:125], v[124:125], v[128:129], v[202:203]
	v_pk_fma_f32 v[122:123], v[122:123], v[134:135], v[208:209]
	v_pk_fma_f32 v[120:121], v[120:121], v[132:133], v[206:207]
	v_cvt_pk_f16_f32 v169, v122, v123
	v_cvt_pk_f16_f32 v168, v120, v121
	v_cvt_pk_f16_f32 v167, v126, v127
	v_cvt_pk_f16_f32 v166, v124, v125
	global_store_dwordx4 v153, v[166:169], s[26:27]
	s_nop 1
	v_add_u32_e32 v154, 0x40000, v153
	global_load_dwordx4 v[166:169], v154, s[26:27]
	s_waitcnt vmcnt(8)
	v_cvt_f32_f16_e32 v202, v170
	v_cvt_f32_f16_sdwa v203, v170 dst_sel:DWORD dst_unused:UNUSED_PAD src0_sel:WORD_1
	v_cvt_f32_f16_e32 v204, v171
	v_cvt_f32_f16_sdwa v205, v171 dst_sel:DWORD dst_unused:UNUSED_PAD src0_sel:WORD_1
	v_cvt_f32_f16_e32 v206, v172
	v_cvt_f32_f16_sdwa v207, v172 dst_sel:DWORD dst_unused:UNUSED_PAD src0_sel:WORD_1
	v_cvt_f32_f16_e32 v208, v173
	v_cvt_f32_f16_sdwa v209, v173 dst_sel:DWORD dst_unused:UNUSED_PAD src0_sel:WORD_1
	v_pk_fma_f32 v[118:119], v[118:119], v[138:139], v[204:205]
	v_pk_fma_f32 v[116:117], v[116:117], v[136:137], v[202:203]
	v_pk_fma_f32 v[114:115], v[114:115], v[142:143], v[208:209]
	v_pk_fma_f32 v[112:113], v[112:113], v[140:141], v[206:207]
	v_cvt_pk_f16_f32 v173, v114, v115
	v_cvt_pk_f16_f32 v172, v112, v113
	v_cvt_pk_f16_f32 v171, v118, v119
	v_cvt_pk_f16_f32 v170, v116, v117
	global_store_dwordx4 v153, v[170:173], s[26:27] offset:64
	s_nop 1
	v_add_u32_e32 v154, 0x40000, v153
	global_load_dwordx4 v[170:173], v154, s[26:27] offset:64
	s_waitcnt vmcnt(9)
	v_cvt_f32_f16_e32 v202, v174
	v_cvt_f32_f16_sdwa v203, v174 dst_sel:DWORD dst_unused:UNUSED_PAD src0_sel:WORD_1
	v_cvt_f32_f16_e32 v204, v175
	v_cvt_f32_f16_sdwa v205, v175 dst_sel:DWORD dst_unused:UNUSED_PAD src0_sel:WORD_1
	v_cvt_f32_f16_e32 v206, v176
	v_cvt_f32_f16_sdwa v207, v176 dst_sel:DWORD dst_unused:UNUSED_PAD src0_sel:WORD_1
	v_cvt_f32_f16_e32 v208, v177
	v_cvt_f32_f16_sdwa v209, v177 dst_sel:DWORD dst_unused:UNUSED_PAD src0_sel:WORD_1
	v_pk_fma_f32 v[110:111], v[110:111], v[130:131], v[204:205]
	v_pk_fma_f32 v[108:109], v[108:109], v[128:129], v[202:203]
	v_pk_fma_f32 v[106:107], v[106:107], v[134:135], v[208:209]
	v_pk_fma_f32 v[104:105], v[104:105], v[132:133], v[206:207]
	v_cvt_pk_f16_f32 v177, v106, v107
	v_cvt_pk_f16_f32 v176, v104, v105
	v_cvt_pk_f16_f32 v175, v110, v111
	v_cvt_pk_f16_f32 v174, v108, v109
	v_add_u32_e32 v155, 0x8000, v153
	global_store_dwordx4 v155, v[174:177], s[26:27]
	s_nop 1
	v_add_u32_e32 v154, 0x48000, v153
	global_load_dwordx4 v[174:177], v154, s[26:27]
	s_waitcnt vmcnt(10)
	v_cvt_f32_f16_e32 v202, v178
	v_cvt_f32_f16_sdwa v203, v178 dst_sel:DWORD dst_unused:UNUSED_PAD src0_sel:WORD_1
	v_cvt_f32_f16_e32 v204, v179
	v_cvt_f32_f16_sdwa v205, v179 dst_sel:DWORD dst_unused:UNUSED_PAD src0_sel:WORD_1
	v_cvt_f32_f16_e32 v206, v180
	v_cvt_f32_f16_sdwa v207, v180 dst_sel:DWORD dst_unused:UNUSED_PAD src0_sel:WORD_1
	v_cvt_f32_f16_e32 v208, v181
	v_cvt_f32_f16_sdwa v209, v181 dst_sel:DWORD dst_unused:UNUSED_PAD src0_sel:WORD_1
	v_pk_fma_f32 v[102:103], v[102:103], v[138:139], v[204:205]
	v_pk_fma_f32 v[100:101], v[100:101], v[136:137], v[202:203]
	v_pk_fma_f32 v[98:99], v[98:99], v[142:143], v[208:209]
	v_pk_fma_f32 v[96:97], v[96:97], v[140:141], v[206:207]
	v_cvt_pk_f16_f32 v181, v98, v99
	v_cvt_pk_f16_f32 v180, v96, v97
	v_cvt_pk_f16_f32 v179, v102, v103
	v_cvt_pk_f16_f32 v178, v100, v101
	v_add_u32_e32 v155, 0x8000, v153
	global_store_dwordx4 v155, v[178:181], s[26:27] offset:64
	s_nop 1
	v_add_u32_e32 v154, 0x48000, v153
	global_load_dwordx4 v[178:181], v154, s[26:27] offset:64
	s_waitcnt vmcnt(11)
	v_cvt_f32_f16_e32 v202, v182
	v_cvt_f32_f16_sdwa v203, v182 dst_sel:DWORD dst_unused:UNUSED_PAD src0_sel:WORD_1
	v_cvt_f32_f16_e32 v204, v183
	v_cvt_f32_f16_sdwa v205, v183 dst_sel:DWORD dst_unused:UNUSED_PAD src0_sel:WORD_1
	v_cvt_f32_f16_e32 v206, v184
	v_cvt_f32_f16_sdwa v207, v184 dst_sel:DWORD dst_unused:UNUSED_PAD src0_sel:WORD_1
	v_cvt_f32_f16_e32 v208, v185
	v_cvt_f32_f16_sdwa v209, v185 dst_sel:DWORD dst_unused:UNUSED_PAD src0_sel:WORD_1
	v_pk_fma_f32 v[94:95], v[94:95], v[130:131], v[204:205]
	v_pk_fma_f32 v[92:93], v[92:93], v[128:129], v[202:203]
	v_pk_fma_f32 v[90:91], v[90:91], v[134:135], v[208:209]
	v_pk_fma_f32 v[88:89], v[88:89], v[132:133], v[206:207]
	v_cvt_pk_f16_f32 v185, v90, v91
	v_cvt_pk_f16_f32 v184, v88, v89
	v_cvt_pk_f16_f32 v183, v94, v95
	v_cvt_pk_f16_f32 v182, v92, v93
	v_add_u32_e32 v155, 0x10000, v153
	global_store_dwordx4 v155, v[182:185], s[26:27]
	s_nop 1
	v_add_u32_e32 v154, 0x50000, v153
	global_load_dwordx4 v[182:185], v154, s[26:27]
	s_waitcnt vmcnt(12)
	v_cvt_f32_f16_e32 v202, v186
	v_cvt_f32_f16_sdwa v203, v186 dst_sel:DWORD dst_unused:UNUSED_PAD src0_sel:WORD_1
	v_cvt_f32_f16_e32 v204, v187
	v_cvt_f32_f16_sdwa v205, v187 dst_sel:DWORD dst_unused:UNUSED_PAD src0_sel:WORD_1
	v_cvt_f32_f16_e32 v206, v188
	v_cvt_f32_f16_sdwa v207, v188 dst_sel:DWORD dst_unused:UNUSED_PAD src0_sel:WORD_1
	v_cvt_f32_f16_e32 v208, v189
	v_cvt_f32_f16_sdwa v209, v189 dst_sel:DWORD dst_unused:UNUSED_PAD src0_sel:WORD_1
	v_pk_fma_f32 v[86:87], v[86:87], v[138:139], v[204:205]
	v_pk_fma_f32 v[84:85], v[84:85], v[136:137], v[202:203]
	v_pk_fma_f32 v[82:83], v[82:83], v[142:143], v[208:209]
	v_pk_fma_f32 v[80:81], v[80:81], v[140:141], v[206:207]
	v_cvt_pk_f16_f32 v189, v82, v83
	v_cvt_pk_f16_f32 v188, v80, v81
	v_cvt_pk_f16_f32 v187, v86, v87
	v_cvt_pk_f16_f32 v186, v84, v85
	v_add_u32_e32 v155, 0x10000, v153
	global_store_dwordx4 v155, v[186:189], s[26:27] offset:64
	s_nop 1
	v_add_u32_e32 v154, 0x50000, v153
	global_load_dwordx4 v[186:189], v154, s[26:27] offset:64
	s_waitcnt vmcnt(13)
;     __device__ __forceinline__ void operator()(AccRef acc, int pm, int pn, int wr, int wc, int fr, int fq) const {
;     ...
;             for (int m = 0; m < 4; ++m) { const int row = EPI_ROW(ai, m); const float* gp = gate + (size_t)(row >> 12) * 9216; const size_t ro = (size_t)row * 1024;
; #pragma unroll
;                 for (int bj = 0; bj < 2; ++bj) { const int col = pn * 256 + wc * 64 + bj * 32 + 8 * fq;
;                     const f32x4 g0 = *(const f32x4*)(gp + col), g1 = *(const f32x4*)(gp + col + 4);
;                     f32x4 x0, x1;
;                     if (mode == 0) { x0 = *(const f32x4*)(xin_f + ro + col); x1 = *(const f32x4*)(xin_f + ro + col + 4); }
;                     else { const h16x8 h = *(const h16x8*)(xh + ro + col); x0 = (f32x4){(float)h[0], (float)h[1], (float)h[2], (float)h[3]}; x1 = (f32x4){(float)h[4], (float)h[5], (float)h[6], (float)h[7]}; }
;                     const f32x4 y0 = x0 + gs * g0 * acc[ai][bj][m][0], y1 = x1 + gs * g1 * acc[ai][bj][m][1];
;                     if (mode == 2) { *(f32x4*)(xout_f + ro + col) = y0; *(f32x4*)(xout_f + ro + col + 4) = y1; }
;                     else { h16x8 h; h[0] = (_Float16)y0[0]; h[1] = (_Float16)y0[1]; h[2] = (_Float16)y0[2]; h[3] = (_Float16)y0[3]; h[4] = (_Float16)y1[0]; h[5] = (_Float16)y1[1]; h[6] = (_Float16)y1[2]; h[7] = (_Float16)y1[3];
;                         *(h16x8*)(xh + ro + col) = h; } } }
	v_cvt_f32_f16_e32 v202, v194
	v_cvt_f32_f16_sdwa v203, v194 dst_sel:DWORD dst_unused:UNUSED_PAD src0_sel:WORD_1
	v_cvt_f32_f16_e32 v204, v195
	v_cvt_f32_f16_sdwa v205, v195 dst_sel:DWORD dst_unused:UNUSED_PAD src0_sel:WORD_1
	v_cvt_f32_f16_e32 v206, v196
	v_cvt_f32_f16_sdwa v207, v196 dst_sel:DWORD dst_unused:UNUSED_PAD src0_sel:WORD_1
	v_cvt_f32_f16_e32 v208, v197
	v_cvt_f32_f16_sdwa v209, v197 dst_sel:DWORD dst_unused:UNUSED_PAD src0_sel:WORD_1
	v_pk_fma_f32 v[78:79], v[78:79], v[130:131], v[204:205]
	v_pk_fma_f32 v[76:77], v[76:77], v[128:129], v[202:203]
	v_pk_fma_f32 v[74:75], v[74:75], v[134:135], v[208:209]
	v_pk_fma_f32 v[72:73], v[72:73], v[132:133], v[206:207]
	v_cvt_pk_f16_f32 v197, v74, v75
	v_cvt_pk_f16_f32 v196, v72, v73
	v_cvt_pk_f16_f32 v195, v78, v79
	v_cvt_pk_f16_f32 v194, v76, v77
	v_add_u32_e32 v155, 0x18000, v153
	global_store_dwordx4 v155, v[194:197], s[26:27]
	s_nop 1
	v_add_u32_e32 v154, 0x58000, v153
	global_load_dwordx4 v[194:197], v154, s[26:27]
	s_waitcnt vmcnt(14)
	v_cvt_f32_f16_e32 v202, v198
	v_cvt_f32_f16_sdwa v203, v198 dst_sel:DWORD dst_unused:UNUSED_PAD src0_sel:WORD_1
	v_cvt_f32_f16_e32 v204, v199
	v_cvt_f32_f16_sdwa v205, v199 dst_sel:DWORD dst_unused:UNUSED_PAD src0_sel:WORD_1
	v_cvt_f32_f16_e32 v206, v200
	v_cvt_f32_f16_sdwa v207, v200 dst_sel:DWORD dst_unused:UNUSED_PAD src0_sel:WORD_1
	v_cvt_f32_f16_e32 v208, v201
	v_cvt_f32_f16_sdwa v209, v201 dst_sel:DWORD dst_unused:UNUSED_PAD src0_sel:WORD_1
	v_pk_fma_f32 v[70:71], v[70:71], v[138:139], v[204:205]
	v_pk_fma_f32 v[68:69], v[68:69], v[136:137], v[202:203]
	v_pk_fma_f32 v[66:67], v[66:67], v[142:143], v[208:209]
	v_pk_fma_f32 v[64:65], v[64:65], v[140:141], v[206:207]
	v_cvt_pk_f16_f32 v201, v66, v67
	v_cvt_pk_f16_f32 v200, v64, v65
	v_cvt_pk_f16_f32 v199, v70, v71
	v_cvt_pk_f16_f32 v198, v68, v69
	v_add_u32_e32 v155, 0x18000, v153
	global_store_dwordx4 v155, v[198:201], s[26:27] offset:64
	s_nop 1
	v_add_u32_e32 v154, 0x58000, v153
	global_load_dwordx4 v[198:201], v154, s[26:27] offset:64
	s_waitcnt vmcnt(14)
	v_cvt_f32_f16_e32 v202, v166
	v_cvt_f32_f16_sdwa v203, v166 dst_sel:DWORD dst_unused:UNUSED_PAD src0_sel:WORD_1
	v_cvt_f32_f16_e32 v204, v167
	v_cvt_f32_f16_sdwa v205, v167 dst_sel:DWORD dst_unused:UNUSED_PAD src0_sel:WORD_1
	v_cvt_f32_f16_e32 v206, v168
	v_cvt_f32_f16_sdwa v207, v168 dst_sel:DWORD dst_unused:UNUSED_PAD src0_sel:WORD_1
	v_cvt_f32_f16_e32 v208, v169
	v_cvt_f32_f16_sdwa v209, v169 dst_sel:DWORD dst_unused:UNUSED_PAD src0_sel:WORD_1
	v_pk_fma_f32 v[62:63], v[62:63], v[130:131], v[204:205]
	v_pk_fma_f32 v[60:61], v[60:61], v[128:129], v[202:203]
	v_pk_fma_f32 v[58:59], v[58:59], v[134:135], v[208:209]
	v_pk_fma_f32 v[56:57], v[56:57], v[132:133], v[206:207]
	v_cvt_pk_f16_f32 v169, v58, v59
	v_cvt_pk_f16_f32 v168, v56, v57
	v_cvt_pk_f16_f32 v167, v62, v63
	v_cvt_pk_f16_f32 v166, v60, v61
	v_add_u32_e32 v155, 0x40000, v153
	global_store_dwordx4 v155, v[166:169], s[26:27]
	s_waitcnt vmcnt(13)
	v_cvt_f32_f16_e32 v202, v170
	v_cvt_f32_f16_sdwa v203, v170 dst_sel:DWORD dst_unused:UNUSED_PAD src0_sel:WORD_1
	v_cvt_f32_f16_e32 v204, v171
	v_cvt_f32_f16_sdwa v205, v171 dst_sel:DWORD dst_unused:UNUSED_PAD src0_sel:WORD_1
	v_cvt_f32_f16_e32 v206, v172
	v_cvt_f32_f16_sdwa v207, v172 dst_sel:DWORD dst_unused:UNUSED_PAD src0_sel:WORD_1
	v_cvt_f32_f16_e32 v208, v173
	v_cvt_f32_f16_sdwa v209, v173 dst_sel:DWORD dst_unused:UNUSED_PAD src0_sel:WORD_1
	v_pk_fma_f32 v[54:55], v[54:55], v[138:139], v[204:205]
	v_pk_fma_f32 v[52:53], v[52:53], v[136:137], v[202:203]
	v_pk_fma_f32 v[50:51], v[50:51], v[142:143], v[208:209]
	v_pk_fma_f32 v[48:49], v[48:49], v[140:141], v[206:207]
	v_cvt_pk_f16_f32 v173, v50, v51
	v_cvt_pk_f16_f32 v172, v48, v49
	v_cvt_pk_f16_f32 v171, v54, v55
	v_cvt_pk_f16_f32 v170, v52, v53
	v_add_u32_e32 v155, 0x40000, v153
	global_store_dwordx4 v155, v[170:173], s[26:27] offset:64
	s_waitcnt vmcnt(12)
	v_cvt_f32_f16_e32 v202, v174
	v_cvt_f32_f16_sdwa v203, v174 dst_sel:DWORD dst_unused:UNUSED_PAD src0_sel:WORD_1
	v_cvt_f32_f16_e32 v204, v175
	v_cvt_f32_f16_sdwa v205, v175 dst_sel:DWORD dst_unused:UNUSED_PAD src0_sel:WORD_1
	v_cvt_f32_f16_e32 v206, v176
	v_cvt_f32_f16_sdwa v207, v176 dst_sel:DWORD dst_unused:UNUSED_PAD src0_sel:WORD_1
	v_cvt_f32_f16_e32 v208, v177
	v_cvt_f32_f16_sdwa v209, v177 dst_sel:DWORD dst_unused:UNUSED_PAD src0_sel:WORD_1
	v_pk_fma_f32 v[46:47], v[46:47], v[130:131], v[204:205]
	v_pk_fma_f32 v[44:45], v[44:45], v[128:129], v[202:203]
	v_pk_fma_f32 v[42:43], v[42:43], v[134:135], v[208:209]
	v_pk_fma_f32 v[40:41], v[40:41], v[132:133], v[206:207]
	v_cvt_pk_f16_f32 v177, v42, v43
	v_cvt_pk_f16_f32 v176, v40, v41
	v_cvt_pk_f16_f32 v175, v46, v47
	v_cvt_pk_f16_f32 v174, v44, v45
	v_add_u32_e32 v155, 0x48000, v153
	global_store_dwordx4 v155, v[174:177], s[26:27]
	s_waitcnt vmcnt(11)
	v_cvt_f32_f16_e32 v202, v178
	v_cvt_f32_f16_sdwa v203, v178 dst_sel:DWORD dst_unused:UNUSED_PAD src0_sel:WORD_1
	v_cvt_f32_f16_e32 v204, v179
	v_cvt_f32_f16_sdwa v205, v179 dst_sel:DWORD dst_unused:UNUSED_PAD src0_sel:WORD_1
	v_cvt_f32_f16_e32 v206, v180
	v_cvt_f32_f16_sdwa v207, v180 dst_sel:DWORD dst_unused:UNUSED_PAD src0_sel:WORD_1
	v_cvt_f32_f16_e32 v208, v181
	v_cvt_f32_f16_sdwa v209, v181 dst_sel:DWORD dst_unused:UNUSED_PAD src0_sel:WORD_1
	v_pk_fma_f32 v[38:39], v[38:39], v[138:139], v[204:205]
	v_pk_fma_f32 v[36:37], v[36:37], v[136:137], v[202:203]
	v_pk_fma_f32 v[34:35], v[34:35], v[142:143], v[208:209]
	v_pk_fma_f32 v[32:33], v[32:33], v[140:141], v[206:207]
	v_cvt_pk_f16_f32 v181, v34, v35
	v_cvt_pk_f16_f32 v180, v32, v33
	v_cvt_pk_f16_f32 v179, v38, v39
	v_cvt_pk_f16_f32 v178, v36, v37
	v_add_u32_e32 v155, 0x48000, v153
	global_store_dwordx4 v155, v[178:181], s[26:27] offset:64
	s_waitcnt vmcnt(10)
;     __device__ __forceinline__ void operator()(AccRef acc, int pm, int pn, int wr, int wc, int fr, int fq) const {
;     ...
;             for (int m = 0; m < 4; ++m) { const int row = EPI_ROW(ai, m); const float* gp = gate + (size_t)(row >> 12) * 9216; const size_t ro = (size_t)row * 1024;
; #pragma unroll
;                 for (int bj = 0; bj < 2; ++bj) { const int col = pn * 256 + wc * 64 + bj * 32 + 8 * fq;
;                     const f32x4 g0 = *(const f32x4*)(gp + col), g1 = *(const f32x4*)(gp + col + 4);
;                     f32x4 x0, x1;
;                     if (mode == 0) { x0 = *(const f32x4*)(xin_f + ro + col); x1 = *(const f32x4*)(xin_f + ro + col + 4); }
;                     else { const h16x8 h = *(const h16x8*)(xh + ro + col); x0 = (f32x4){(float)h[0], (float)h[1], (float)h[2], (float)h[3]}; x1 = (f32x4){(float)h[4], (float)h[5], (float)h[6], (float)h[7]}; }
;                     const f32x4 y0 = x0 + gs * g0 * acc[ai][bj][m][0], y1 = x1 + gs * g1 * acc[ai][bj][m][1];
;                     if (mode == 2) { *(f32x4*)(xout_f + ro + col) = y0; *(f32x4*)(xout_f + ro + col + 4) = y1; }
;                     else { h16x8 h; h[0] = (_Float16)y0[0]; h[1] = (_Float16)y0[1]; h[2] = (_Float16)y0[2]; h[3] = (_Float16)y0[3]; h[4] = (_Float16)y1[0]; h[5] = (_Float16)y1[1]; h[6] = (_Float16)y1[2]; h[7] = (_Float16)y1[3];
;                         *(h16x8*)(xh + ro + col) = h; } } }
	v_cvt_f32_f16_e32 v202, v182
	v_cvt_f32_f16_sdwa v203, v182 dst_sel:DWORD dst_unused:UNUSED_PAD src0_sel:WORD_1
	v_cvt_f32_f16_e32 v204, v183
	v_cvt_f32_f16_sdwa v205, v183 dst_sel:DWORD dst_unused:UNUSED_PAD src0_sel:WORD_1
	v_cvt_f32_f16_e32 v206, v184
	v_cvt_f32_f16_sdwa v207, v184 dst_sel:DWORD dst_unused:UNUSED_PAD src0_sel:WORD_1
	v_cvt_f32_f16_e32 v208, v185
	v_cvt_f32_f16_sdwa v209, v185 dst_sel:DWORD dst_unused:UNUSED_PAD src0_sel:WORD_1
	v_pk_fma_f32 v[30:31], v[30:31], v[130:131], v[204:205]
	v_pk_fma_f32 v[28:29], v[28:29], v[128:129], v[202:203]
	v_pk_fma_f32 v[26:27], v[26:27], v[134:135], v[208:209]
	v_pk_fma_f32 v[24:25], v[24:25], v[132:133], v[206:207]
	v_cvt_pk_f16_f32 v185, v26, v27
	v_cvt_pk_f16_f32 v184, v24, v25
	v_cvt_pk_f16_f32 v183, v30, v31
	v_cvt_pk_f16_f32 v182, v28, v29
	v_add_u32_e32 v155, 0x50000, v153
	global_store_dwordx4 v155, v[182:185], s[26:27]
	s_waitcnt vmcnt(9)
	v_cvt_f32_f16_e32 v202, v186
	v_cvt_f32_f16_sdwa v203, v186 dst_sel:DWORD dst_unused:UNUSED_PAD src0_sel:WORD_1
	v_cvt_f32_f16_e32 v204, v187
	v_cvt_f32_f16_sdwa v205, v187 dst_sel:DWORD dst_unused:UNUSED_PAD src0_sel:WORD_1
	v_cvt_f32_f16_e32 v206, v188
	v_cvt_f32_f16_sdwa v207, v188 dst_sel:DWORD dst_unused:UNUSED_PAD src0_sel:WORD_1
	v_cvt_f32_f16_e32 v208, v189
	v_cvt_f32_f16_sdwa v209, v189 dst_sel:DWORD dst_unused:UNUSED_PAD src0_sel:WORD_1
	v_pk_fma_f32 v[22:23], v[22:23], v[138:139], v[204:205]
	v_pk_fma_f32 v[20:21], v[20:21], v[136:137], v[202:203]
	v_pk_fma_f32 v[18:19], v[18:19], v[142:143], v[208:209]
	v_pk_fma_f32 v[16:17], v[16:17], v[140:141], v[206:207]
	v_cvt_pk_f16_f32 v189, v18, v19
	v_cvt_pk_f16_f32 v188, v16, v17
	v_cvt_pk_f16_f32 v187, v22, v23
	v_cvt_pk_f16_f32 v186, v20, v21
	v_add_u32_e32 v155, 0x50000, v153
	global_store_dwordx4 v155, v[186:189], s[26:27] offset:64
	s_waitcnt vmcnt(8)
	v_cvt_f32_f16_e32 v202, v194
	v_cvt_f32_f16_sdwa v203, v194 dst_sel:DWORD dst_unused:UNUSED_PAD src0_sel:WORD_1
	v_cvt_f32_f16_e32 v204, v195
	v_cvt_f32_f16_sdwa v205, v195 dst_sel:DWORD dst_unused:UNUSED_PAD src0_sel:WORD_1
	v_cvt_f32_f16_e32 v206, v196
	v_cvt_f32_f16_sdwa v207, v196 dst_sel:DWORD dst_unused:UNUSED_PAD src0_sel:WORD_1
	v_cvt_f32_f16_e32 v208, v197
	v_cvt_f32_f16_sdwa v209, v197 dst_sel:DWORD dst_unused:UNUSED_PAD src0_sel:WORD_1
	v_pk_fma_f32 v[14:15], v[14:15], v[130:131], v[204:205]
	v_pk_fma_f32 v[12:13], v[12:13], v[128:129], v[202:203]
	v_pk_fma_f32 v[10:11], v[10:11], v[134:135], v[208:209]
	v_pk_fma_f32 v[8:9], v[8:9], v[132:133], v[206:207]
	v_cvt_pk_f16_f32 v197, v10, v11
	v_cvt_pk_f16_f32 v196, v8, v9
	v_cvt_pk_f16_f32 v195, v14, v15
	v_cvt_pk_f16_f32 v194, v12, v13
	v_add_u32_e32 v155, 0x58000, v153
	global_store_dwordx4 v155, v[194:197], s[26:27]
	s_waitcnt vmcnt(7)
	v_cvt_f32_f16_e32 v202, v198
	v_cvt_f32_f16_sdwa v203, v198 dst_sel:DWORD dst_unused:UNUSED_PAD src0_sel:WORD_1
	v_cvt_f32_f16_e32 v204, v199
	v_cvt_f32_f16_sdwa v205, v199 dst_sel:DWORD dst_unused:UNUSED_PAD src0_sel:WORD_1
	v_cvt_f32_f16_e32 v206, v200
	v_cvt_f32_f16_sdwa v207, v200 dst_sel:DWORD dst_unused:UNUSED_PAD src0_sel:WORD_1
	v_cvt_f32_f16_e32 v208, v201
	v_cvt_f32_f16_sdwa v209, v201 dst_sel:DWORD dst_unused:UNUSED_PAD src0_sel:WORD_1
	v_pk_fma_f32 v[6:7], v[6:7], v[138:139], v[204:205]
	v_pk_fma_f32 v[4:5], v[4:5], v[136:137], v[202:203]
	v_pk_fma_f32 v[2:3], v[2:3], v[142:143], v[208:209]
	v_pk_fma_f32 v[0:1], v[0:1], v[140:141], v[206:207]
	v_cvt_pk_f16_f32 v201, v2, v3
	v_cvt_pk_f16_f32 v200, v0, v1
	v_cvt_pk_f16_f32 v199, v6, v7
	v_cvt_pk_f16_f32 v198, v4, v5
	v_add_u32_e32 v155, 0x58000, v153
	global_store_dwordx4 v155, v[198:201], s[26:27] offset:64
	s_branch .LBB0_46
.Lepi_ffo_m0:
	v_ashrrev_i32_e32 v154, 12, v152
	v_mul_hi_i32_i24_e32 v155, 0x9000, v154
	v_mul_i32_i24_e32 v154, 0x9000, v154
	v_lshl_add_u64 v[154:155], s[50:51], 0, v[154:155]
	v_ashrrev_i32_e32 v151, 31, v150
	v_lshl_add_u64 v[158:159], v[150:151], 2, v[154:155]
	global_load_dwordx4 v[128:131], v[158:159], off
	global_load_dwordx4 v[132:135], v[158:159], off offset:16
	global_load_dwordx4 v[136:139], v[158:159], off offset:128
	global_load_dwordx4 v[140:143], v[158:159], off offset:144
	v_lshlrev_b32_e32 v153, 11, v152
	v_lshl_add_u32 v153, v150, 1, v153
	v_lshlrev_b32_e32 v156, 12, v152
	v_lshl_add_u32 v156, v150, 2, v156
	s_movk_i32 s66, 0x3ff
	global_load_dwordx4 v[166:169], v156, s[42:43]
	global_load_dwordx4 v[170:173], v156, s[42:43] offset:16
	global_load_dwordx4 v[174:177], v156, s[42:43] offset:128
	global_load_dwordx4 v[178:181], v156, s[42:43] offset:144
	v_add_u32_e32 v154, 0x10000, v156
	global_load_dwordx4 v[182:185], v154, s[42:43]
	global_load_dwordx4 v[186:189], v154, s[42:43] offset:16
	v_add_u32_e32 v154, 0x10000, v156
	global_load_dwordx4 v[194:197], v154, s[42:43] offset:128
	global_load_dwordx4 v[198:201], v154, s[42:43] offset:144
	s_waitcnt vmcnt(8)
	v_pk_mul_f32 v[128:129], v[128:129], 0.5 op_sel_hi:[1,0]
	v_pk_mul_f32 v[130:131], v[130:131], 0.5 op_sel_hi:[1,0]
	v_pk_mul_f32 v[132:133], v[132:133], 0.5 op_sel_hi:[1,0]
	v_pk_mul_f32 v[134:135], v[134:135], 0.5 op_sel_hi:[1,0]
	v_pk_mul_f32 v[136:137], v[136:137], 0.5 op_sel_hi:[1,0]
	v_pk_mul_f32 v[138:139], v[138:139], 0.5 op_sel_hi:[1,0]
	v_pk_mul_f32 v[140:141], v[140:141], 0.5 op_sel_hi:[1,0]
	v_pk_mul_f32 v[142:143], v[142:143], 0.5 op_sel_hi:[1,0]
	s_waitcnt vmcnt(6)
	v_pk_fma_f32 v[126:127], v[126:127], v[130:131], v[168:169]
	v_pk_fma_f32 v[124:125], v[124:125], v[128:129], v[166:167]
	v_pk_fma_f32 v[122:123], v[122:123], v[134:135], v[172:173]
	v_pk_fma_f32 v[120:121], v[120:121], v[132:133], v[170:171]
	v_cvt_pk_f16_f32 v169, v122, v123
	v_cvt_pk_f16_f32 v168, v120, v121
	v_cvt_pk_f16_f32 v167, v126, v127
	v_cvt_pk_f16_f32 v166, v124, v125
	global_store_dwordx4 v153, v[166:169], s[26:27]
	s_nop 1
	v_add_u32_e32 v154, 0x20000, v156
	global_load_dwordx4 v[166:169], v154, s[42:43]
	global_load_dwordx4 v[170:173], v154, s[42:43] offset:16
	s_waitcnt vmcnt(7)
;     __device__ __forceinline__ void operator()(AccRef acc, int pm, int pn, int wr, int wc, int fr, int fq) const {
;     ...
;             for (int m = 0; m < 4; ++m) { const int row = EPI_ROW(ai, m); const float* gp = gate + (size_t)(row >> 12) * 9216; const size_t ro = (size_t)row * 1024;
; #pragma unroll
;                 for (int bj = 0; bj < 2; ++bj) { const int col = pn * 256 + wc * 64 + bj * 32 + 8 * fq;
;                     const f32x4 g0 = *(const f32x4*)(gp + col), g1 = *(const f32x4*)(gp + col + 4);
;                     f32x4 x0, x1;
;                     if (mode == 0) { x0 = *(const f32x4*)(xin_f + ro + col); x1 = *(const f32x4*)(xin_f + ro + col + 4); }
;                     else { const h16x8 h = *(const h16x8*)(xh + ro + col); x0 = (f32x4){(float)h[0], (float)h[1], (float)h[2], (float)h[3]}; x1 = (f32x4){(float)h[4], (float)h[5], (float)h[6], (float)h[7]}; }
;                     const f32x4 y0 = x0 + gs * g0 * acc[ai][bj][m][0], y1 = x1 + gs * g1 * acc[ai][bj][m][1];
;                     if (mode == 2) { *(f32x4*)(xout_f + ro + col) = y0; *(f32x4*)(xout_f + ro + col + 4) = y1; }
;                     else { h16x8 h; h[0] = (_Float16)y0[0]; h[1] = (_Float16)y0[1]; h[2] = (_Float16)y0[2]; h[3] = (_Float16)y0[3]; h[4] = (_Float16)y1[0]; h[5] = (_Float16)y1[1]; h[6] = (_Float16)y1[2]; h[7] = (_Float16)y1[3];
;                         *(h16x8*)(xh + ro + col) = h; } } }
	v_pk_fma_f32 v[118:119], v[118:119], v[138:139], v[176:177]
	v_pk_fma_f32 v[116:117], v[116:117], v[136:137], v[174:175]
	v_pk_fma_f32 v[114:115], v[114:115], v[142:143], v[180:181]
	v_pk_fma_f32 v[112:113], v[112:113], v[140:141], v[178:179]
	v_cvt_pk_f16_f32 v177, v114, v115
	v_cvt_pk_f16_f32 v176, v112, v113
	v_cvt_pk_f16_f32 v175, v118, v119
	v_cvt_pk_f16_f32 v174, v116, v117
	global_store_dwordx4 v153, v[174:177], s[26:27] offset:64
	s_nop 1
	v_add_u32_e32 v154, 0x20000, v156
	global_load_dwordx4 v[174:177], v154, s[42:43] offset:128
	global_load_dwordx4 v[178:181], v154, s[42:43] offset:144
	s_waitcnt vmcnt(8)
	v_pk_fma_f32 v[110:111], v[110:111], v[130:131], v[184:185]
	v_pk_fma_f32 v[108:109], v[108:109], v[128:129], v[182:183]
	v_pk_fma_f32 v[106:107], v[106:107], v[134:135], v[188:189]
	v_pk_fma_f32 v[104:105], v[104:105], v[132:133], v[186:187]
	v_cvt_pk_f16_f32 v185, v106, v107
	v_cvt_pk_f16_f32 v184, v104, v105
	v_cvt_pk_f16_f32 v183, v110, v111
	v_cvt_pk_f16_f32 v182, v108, v109
	v_add_u32_e32 v155, 0x8000, v153
	global_store_dwordx4 v155, v[182:185], s[26:27]
	s_nop 1
	v_add_u32_e32 v154, 0x30000, v156
	global_load_dwordx4 v[182:185], v154, s[42:43]
	global_load_dwordx4 v[186:189], v154, s[42:43] offset:16
	s_waitcnt vmcnt(9)
	v_pk_fma_f32 v[102:103], v[102:103], v[138:139], v[196:197]
	v_pk_fma_f32 v[100:101], v[100:101], v[136:137], v[194:195]
	v_pk_fma_f32 v[98:99], v[98:99], v[142:143], v[200:201]
	v_pk_fma_f32 v[96:97], v[96:97], v[140:141], v[198:199]
	v_cvt_pk_f16_f32 v197, v98, v99
	v_cvt_pk_f16_f32 v196, v96, v97
	v_cvt_pk_f16_f32 v195, v102, v103
	v_cvt_pk_f16_f32 v194, v100, v101
	v_add_u32_e32 v155, 0x8000, v153
	global_store_dwordx4 v155, v[194:197], s[26:27] offset:64
	s_nop 1
	v_add_u32_e32 v154, 0x30000, v156
	global_load_dwordx4 v[194:197], v154, s[42:43] offset:128
	global_load_dwordx4 v[198:201], v154, s[42:43] offset:144
	s_waitcnt vmcnt(9)
	v_pk_fma_f32 v[94:95], v[94:95], v[130:131], v[168:169]
	v_pk_fma_f32 v[92:93], v[92:93], v[128:129], v[166:167]
	v_pk_fma_f32 v[90:91], v[90:91], v[134:135], v[172:173]
	v_pk_fma_f32 v[88:89], v[88:89], v[132:133], v[170:171]
	v_cvt_pk_f16_f32 v169, v90, v91
	v_cvt_pk_f16_f32 v168, v88, v89
	v_cvt_pk_f16_f32 v167, v94, v95
	v_cvt_pk_f16_f32 v166, v92, v93
	v_add_u32_e32 v155, 0x10000, v153
	global_store_dwordx4 v155, v[166:169], s[26:27]
	s_nop 1
	v_add_u32_e32 v154, 0x80000, v156
	global_load_dwordx4 v[166:169], v154, s[42:43]
	global_load_dwordx4 v[170:173], v154, s[42:43] offset:16
	s_waitcnt vmcnt(9)
	v_pk_fma_f32 v[86:87], v[86:87], v[138:139], v[176:177]
	v_pk_fma_f32 v[84:85], v[84:85], v[136:137], v[174:175]
	v_pk_fma_f32 v[82:83], v[82:83], v[142:143], v[180:181]
	v_pk_fma_f32 v[80:81], v[80:81], v[140:141], v[178:179]
	v_cvt_pk_f16_f32 v177, v82, v83
	v_cvt_pk_f16_f32 v176, v80, v81
	v_cvt_pk_f16_f32 v175, v86, v87
	v_cvt_pk_f16_f32 v174, v84, v85
	v_add_u32_e32 v155, 0x10000, v153
	global_store_dwordx4 v155, v[174:177], s[26:27] offset:64
	s_nop 1
	v_add_u32_e32 v154, 0x80000, v156
	global_load_dwordx4 v[174:177], v154, s[42:43] offset:128
	global_load_dwordx4 v[178:181], v154, s[42:43] offset:144
	s_waitcnt vmcnt(9)
	v_pk_fma_f32 v[78:79], v[78:79], v[130:131], v[184:185]
	v_pk_fma_f32 v[76:77], v[76:77], v[128:129], v[182:183]
	v_pk_fma_f32 v[74:75], v[74:75], v[134:135], v[188:189]
	v_pk_fma_f32 v[72:73], v[72:73], v[132:133], v[186:187]
	v_cvt_pk_f16_f32 v185, v74, v75
	v_cvt_pk_f16_f32 v184, v72, v73
	v_cvt_pk_f16_f32 v183, v78, v79
	v_cvt_pk_f16_f32 v182, v76, v77
	v_add_u32_e32 v155, 0x18000, v153
	global_store_dwordx4 v155, v[182:185], s[26:27]
	s_nop 1
	v_add_u32_e32 v154, 0x90000, v156
	global_load_dwordx4 v[182:185], v154, s[42:43]
	global_load_dwordx4 v[186:189], v154, s[42:43] offset:16
	s_waitcnt vmcnt(9)
	v_pk_fma_f32 v[70:71], v[70:71], v[138:139], v[196:197]
	v_pk_fma_f32 v[68:69], v[68:69], v[136:137], v[194:195]
	v_pk_fma_f32 v[66:67], v[66:67], v[142:143], v[200:201]
	v_pk_fma_f32 v[64:65], v[64:65], v[140:141], v[198:199]
	v_cvt_pk_f16_f32 v197, v66, v67
	v_cvt_pk_f16_f32 v196, v64, v65
	v_cvt_pk_f16_f32 v195, v70, v71
	v_cvt_pk_f16_f32 v194, v68, v69
	v_add_u32_e32 v155, 0x18000, v153
	global_store_dwordx4 v155, v[194:197], s[26:27] offset:64
	s_nop 1
	v_add_u32_e32 v154, 0x90000, v156
	global_load_dwordx4 v[194:197], v154, s[42:43] offset:128
	global_load_dwordx4 v[198:201], v154, s[42:43] offset:144
	s_waitcnt vmcnt(9)
	v_pk_fma_f32 v[62:63], v[62:63], v[130:131], v[168:169]
	v_pk_fma_f32 v[60:61], v[60:61], v[128:129], v[166:167]
	v_pk_fma_f32 v[58:59], v[58:59], v[134:135], v[172:173]
	v_pk_fma_f32 v[56:57], v[56:57], v[132:133], v[170:171]
	v_cvt_pk_f16_f32 v169, v58, v59
	v_cvt_pk_f16_f32 v168, v56, v57
	v_cvt_pk_f16_f32 v167, v62, v63
	v_cvt_pk_f16_f32 v166, v60, v61
	v_add_u32_e32 v155, 0x40000, v153
	global_store_dwordx4 v155, v[166:169], s[26:27]
	s_nop 1
	v_add_u32_e32 v154, 0xa0000, v156
	global_load_dwordx4 v[166:169], v154, s[42:43]
	global_load_dwordx4 v[170:173], v154, s[42:43] offset:16
	s_waitcnt vmcnt(9)
	v_pk_fma_f32 v[54:55], v[54:55], v[138:139], v[176:177]
	v_pk_fma_f32 v[52:53], v[52:53], v[136:137], v[174:175]
	v_pk_fma_f32 v[50:51], v[50:51], v[142:143], v[180:181]
	v_pk_fma_f32 v[48:49], v[48:49], v[140:141], v[178:179]
	v_cvt_pk_f16_f32 v177, v50, v51
	v_cvt_pk_f16_f32 v176, v48, v49
	v_cvt_pk_f16_f32 v175, v54, v55
	v_cvt_pk_f16_f32 v174, v52, v53
	v_add_u32_e32 v155, 0x40000, v153
	global_store_dwordx4 v155, v[174:177], s[26:27] offset:64
	s_nop 1
	v_add_u32_e32 v154, 0xa0000, v156
	global_load_dwordx4 v[174:177], v154, s[42:43] offset:128
	global_load_dwordx4 v[178:181], v154, s[42:43] offset:144
	s_waitcnt vmcnt(9)
;     __device__ __forceinline__ void operator()(AccRef acc, int pm, int pn, int wr, int wc, int fr, int fq) const {
; #pragma unroll
;         for (int ai = 0; ai < 2; ++ai)
; #pragma unroll
;             for (int m = 0; m < 4; ++m) { const int row = EPI_ROW(ai, m); const float* gp = gate + (size_t)(row >> 12) * 9216; const size_t ro = (size_t)row * 1024;
; #pragma unroll
;                 for (int bj = 0; bj < 2; ++bj) { const int col = pn * 256 + wc * 64 + bj * 32 + 8 * fq;
;                     const f32x4 g0 = *(const f32x4*)(gp + col), g1 = *(const f32x4*)(gp + col + 4);
;                     f32x4 x0, x1;
;                     if (mode == 0) { x0 = *(const f32x4*)(xin_f + ro + col); x1 = *(const f32x4*)(xin_f + ro + col + 4); }
;                     else { const h16x8 h = *(const h16x8*)(xh + ro + col); x0 = (f32x4){(float)h[0], (float)h[1], (float)h[2], (float)h[3]}; x1 = (f32x4){(float)h[4], (float)h[5], (float)h[6], (float)h[7]}; }
;                     const f32x4 y0 = x0 + gs * g0 * acc[ai][bj][m][0], y1 = x1 + gs * g1 * acc[ai][bj][m][1];
;                     if (mode == 2) { *(f32x4*)(xout_f + ro + col) = y0; *(f32x4*)(xout_f + ro + col + 4) = y1; }
;                     else { h16x8 h; h[0] = (_Float16)y0[0]; h[1] = (_Float16)y0[1]; h[2] = (_Float16)y0[2]; h[3] = (_Float16)y0[3]; h[4] = (_Float16)y1[0]; h[5] = (_Float16)y1[1]; h[6] = (_Float16)y1[2]; h[7] = (_Float16)y1[3];
;                         *(h16x8*)(xh + ro + col) = h; } } }
;     }
	v_pk_fma_f32 v[46:47], v[46:47], v[130:131], v[184:185]
	v_pk_fma_f32 v[44:45], v[44:45], v[128:129], v[182:183]
	v_pk_fma_f32 v[42:43], v[42:43], v[134:135], v[188:189]
	v_pk_fma_f32 v[40:41], v[40:41], v[132:133], v[186:187]
	v_cvt_pk_f16_f32 v185, v42, v43
	v_cvt_pk_f16_f32 v184, v40, v41
	v_cvt_pk_f16_f32 v183, v46, v47
	v_cvt_pk_f16_f32 v182, v44, v45
	v_add_u32_e32 v155, 0x48000, v153
	global_store_dwordx4 v155, v[182:185], s[26:27]
	s_nop 1
	v_add_u32_e32 v154, 0xb0000, v156
	global_load_dwordx4 v[182:185], v154, s[42:43]
	global_load_dwordx4 v[186:189], v154, s[42:43] offset:16
	s_waitcnt vmcnt(9)
	v_pk_fma_f32 v[38:39], v[38:39], v[138:139], v[196:197]
	v_pk_fma_f32 v[36:37], v[36:37], v[136:137], v[194:195]
	v_pk_fma_f32 v[34:35], v[34:35], v[142:143], v[200:201]
	v_pk_fma_f32 v[32:33], v[32:33], v[140:141], v[198:199]
	v_cvt_pk_f16_f32 v197, v34, v35
	v_cvt_pk_f16_f32 v196, v32, v33
	v_cvt_pk_f16_f32 v195, v38, v39
	v_cvt_pk_f16_f32 v194, v36, v37
	v_add_u32_e32 v155, 0x48000, v153
	global_store_dwordx4 v155, v[194:197], s[26:27] offset:64
	s_nop 1
	v_add_u32_e32 v154, 0xb0000, v156
	global_load_dwordx4 v[194:197], v154, s[42:43] offset:128
	global_load_dwordx4 v[198:201], v154, s[42:43] offset:144
	s_waitcnt vmcnt(9)
	v_pk_fma_f32 v[30:31], v[30:31], v[130:131], v[168:169]
	v_pk_fma_f32 v[28:29], v[28:29], v[128:129], v[166:167]
	v_pk_fma_f32 v[26:27], v[26:27], v[134:135], v[172:173]
	v_pk_fma_f32 v[24:25], v[24:25], v[132:133], v[170:171]
	v_cvt_pk_f16_f32 v169, v26, v27
	v_cvt_pk_f16_f32 v168, v24, v25
	v_cvt_pk_f16_f32 v167, v30, v31
	v_cvt_pk_f16_f32 v166, v28, v29
	v_add_u32_e32 v155, 0x50000, v153
	global_store_dwordx4 v155, v[166:169], s[26:27]
	s_waitcnt vmcnt(7)
	v_pk_fma_f32 v[22:23], v[22:23], v[138:139], v[176:177]
	v_pk_fma_f32 v[20:21], v[20:21], v[136:137], v[174:175]
	v_pk_fma_f32 v[18:19], v[18:19], v[142:143], v[180:181]
	v_pk_fma_f32 v[16:17], v[16:17], v[140:141], v[178:179]
	v_cvt_pk_f16_f32 v177, v18, v19
	v_cvt_pk_f16_f32 v176, v16, v17
	v_cvt_pk_f16_f32 v175, v22, v23
	v_cvt_pk_f16_f32 v174, v20, v21
	v_add_u32_e32 v155, 0x50000, v153
	global_store_dwordx4 v155, v[174:177], s[26:27] offset:64
	s_waitcnt vmcnt(5)
	v_pk_fma_f32 v[14:15], v[14:15], v[130:131], v[184:185]
	v_pk_fma_f32 v[12:13], v[12:13], v[128:129], v[182:183]
	v_pk_fma_f32 v[10:11], v[10:11], v[134:135], v[188:189]
	v_pk_fma_f32 v[8:9], v[8:9], v[132:133], v[186:187]
	v_cvt_pk_f16_f32 v185, v10, v11
	v_cvt_pk_f16_f32 v184, v8, v9
	v_cvt_pk_f16_f32 v183, v14, v15
	v_cvt_pk_f16_f32 v182, v12, v13
	v_add_u32_e32 v155, 0x58000, v153
	global_store_dwordx4 v155, v[182:185], s[26:27]
	s_waitcnt vmcnt(3)
	v_pk_fma_f32 v[6:7], v[6:7], v[138:139], v[196:197]
	v_pk_fma_f32 v[4:5], v[4:5], v[136:137], v[194:195]
	v_pk_fma_f32 v[2:3], v[2:3], v[142:143], v[200:201]
	v_pk_fma_f32 v[0:1], v[0:1], v[140:141], v[198:199]
	v_cvt_pk_f16_f32 v197, v2, v3
	v_cvt_pk_f16_f32 v196, v0, v1
	v_cvt_pk_f16_f32 v195, v6, v7
	v_cvt_pk_f16_f32 v194, v4, v5
	v_add_u32_e32 v155, 0x58000, v153
	global_store_dwordx4 v155, v[194:197], s[26:27] offset:64
	s_branch .LBB0_46
.Lepi_ffo_m2:
	v_ashrrev_i32_e32 v154, 12, v152
	v_mul_hi_i32_i24_e32 v155, 0x9000, v154
	v_mul_i32_i24_e32 v154, 0x9000, v154
	v_lshl_add_u64 v[154:155], s[50:51], 0, v[154:155]
	v_ashrrev_i32_e32 v151, 31, v150
	v_lshl_add_u64 v[158:159], v[150:151], 2, v[154:155]
	global_load_dwordx4 v[128:131], v[158:159], off
	global_load_dwordx4 v[132:135], v[158:159], off offset:16
	global_load_dwordx4 v[136:139], v[158:159], off offset:128
	global_load_dwordx4 v[140:143], v[158:159], off offset:144
	v_lshlrev_b32_e32 v153, 11, v152
	v_lshl_add_u32 v153, v150, 1, v153
	v_lshlrev_b32_e32 v156, 12, v152
	v_lshl_add_u32 v156, v150, 2, v156
	s_movk_i32 s66, 0x3ff
	global_load_dwordx4 v[166:169], v153, s[26:27]
	global_load_dwordx4 v[170:173], v153, s[26:27] offset:64
	v_add_u32_e32 v154, 0x8000, v153
	global_load_dwordx4 v[174:177], v154, s[26:27]
	v_add_u32_e32 v154, 0x8000, v153
	global_load_dwordx4 v[178:181], v154, s[26:27] offset:64
	v_add_u32_e32 v154, 0x10000, v153
	global_load_dwordx4 v[182:185], v154, s[26:27]
	v_add_u32_e32 v154, 0x10000, v153
	global_load_dwordx4 v[186:189], v154, s[26:27] offset:64
	v_add_u32_e32 v154, 0x18000, v153
	global_load_dwordx4 v[194:197], v154, s[26:27]
	v_add_u32_e32 v154, 0x18000, v153
	global_load_dwordx4 v[198:201], v154, s[26:27] offset:64
	s_waitcnt vmcnt(8)
	v_pk_mul_f32 v[128:129], v[128:129], 0.5 op_sel_hi:[1,0]
	v_pk_mul_f32 v[130:131], v[130:131], 0.5 op_sel_hi:[1,0]
	v_pk_mul_f32 v[132:133], v[132:133], 0.5 op_sel_hi:[1,0]
	v_pk_mul_f32 v[134:135], v[134:135], 0.5 op_sel_hi:[1,0]
	v_pk_mul_f32 v[136:137], v[136:137], 0.5 op_sel_hi:[1,0]
	v_pk_mul_f32 v[138:139], v[138:139], 0.5 op_sel_hi:[1,0]
	v_pk_mul_f32 v[140:141], v[140:141], 0.5 op_sel_hi:[1,0]
	v_pk_mul_f32 v[142:143], v[142:143], 0.5 op_sel_hi:[1,0]
	s_waitcnt vmcnt(7)
	v_cvt_f32_f16_e32 v202, v166
	v_cvt_f32_f16_sdwa v203, v166 dst_sel:DWORD dst_unused:UNUSED_PAD src0_sel:WORD_1
	v_cvt_f32_f16_e32 v204, v167
	v_cvt_f32_f16_sdwa v205, v167 dst_sel:DWORD dst_unused:UNUSED_PAD src0_sel:WORD_1
	v_cvt_f32_f16_e32 v206, v168
	v_cvt_f32_f16_sdwa v207, v168 dst_sel:DWORD dst_unused:UNUSED_PAD src0_sel:WORD_1
	v_cvt_f32_f16_e32 v208, v169
	v_cvt_f32_f16_sdwa v209, v169 dst_sel:DWORD dst_unused:UNUSED_PAD src0_sel:WORD_1
	v_pk_fma_f32 v[126:127], v[126:127], v[130:131], v[204:205]
	v_pk_fma_f32 v[124:125], v[124:125], v[128:129], v[202:203]
	v_pk_fma_f32 v[122:123], v[122:123], v[134:135], v[208:209]
	v_pk_fma_f32 v[120:121], v[120:121], v[132:133], v[206:207]
	global_store_dwordx4 v156, v[124:127], s[44:45]
	global_store_dwordx4 v156, v[120:123], s[44:45] offset:16
	s_nop 1
	v_add_u32_e32 v154, 0x40000, v153
	global_load_dwordx4 v[166:169], v154, s[26:27]
	s_waitcnt vmcnt(9)
;     __device__ __forceinline__ void operator()(AccRef acc, int pm, int pn, int wr, int wc, int fr, int fq) const {
;     ...
;             for (int m = 0; m < 4; ++m) { const int row = EPI_ROW(ai, m); const float* gp = gate + (size_t)(row >> 12) * 9216; const size_t ro = (size_t)row * 1024;
; #pragma unroll
;                 for (int bj = 0; bj < 2; ++bj) { const int col = pn * 256 + wc * 64 + bj * 32 + 8 * fq;
;                     const f32x4 g0 = *(const f32x4*)(gp + col), g1 = *(const f32x4*)(gp + col + 4);
;                     f32x4 x0, x1;
;                     if (mode == 0) { x0 = *(const f32x4*)(xin_f + ro + col); x1 = *(const f32x4*)(xin_f + ro + col + 4); }
;                     else { const h16x8 h = *(const h16x8*)(xh + ro + col); x0 = (f32x4){(float)h[0], (float)h[1], (float)h[2], (float)h[3]}; x1 = (f32x4){(float)h[4], (float)h[5], (float)h[6], (float)h[7]}; }
;                     const f32x4 y0 = x0 + gs * g0 * acc[ai][bj][m][0], y1 = x1 + gs * g1 * acc[ai][bj][m][1];
;                     if (mode == 2) { *(f32x4*)(xout_f + ro + col) = y0; *(f32x4*)(xout_f + ro + col + 4) = y1; }
;                     else { h16x8 h; h[0] = (_Float16)y0[0]; h[1] = (_Float16)y0[1]; h[2] = (_Float16)y0[2]; h[3] = (_Float16)y0[3]; h[4] = (_Float16)y1[0]; h[5] = (_Float16)y1[1]; h[6] = (_Float16)y1[2]; h[7] = (_Float16)y1[3];
;                         *(h16x8*)(xh + ro + col) = h; } } }
	v_cvt_f32_f16_e32 v202, v170
	v_cvt_f32_f16_sdwa v203, v170 dst_sel:DWORD dst_unused:UNUSED_PAD src0_sel:WORD_1
	v_cvt_f32_f16_e32 v204, v171
	v_cvt_f32_f16_sdwa v205, v171 dst_sel:DWORD dst_unused:UNUSED_PAD src0_sel:WORD_1
	v_cvt_f32_f16_e32 v206, v172
	v_cvt_f32_f16_sdwa v207, v172 dst_sel:DWORD dst_unused:UNUSED_PAD src0_sel:WORD_1
	v_cvt_f32_f16_e32 v208, v173
	v_cvt_f32_f16_sdwa v209, v173 dst_sel:DWORD dst_unused:UNUSED_PAD src0_sel:WORD_1
	v_pk_fma_f32 v[118:119], v[118:119], v[138:139], v[204:205]
	v_pk_fma_f32 v[116:117], v[116:117], v[136:137], v[202:203]
	v_pk_fma_f32 v[114:115], v[114:115], v[142:143], v[208:209]
	v_pk_fma_f32 v[112:113], v[112:113], v[140:141], v[206:207]
	global_store_dwordx4 v156, v[116:119], s[44:45] offset:128
	global_store_dwordx4 v156, v[112:115], s[44:45] offset:144
	s_nop 1
	v_add_u32_e32 v154, 0x40000, v153
	global_load_dwordx4 v[170:173], v154, s[26:27] offset:64
	s_waitcnt vmcnt(11)
	v_cvt_f32_f16_e32 v202, v174
	v_cvt_f32_f16_sdwa v203, v174 dst_sel:DWORD dst_unused:UNUSED_PAD src0_sel:WORD_1
	v_cvt_f32_f16_e32 v204, v175
	v_cvt_f32_f16_sdwa v205, v175 dst_sel:DWORD dst_unused:UNUSED_PAD src0_sel:WORD_1
	v_cvt_f32_f16_e32 v206, v176
	v_cvt_f32_f16_sdwa v207, v176 dst_sel:DWORD dst_unused:UNUSED_PAD src0_sel:WORD_1
	v_cvt_f32_f16_e32 v208, v177
	v_cvt_f32_f16_sdwa v209, v177 dst_sel:DWORD dst_unused:UNUSED_PAD src0_sel:WORD_1
	v_pk_fma_f32 v[110:111], v[110:111], v[130:131], v[204:205]
	v_pk_fma_f32 v[108:109], v[108:109], v[128:129], v[202:203]
	v_pk_fma_f32 v[106:107], v[106:107], v[134:135], v[208:209]
	v_pk_fma_f32 v[104:105], v[104:105], v[132:133], v[206:207]
	v_add_u32_e32 v155, 0x10000, v156
	global_store_dwordx4 v155, v[108:111], s[44:45]
	global_store_dwordx4 v155, v[104:107], s[44:45] offset:16
	s_nop 1
	v_add_u32_e32 v154, 0x48000, v153
	global_load_dwordx4 v[174:177], v154, s[26:27]
	s_waitcnt vmcnt(13)
	v_cvt_f32_f16_e32 v202, v178
	v_cvt_f32_f16_sdwa v203, v178 dst_sel:DWORD dst_unused:UNUSED_PAD src0_sel:WORD_1
	v_cvt_f32_f16_e32 v204, v179
	v_cvt_f32_f16_sdwa v205, v179 dst_sel:DWORD dst_unused:UNUSED_PAD src0_sel:WORD_1
	v_cvt_f32_f16_e32 v206, v180
	v_cvt_f32_f16_sdwa v207, v180 dst_sel:DWORD dst_unused:UNUSED_PAD src0_sel:WORD_1
	v_cvt_f32_f16_e32 v208, v181
	v_cvt_f32_f16_sdwa v209, v181 dst_sel:DWORD dst_unused:UNUSED_PAD src0_sel:WORD_1
	v_pk_fma_f32 v[102:103], v[102:103], v[138:139], v[204:205]
	v_pk_fma_f32 v[100:101], v[100:101], v[136:137], v[202:203]
	v_pk_fma_f32 v[98:99], v[98:99], v[142:143], v[208:209]
	v_pk_fma_f32 v[96:97], v[96:97], v[140:141], v[206:207]
	v_add_u32_e32 v155, 0x10000, v156
	global_store_dwordx4 v155, v[100:103], s[44:45] offset:128
	global_store_dwordx4 v155, v[96:99], s[44:45] offset:144
	s_nop 1
	v_add_u32_e32 v154, 0x48000, v153
	global_load_dwordx4 v[178:181], v154, s[26:27] offset:64
	s_waitcnt vmcnt(15)
	v_cvt_f32_f16_e32 v202, v182
	v_cvt_f32_f16_sdwa v203, v182 dst_sel:DWORD dst_unused:UNUSED_PAD src0_sel:WORD_1
	v_cvt_f32_f16_e32 v204, v183
	v_cvt_f32_f16_sdwa v205, v183 dst_sel:DWORD dst_unused:UNUSED_PAD src0_sel:WORD_1
	v_cvt_f32_f16_e32 v206, v184
	v_cvt_f32_f16_sdwa v207, v184 dst_sel:DWORD dst_unused:UNUSED_PAD src0_sel:WORD_1
	v_cvt_f32_f16_e32 v208, v185
	v_cvt_f32_f16_sdwa v209, v185 dst_sel:DWORD dst_unused:UNUSED_PAD src0_sel:WORD_1
	v_pk_fma_f32 v[94:95], v[94:95], v[130:131], v[204:205]
	v_pk_fma_f32 v[92:93], v[92:93], v[128:129], v[202:203]
	v_pk_fma_f32 v[90:91], v[90:91], v[134:135], v[208:209]
	v_pk_fma_f32 v[88:89], v[88:89], v[132:133], v[206:207]
	v_add_u32_e32 v155, 0x20000, v156
	global_store_dwordx4 v155, v[92:95], s[44:45]
	global_store_dwordx4 v155, v[88:91], s[44:45] offset:16
	s_nop 1
	v_add_u32_e32 v154, 0x50000, v153
	global_load_dwordx4 v[182:185], v154, s[26:27]
	s_waitcnt vmcnt(17)
	v_cvt_f32_f16_e32 v202, v186
	v_cvt_f32_f16_sdwa v203, v186 dst_sel:DWORD dst_unused:UNUSED_PAD src0_sel:WORD_1
	v_cvt_f32_f16_e32 v204, v187
	v_cvt_f32_f16_sdwa v205, v187 dst_sel:DWORD dst_unused:UNUSED_PAD src0_sel:WORD_1
	v_cvt_f32_f16_e32 v206, v188
	v_cvt_f32_f16_sdwa v207, v188 dst_sel:DWORD dst_unused:UNUSED_PAD src0_sel:WORD_1
	v_cvt_f32_f16_e32 v208, v189
	v_cvt_f32_f16_sdwa v209, v189 dst_sel:DWORD dst_unused:UNUSED_PAD src0_sel:WORD_1
	v_pk_fma_f32 v[86:87], v[86:87], v[138:139], v[204:205]
	v_pk_fma_f32 v[84:85], v[84:85], v[136:137], v[202:203]
	v_pk_fma_f32 v[82:83], v[82:83], v[142:143], v[208:209]
	v_pk_fma_f32 v[80:81], v[80:81], v[140:141], v[206:207]
	v_add_u32_e32 v155, 0x20000, v156
	global_store_dwordx4 v155, v[84:87], s[44:45] offset:128
	global_store_dwordx4 v155, v[80:83], s[44:45] offset:144
	s_nop 1
	v_add_u32_e32 v154, 0x50000, v153
	global_load_dwordx4 v[186:189], v154, s[26:27] offset:64
	s_waitcnt vmcnt(19)
	v_cvt_f32_f16_e32 v202, v194
	v_cvt_f32_f16_sdwa v203, v194 dst_sel:DWORD dst_unused:UNUSED_PAD src0_sel:WORD_1
	v_cvt_f32_f16_e32 v204, v195
	v_cvt_f32_f16_sdwa v205, v195 dst_sel:DWORD dst_unused:UNUSED_PAD src0_sel:WORD_1
	v_cvt_f32_f16_e32 v206, v196
	v_cvt_f32_f16_sdwa v207, v196 dst_sel:DWORD dst_unused:UNUSED_PAD src0_sel:WORD_1
	v_cvt_f32_f16_e32 v208, v197
	v_cvt_f32_f16_sdwa v209, v197 dst_sel:DWORD dst_unused:UNUSED_PAD src0_sel:WORD_1
	v_pk_fma_f32 v[78:79], v[78:79], v[130:131], v[204:205]
	v_pk_fma_f32 v[76:77], v[76:77], v[128:129], v[202:203]
	v_pk_fma_f32 v[74:75], v[74:75], v[134:135], v[208:209]
	v_pk_fma_f32 v[72:73], v[72:73], v[132:133], v[206:207]
	v_add_u32_e32 v155, 0x30000, v156
	global_store_dwordx4 v155, v[76:79], s[44:45]
	global_store_dwordx4 v155, v[72:75], s[44:45] offset:16
	s_nop 1
	v_add_u32_e32 v154, 0x58000, v153
	global_load_dwordx4 v[194:197], v154, s[26:27]
	s_waitcnt vmcnt(21)
;     __device__ __forceinline__ void operator()(AccRef acc, int pm, int pn, int wr, int wc, int fr, int fq) const {
;     ...
;             for (int m = 0; m < 4; ++m) { const int row = EPI_ROW(ai, m); const float* gp = gate + (size_t)(row >> 12) * 9216; const size_t ro = (size_t)row * 1024;
; #pragma unroll
;                 for (int bj = 0; bj < 2; ++bj) { const int col = pn * 256 + wc * 64 + bj * 32 + 8 * fq;
;                     const f32x4 g0 = *(const f32x4*)(gp + col), g1 = *(const f32x4*)(gp + col + 4);
;                     f32x4 x0, x1;
;                     if (mode == 0) { x0 = *(const f32x4*)(xin_f + ro + col); x1 = *(const f32x4*)(xin_f + ro + col + 4); }
;                     else { const h16x8 h = *(const h16x8*)(xh + ro + col); x0 = (f32x4){(float)h[0], (float)h[1], (float)h[2], (float)h[3]}; x1 = (f32x4){(float)h[4], (float)h[5], (float)h[6], (float)h[7]}; }
;                     const f32x4 y0 = x0 + gs * g0 * acc[ai][bj][m][0], y1 = x1 + gs * g1 * acc[ai][bj][m][1];
;                     if (mode == 2) { *(f32x4*)(xout_f + ro + col) = y0; *(f32x4*)(xout_f + ro + col + 4) = y1; }
;                     else { h16x8 h; h[0] = (_Float16)y0[0]; h[1] = (_Float16)y0[1]; h[2] = (_Float16)y0[2]; h[3] = (_Float16)y0[3]; h[4] = (_Float16)y1[0]; h[5] = (_Float16)y1[1]; h[6] = (_Float16)y1[2]; h[7] = (_Float16)y1[3];
;                         *(h16x8*)(xh + ro + col) = h; } } }
	v_cvt_f32_f16_e32 v202, v198
	v_cvt_f32_f16_sdwa v203, v198 dst_sel:DWORD dst_unused:UNUSED_PAD src0_sel:WORD_1
	v_cvt_f32_f16_e32 v204, v199
	v_cvt_f32_f16_sdwa v205, v199 dst_sel:DWORD dst_unused:UNUSED_PAD src0_sel:WORD_1
	v_cvt_f32_f16_e32 v206, v200
	v_cvt_f32_f16_sdwa v207, v200 dst_sel:DWORD dst_unused:UNUSED_PAD src0_sel:WORD_1
	v_cvt_f32_f16_e32 v208, v201
	v_cvt_f32_f16_sdwa v209, v201 dst_sel:DWORD dst_unused:UNUSED_PAD src0_sel:WORD_1
	v_pk_fma_f32 v[70:71], v[70:71], v[138:139], v[204:205]
	v_pk_fma_f32 v[68:69], v[68:69], v[136:137], v[202:203]
	v_pk_fma_f32 v[66:67], v[66:67], v[142:143], v[208:209]
	v_pk_fma_f32 v[64:65], v[64:65], v[140:141], v[206:207]
	v_add_u32_e32 v155, 0x30000, v156
	global_store_dwordx4 v155, v[68:71], s[44:45] offset:128
	global_store_dwordx4 v155, v[64:67], s[44:45] offset:144
	s_nop 1
	v_add_u32_e32 v154, 0x58000, v153
	global_load_dwordx4 v[198:201], v154, s[26:27] offset:64
	s_waitcnt vmcnt(21)
	v_cvt_f32_f16_e32 v202, v166
	v_cvt_f32_f16_sdwa v203, v166 dst_sel:DWORD dst_unused:UNUSED_PAD src0_sel:WORD_1
	v_cvt_f32_f16_e32 v204, v167
	v_cvt_f32_f16_sdwa v205, v167 dst_sel:DWORD dst_unused:UNUSED_PAD src0_sel:WORD_1
	v_cvt_f32_f16_e32 v206, v168
	v_cvt_f32_f16_sdwa v207, v168 dst_sel:DWORD dst_unused:UNUSED_PAD src0_sel:WORD_1
	v_cvt_f32_f16_e32 v208, v169
	v_cvt_f32_f16_sdwa v209, v169 dst_sel:DWORD dst_unused:UNUSED_PAD src0_sel:WORD_1
	v_pk_fma_f32 v[62:63], v[62:63], v[130:131], v[204:205]
	v_pk_fma_f32 v[60:61], v[60:61], v[128:129], v[202:203]
	v_pk_fma_f32 v[58:59], v[58:59], v[134:135], v[208:209]
	v_pk_fma_f32 v[56:57], v[56:57], v[132:133], v[206:207]
	v_add_u32_e32 v155, 0x80000, v156
	global_store_dwordx4 v155, v[60:63], s[44:45]
	global_store_dwordx4 v155, v[56:59], s[44:45] offset:16
	s_waitcnt vmcnt(20)
	v_cvt_f32_f16_e32 v202, v170
	v_cvt_f32_f16_sdwa v203, v170 dst_sel:DWORD dst_unused:UNUSED_PAD src0_sel:WORD_1
	v_cvt_f32_f16_e32 v204, v171
	v_cvt_f32_f16_sdwa v205, v171 dst_sel:DWORD dst_unused:UNUSED_PAD src0_sel:WORD_1
	v_cvt_f32_f16_e32 v206, v172
	v_cvt_f32_f16_sdwa v207, v172 dst_sel:DWORD dst_unused:UNUSED_PAD src0_sel:WORD_1
	v_cvt_f32_f16_e32 v208, v173
	v_cvt_f32_f16_sdwa v209, v173 dst_sel:DWORD dst_unused:UNUSED_PAD src0_sel:WORD_1
	v_pk_fma_f32 v[54:55], v[54:55], v[138:139], v[204:205]
	v_pk_fma_f32 v[52:53], v[52:53], v[136:137], v[202:203]
	v_pk_fma_f32 v[50:51], v[50:51], v[142:143], v[208:209]
	v_pk_fma_f32 v[48:49], v[48:49], v[140:141], v[206:207]
	v_add_u32_e32 v155, 0x80000, v156
	global_store_dwordx4 v155, v[52:55], s[44:45] offset:128
	global_store_dwordx4 v155, v[48:51], s[44:45] offset:144
	s_waitcnt vmcnt(19)
	v_cvt_f32_f16_e32 v202, v174
	v_cvt_f32_f16_sdwa v203, v174 dst_sel:DWORD dst_unused:UNUSED_PAD src0_sel:WORD_1
	v_cvt_f32_f16_e32 v204, v175
	v_cvt_f32_f16_sdwa v205, v175 dst_sel:DWORD dst_unused:UNUSED_PAD src0_sel:WORD_1
	v_cvt_f32_f16_e32 v206, v176
	v_cvt_f32_f16_sdwa v207, v176 dst_sel:DWORD dst_unused:UNUSED_PAD src0_sel:WORD_1
	v_cvt_f32_f16_e32 v208, v177
	v_cvt_f32_f16_sdwa v209, v177 dst_sel:DWORD dst_unused:UNUSED_PAD src0_sel:WORD_1
	v_pk_fma_f32 v[46:47], v[46:47], v[130:131], v[204:205]
	v_pk_fma_f32 v[44:45], v[44:45], v[128:129], v[202:203]
	v_pk_fma_f32 v[42:43], v[42:43], v[134:135], v[208:209]
	v_pk_fma_f32 v[40:41], v[40:41], v[132:133], v[206:207]
	v_add_u32_e32 v155, 0x90000, v156
	global_store_dwordx4 v155, v[44:47], s[44:45]
	global_store_dwordx4 v155, v[40:43], s[44:45] offset:16
	s_waitcnt vmcnt(18)
	v_cvt_f32_f16_e32 v202, v178
	v_cvt_f32_f16_sdwa v203, v178 dst_sel:DWORD dst_unused:UNUSED_PAD src0_sel:WORD_1
	v_cvt_f32_f16_e32 v204, v179
	v_cvt_f32_f16_sdwa v205, v179 dst_sel:DWORD dst_unused:UNUSED_PAD src0_sel:WORD_1
	v_cvt_f32_f16_e32 v206, v180
	v_cvt_f32_f16_sdwa v207, v180 dst_sel:DWORD dst_unused:UNUSED_PAD src0_sel:WORD_1
	v_cvt_f32_f16_e32 v208, v181
	v_cvt_f32_f16_sdwa v209, v181 dst_sel:DWORD dst_unused:UNUSED_PAD src0_sel:WORD_1
	v_pk_fma_f32 v[38:39], v[38:39], v[138:139], v[204:205]
	v_pk_fma_f32 v[36:37], v[36:37], v[136:137], v[202:203]
	v_pk_fma_f32 v[34:35], v[34:35], v[142:143], v[208:209]
	v_pk_fma_f32 v[32:33], v[32:33], v[140:141], v[206:207]
	v_add_u32_e32 v155, 0x90000, v156
	global_store_dwordx4 v155, v[36:39], s[44:45] offset:128
	global_store_dwordx4 v155, v[32:35], s[44:45] offset:144
	s_waitcnt vmcnt(17)
;     __device__ __forceinline__ void operator()(AccRef acc, int pm, int pn, int wr, int wc, int fr, int fq) const {
;     ...
;             for (int m = 0; m < 4; ++m) { const int row = EPI_ROW(ai, m); const float* gp = gate + (size_t)(row >> 12) * 9216; const size_t ro = (size_t)row * 1024;
; #pragma unroll
;                 for (int bj = 0; bj < 2; ++bj) { const int col = pn * 256 + wc * 64 + bj * 32 + 8 * fq;
;                     const f32x4 g0 = *(const f32x4*)(gp + col), g1 = *(const f32x4*)(gp + col + 4);
;                     f32x4 x0, x1;
;                     if (mode == 0) { x0 = *(const f32x4*)(xin_f + ro + col); x1 = *(const f32x4*)(xin_f + ro + col + 4); }
;                     else { const h16x8 h = *(const h16x8*)(xh + ro + col); x0 = (f32x4){(float)h[0], (float)h[1], (float)h[2], (float)h[3]}; x1 = (f32x4){(float)h[4], (float)h[5], (float)h[6], (float)h[7]}; }
;                     const f32x4 y0 = x0 + gs * g0 * acc[ai][bj][m][0], y1 = x1 + gs * g1 * acc[ai][bj][m][1];
;                     if (mode == 2) { *(f32x4*)(xout_f + ro + col) = y0; *(f32x4*)(xout_f + ro + col + 4) = y1; }
;                     else { h16x8 h; h[0] = (_Float16)y0[0]; h[1] = (_Float16)y0[1]; h[2] = (_Float16)y0[2]; h[3] = (_Float16)y0[3]; h[4] = (_Float16)y1[0]; h[5] = (_Float16)y1[1]; h[6] = (_Float16)y1[2]; h[7] = (_Float16)y1[3];
;                         *(h16x8*)(xh + ro + col) = h; } } }
	v_cvt_f32_f16_e32 v202, v182
	v_cvt_f32_f16_sdwa v203, v182 dst_sel:DWORD dst_unused:UNUSED_PAD src0_sel:WORD_1
	v_cvt_f32_f16_e32 v204, v183
	v_cvt_f32_f16_sdwa v205, v183 dst_sel:DWORD dst_unused:UNUSED_PAD src0_sel:WORD_1
	v_cvt_f32_f16_e32 v206, v184
	v_cvt_f32_f16_sdwa v207, v184 dst_sel:DWORD dst_unused:UNUSED_PAD src0_sel:WORD_1
	v_cvt_f32_f16_e32 v208, v185
	v_cvt_f32_f16_sdwa v209, v185 dst_sel:DWORD dst_unused:UNUSED_PAD src0_sel:WORD_1
	v_pk_fma_f32 v[30:31], v[30:31], v[130:131], v[204:205]
	v_pk_fma_f32 v[28:29], v[28:29], v[128:129], v[202:203]
	v_pk_fma_f32 v[26:27], v[26:27], v[134:135], v[208:209]
	v_pk_fma_f32 v[24:25], v[24:25], v[132:133], v[206:207]
	v_add_u32_e32 v155, 0xa0000, v156
	global_store_dwordx4 v155, v[28:31], s[44:45]
	global_store_dwordx4 v155, v[24:27], s[44:45] offset:16
	s_waitcnt vmcnt(16)
	v_cvt_f32_f16_e32 v202, v186
	v_cvt_f32_f16_sdwa v203, v186 dst_sel:DWORD dst_unused:UNUSED_PAD src0_sel:WORD_1
	v_cvt_f32_f16_e32 v204, v187
	v_cvt_f32_f16_sdwa v205, v187 dst_sel:DWORD dst_unused:UNUSED_PAD src0_sel:WORD_1
	v_cvt_f32_f16_e32 v206, v188
	v_cvt_f32_f16_sdwa v207, v188 dst_sel:DWORD dst_unused:UNUSED_PAD src0_sel:WORD_1
	v_cvt_f32_f16_e32 v208, v189
	v_cvt_f32_f16_sdwa v209, v189 dst_sel:DWORD dst_unused:UNUSED_PAD src0_sel:WORD_1
	v_pk_fma_f32 v[22:23], v[22:23], v[138:139], v[204:205]
	v_pk_fma_f32 v[20:21], v[20:21], v[136:137], v[202:203]
	v_pk_fma_f32 v[18:19], v[18:19], v[142:143], v[208:209]
	v_pk_fma_f32 v[16:17], v[16:17], v[140:141], v[206:207]
	v_add_u32_e32 v155, 0xa0000, v156
	global_store_dwordx4 v155, v[20:23], s[44:45] offset:128
	global_store_dwordx4 v155, v[16:19], s[44:45] offset:144
	s_waitcnt vmcnt(15)
	v_cvt_f32_f16_e32 v202, v194
	v_cvt_f32_f16_sdwa v203, v194 dst_sel:DWORD dst_unused:UNUSED_PAD src0_sel:WORD_1
	v_cvt_f32_f16_e32 v204, v195
	v_cvt_f32_f16_sdwa v205, v195 dst_sel:DWORD dst_unused:UNUSED_PAD src0_sel:WORD_1
	v_cvt_f32_f16_e32 v206, v196
	v_cvt_f32_f16_sdwa v207, v196 dst_sel:DWORD dst_unused:UNUSED_PAD src0_sel:WORD_1
	v_cvt_f32_f16_e32 v208, v197
	v_cvt_f32_f16_sdwa v209, v197 dst_sel:DWORD dst_unused:UNUSED_PAD src0_sel:WORD_1
	v_pk_fma_f32 v[14:15], v[14:15], v[130:131], v[204:205]
	v_pk_fma_f32 v[12:13], v[12:13], v[128:129], v[202:203]
	v_pk_fma_f32 v[10:11], v[10:11], v[134:135], v[208:209]
	v_pk_fma_f32 v[8:9], v[8:9], v[132:133], v[206:207]
	v_add_u32_e32 v155, 0xb0000, v156
	global_store_dwordx4 v155, v[12:15], s[44:45]
	global_store_dwordx4 v155, v[8:11], s[44:45] offset:16
	s_waitcnt vmcnt(14)
	v_cvt_f32_f16_e32 v202, v198
	v_cvt_f32_f16_sdwa v203, v198 dst_sel:DWORD dst_unused:UNUSED_PAD src0_sel:WORD_1
	v_cvt_f32_f16_e32 v204, v199
	v_cvt_f32_f16_sdwa v205, v199 dst_sel:DWORD dst_unused:UNUSED_PAD src0_sel:WORD_1
	v_cvt_f32_f16_e32 v206, v200
	v_cvt_f32_f16_sdwa v207, v200 dst_sel:DWORD dst_unused:UNUSED_PAD src0_sel:WORD_1
	v_cvt_f32_f16_e32 v208, v201
	v_cvt_f32_f16_sdwa v209, v201 dst_sel:DWORD dst_unused:UNUSED_PAD src0_sel:WORD_1
	v_pk_fma_f32 v[6:7], v[6:7], v[138:139], v[204:205]
	v_pk_fma_f32 v[4:5], v[4:5], v[136:137], v[202:203]
	v_pk_fma_f32 v[2:3], v[2:3], v[142:143], v[208:209]
	v_pk_fma_f32 v[0:1], v[0:1], v[140:141], v[206:207]
	v_add_u32_e32 v155, 0xb0000, v156
	global_store_dwordx4 v155, v[4:7], s[44:45] offset:128
	global_store_dwordx4 v155, v[0:3], s[44:45] offset:144
	s_branch .LBB0_46
	v_ashrrev_i32_e32 v128, 12, v152
	v_mul_hi_i32_i24_e32 v129, 0x9000, v128
	v_mul_i32_i24_e32 v128, 0x9000, v128
	v_lshl_add_u64 v[128:129], s[50:51], 0, v[128:129]
	v_ashrrev_i32_e32 v151, 31, v150
	v_lshl_add_u64 v[158:159], v[150:151], 2, v[128:129]
	flat_load_dwordx4 v[136:139], v[158:159]
	flat_load_dwordx4 v[128:131], v[158:159] offset:16
	v_ashrrev_i32_e32 v153, 31, v152
	v_lshlrev_b64 v[160:161], 10, v[152:153]
	s_mov_b64 s[40:41], -1
	s_andn2_b64 vcc, exec, s[36:37]
	v_lshl_add_u64 v[156:157], v[160:161], 2, s[42:43]
	s_cbranch_vccnz .LBB0_57
	v_lshl_add_u64 v[140:141], v[150:151], 2, v[156:157]
	global_load_dwordx4 v[132:135], v[140:141], off offset:16
	s_nop 0
	global_load_dwordx4 v[140:143], v[140:141], off
	s_mov_b64 s[40:41], 0

; #define G_STAGE(bufoff, gbase, voff) do { _Pragma("unroll") for (int _i = 0; _i < 2; ++_i) \
;     __builtin_amdgcn_global_load_lds((const unsigned*)((const char*)(gbase) + (voff)[_i]), (LAS unsigned*)(lds + (bufoff) + ldsw + _i * 8192), 16, 0, 0); } while (0)
; #define G_LDA(dst, b, h) do { _Pragma("unroll") for (int m = 0; m < 4; ++m) _Pragma("unroll") for (int k = 0; k < 2; ++k) dst[m][k] = *(const LAS bf16x8*)(lds + G_SA(b, h) + aoff + m * 2048 + k * 1024); } while (0)
; #define G_LDB(dst, b, h) do { _Pragma("unroll") for (int n = 0; n < 2; ++n) _Pragma("unroll") for (int k = 0; k < 2; ++k) dst[n][k] = *(const LAS bf16x8*)(lds + G_SB(b, h) + boff + n * 2048 + k * 1024); } while (0)
; #define G_MMA(ai, bj, At, Bt) do { __builtin_amdgcn_s_setprio(1); _Pragma("unroll") for (int m = 0; m < 4; ++m) _Pragma("unroll") for (int n = 0; n < 2; ++n) _Pragma("unroll") for (int k = 0; k < 2; ++k) \
;     acc[ai][bj][m][n] = __builtin_amdgcn_mfma_f32_16x16x32_bf16(Bt[n][k], At[m][k], acc[ai][bj][m][n], 0, 0, 0); __builtin_amdgcn_s_setprio(0); } while (0)
; #define WAIT_V(n) asm volatile("s_waitcnt vmcnt(" #n ")" ::: "memory")
; #define WAIT_L(n) asm volatile("s_waitcnt lgkmcnt(" #n ")" ::: "memory")
; #define BAR __builtin_amdgcn_s_barrier()
; #define SCHED __builtin_amdgcn_sched_barrier(0)
; template <class Epi>
; __device__ __forceinline__ void gemm_phase(const bf16_t* __restrict__ A, int lda, const bf16_t* __restrict__ Bt, int ldb, int K, int nM, int nN, const Epi& epi, LAS unsigned char* lds, int wv) {
;     ...
;             const char* a1 = cA + (size_t)(t + 1) * kstep;
;             const char* a2 = last ? nA : cA + (size_t)(t + 2) * kstep; const char* b2 = last ? nB : cB + (size_t)(t + 2) * kstep;
;             const char* a3 = a2 + kstep; const char* b3 = b2 + kstep;
;             G_LDB(B0, 0, 0); G_LDB(B1, 0, 1); SCHED; G_LDA(At, 0, 0); G_STAGE(G_SA(1, 1), a1 + hstep, voffA);
;             WAIT_V(8); WAIT_L(0); BAR; G_MMA(0, 0, At, B0); G_MMA(0, 1, At, B1); BAR; SCHED;
;             G_LDA(At, 0, 1); G_STAGE(G_SB(0, 0), b2, voffA); G_STAGE(G_SB(0, 1), b2 + hstep, voffA); G_STAGE(G_SA(0, 0), a2, voffA);
;             WAIT_V(8); WAIT_L(0); BAR; G_MMA(1, 0, At, B0); G_MMA(1, 1, At, B1); BAR; SCHED;
.LBB0_303:
	s_add_u32 s30, s80, s48
	s_addc_u32 s31, s81, s49
	s_ashr_i32 s53, s52, 31
	s_lshl_b64 s[48:49], s[52:53], 18
	s_add_u32 s40, s80, s48
	s_addc_u32 s41, s81, s49
	s_ashr_i32 s37, s36, 31
	s_lshl_b64 s[20:21], s[36:37], 18
	v_readlane_b32 s34, v254, 53
	v_readlane_b32 s35, v254, 54
	s_add_u32 s20, s34, s20
	s_addc_u32 s21, s35, s21
	s_add_i32 s34, 0, 0x10000
	s_add_i32 s35, 0, 0x14000
	v_add_u32_e32 v12, s34, v140
	v_add_u32_e32 v28, s35, v140
	ds_read_b128 v[0:3], v12
	ds_read_b128 v[4:7], v12 offset:1024
	ds_read_b128 v[8:11], v12 offset:2048
	ds_read_b128 v[12:15], v12 offset:3072
	ds_read_b128 v[16:19], v28
	ds_read_b128 v[20:23], v28 offset:1024
	ds_read_b128 v[24:27], v28 offset:2048
	ds_read_b128 v[28:31], v28 offset:3072
	s_add_u32 s30, s30, 0x20080
	s_addc_u32 s31, s31, 0
	v_lshl_add_u64 v[64:65], s[30:31], 0, v[192:193]
	s_add_i32 m0, s8, 0xc000
	ds_read_b128 v[32:35], v141
	ds_read_b128 v[36:39], v141 offset:1024
	ds_read_b128 v[40:43], v141 offset:2048
	ds_read_b128 v[44:47], v141 offset:3072
	ds_read_b128 v[48:51], v141 offset:4096
	ds_read_b128 v[52:55], v141 offset:5120
	ds_read_b128 v[56:59], v141 offset:6144
	ds_read_b128 v[60:63], v141 offset:7168
	global_load_lds_dwordx4 v[64:65], off
	v_lshl_add_u64 v[64:65], s[30:31], 0, v[128:129]
	s_add_i32 m0, s8, 0xe000
	s_nop 0
	global_load_lds_dwordx4 v[64:65], off
	s_waitcnt vmcnt(8)
	s_waitcnt lgkmcnt(0)
	s_barrier
	s_setprio 1
	s_waitcnt lgkmcnt(0)
	v_mfma_f32_16x16x32_bf16 v[88:91], v[0:3], v[56:59], 0
	v_mfma_f32_16x16x32_bf16 v[64:67], v[0:3], v[32:35], 0
	v_mfma_f32_16x16x32_bf16 v[68:71], v[8:11], v[32:35], 0
	v_mfma_f32_16x16x32_bf16 v[72:75], v[0:3], v[40:43], 0
	v_mfma_f32_16x16x32_bf16 v[76:79], v[8:11], v[40:43], 0
	v_mfma_f32_16x16x32_bf16 v[80:83], v[0:3], v[48:51], 0
	v_mfma_f32_16x16x32_bf16 v[84:87], v[8:11], v[48:51], 0
	v_mfma_f32_16x16x32_bf16 v[96:99], v[4:7], v[60:63], v[88:91]
	v_mfma_f32_16x16x32_bf16 v[88:91], v[8:11], v[56:59], 0
	v_mfma_f32_16x16x32_bf16 v[64:67], v[4:7], v[36:39], v[64:67]
	v_mfma_f32_16x16x32_bf16 v[68:71], v[12:15], v[36:39], v[68:71]
	v_mfma_f32_16x16x32_bf16 v[72:75], v[4:7], v[44:47], v[72:75]
	v_mfma_f32_16x16x32_bf16 v[76:79], v[12:15], v[44:47], v[76:79]
	v_mfma_f32_16x16x32_bf16 v[80:83], v[4:7], v[52:55], v[80:83]
	v_mfma_f32_16x16x32_bf16 v[84:87], v[12:15], v[52:55], v[84:87]
	v_mfma_f32_16x16x32_bf16 v[100:103], v[12:15], v[60:63], v[88:91]
	s_setprio 0
	s_setprio 1
	v_mfma_f32_16x16x32_bf16 v[88:91], v[16:19], v[32:35], 0
	v_mfma_f32_16x16x32_bf16 v[32:35], v[24:27], v[32:35], 0
	v_mfma_f32_16x16x32_bf16 v[112:115], v[20:23], v[36:39], v[88:91]
	v_mfma_f32_16x16x32_bf16 v[32:35], v[28:31], v[36:39], v[32:35]
	v_mfma_f32_16x16x32_bf16 v[36:39], v[16:19], v[40:43], 0
	v_mfma_f32_16x16x32_bf16 v[40:43], v[24:27], v[40:43], 0
	v_mfma_f32_16x16x32_bf16 v[36:39], v[20:23], v[44:47], v[36:39]
	v_mfma_f32_16x16x32_bf16 v[40:43], v[28:31], v[44:47], v[40:43]
	v_mfma_f32_16x16x32_bf16 v[44:47], v[16:19], v[48:51], 0
	v_mfma_f32_16x16x32_bf16 v[48:51], v[24:27], v[48:51], 0
	v_mfma_f32_16x16x32_bf16 v[44:47], v[20:23], v[52:55], v[44:47]
	v_mfma_f32_16x16x32_bf16 v[48:51], v[28:31], v[52:55], v[48:51]
	v_mfma_f32_16x16x32_bf16 v[52:55], v[16:19], v[56:59], 0
	v_mfma_f32_16x16x32_bf16 v[56:59], v[24:27], v[56:59], 0
	v_mfma_f32_16x16x32_bf16 v[52:55], v[20:23], v[60:63], v[52:55]
	v_mfma_f32_16x16x32_bf16 v[56:59], v[28:31], v[60:63], v[56:59]
	s_setprio 0
	s_barrier
	s_add_i32 s30, s34, s33
	v_lshl_add_u64 v[190:191], s[20:21], 0, v[192:193]
	s_mov_b32 m0, s30
	ds_read_b128 v[60:63], v141 offset:16384
	ds_read_b128 v[88:91], v141 offset:17408
	ds_read_b128 v[92:95], v141 offset:18432
	ds_read_b128 v[104:107], v141 offset:19456
	ds_read_b128 v[108:111], v141 offset:20480
	ds_read_b128 v[116:119], v141 offset:21504
	ds_read_b128 v[120:123], v141 offset:22528
	ds_read_b128 v[124:127], v141 offset:23552
	global_load_lds_dwordx4 v[190:191], off
	s_add_i32 m0, s30, 0x2000
	s_add_u32 s30, s20, 0x20000
	v_lshl_add_u64 v[236:237], s[20:21], 0, v[128:129]
	s_addc_u32 s31, s21, 0
	s_add_i32 s34, s35, s33
	global_load_lds_dwordx4 v[236:237], off
	v_lshl_add_u64 v[130:131], s[30:31], 0, v[192:193]
	s_mov_b32 m0, s34
	v_lshl_add_u64 v[238:239], s[40:41], 0, v[192:193]
	global_load_lds_dwordx4 v[130:131], off
	v_lshl_add_u64 v[130:131], s[30:31], 0, v[128:129]
	s_add_i32 m0, s34, 0x2000
	v_lshl_add_u64 v[240:241], s[40:41], 0, v[128:129]
	global_load_lds_dwordx4 v[130:131], off
	s_mov_b32 m0, s8
	s_nop 0
	global_load_lds_dwordx4 v[238:239], off
	s_mov_b32 m0, s9
	s_nop 0
	global_load_lds_dwordx4 v[240:241], off
	s_waitcnt vmcnt(8)
	s_waitcnt lgkmcnt(0)
	s_barrier
; #define G_STAGE(bufoff, gbase, voff) do { _Pragma("unroll") for (int _i = 0; _i < 2; ++_i) \
;     __builtin_amdgcn_global_load_lds((const unsigned*)((const char*)(gbase) + (voff)[_i]), (LAS unsigned*)(lds + (bufoff) + ldsw + _i * 8192), 16, 0, 0); } while (0)
; #define G_LDA(dst, b, h) do { _Pragma("unroll") for (int m = 0; m < 4; ++m) _Pragma("unroll") for (int k = 0; k < 2; ++k) dst[m][k] = *(const LAS bf16x8*)(lds + G_SA(b, h) + aoff + m * 2048 + k * 1024); } while (0)
; #define G_LDB(dst, b, h) do { _Pragma("unroll") for (int n = 0; n < 2; ++n) _Pragma("unroll") for (int k = 0; k < 2; ++k) dst[n][k] = *(const LAS bf16x8*)(lds + G_SB(b, h) + boff + n * 2048 + k * 1024); } while (0)
; #define G_MMA(ai, bj, At, Bt) do { __builtin_amdgcn_s_setprio(1); _Pragma("unroll") for (int m = 0; m < 4; ++m) _Pragma("unroll") for (int n = 0; n < 2; ++n) _Pragma("unroll") for (int k = 0; k < 2; ++k) \
;     acc[ai][bj][m][n] = __builtin_amdgcn_mfma_f32_16x16x32_bf16(Bt[n][k], At[m][k], acc[ai][bj][m][n], 0, 0, 0); __builtin_amdgcn_s_setprio(0); } while (0)
; #define WAIT_V(n) asm volatile("s_waitcnt vmcnt(" #n ")" ::: "memory")
; #define WAIT_L(n) asm volatile("s_waitcnt lgkmcnt(" #n ")" ::: "memory")
; #define BAR __builtin_amdgcn_s_barrier()
; #define SCHED __builtin_amdgcn_sched_barrier(0)
; template <class Epi>
; __device__ __forceinline__ void gemm_phase(const bf16_t* __restrict__ A, int lda, const bf16_t* __restrict__ Bt, int ldb, int K, int nM, int nN, const Epi& epi, LAS unsigned char* lds, int wv) {
;     ...
;             WAIT_V(8); WAIT_L(0); BAR; G_MMA(1, 0, At, B0); G_MMA(1, 1, At, B1); BAR; SCHED;
;             G_LDB(B0, 1, 0); G_LDB(B1, 1, 1); SCHED; G_LDA(At, 1, 0); G_STAGE(G_SA(0, 1), a2 + hstep, voffA);
;             WAIT_V(8); WAIT_L(0); BAR; G_MMA(0, 0, At, B0); G_MMA(0, 1, At, B1); BAR; SCHED;
;             G_LDA(At, 1, 1); G_STAGE(G_SB(1, 0), b3, voffA); G_STAGE(G_SB(1, 1), b3 + hstep, voffA); G_STAGE(G_SA(1, 0), a3, voffA);
	s_setprio 1
	s_waitcnt lgkmcnt(0)
	v_mfma_f32_16x16x32_bf16 v[130:133], v[0:3], v[60:63], 0
	v_mfma_f32_16x16x32_bf16 v[142:145], v[0:3], v[92:95], 0
	v_mfma_f32_16x16x32_bf16 v[150:153], v[0:3], v[108:111], 0
	v_mfma_f32_16x16x32_bf16 v[0:3], v[0:3], v[120:123], 0
	v_mfma_f32_16x16x32_bf16 v[130:133], v[4:7], v[88:91], v[130:133]
	v_mfma_f32_16x16x32_bf16 v[134:137], v[8:11], v[60:63], 0
	v_mfma_f32_16x16x32_bf16 v[142:145], v[4:7], v[104:107], v[142:145]
	v_mfma_f32_16x16x32_bf16 v[146:149], v[8:11], v[92:95], 0
	v_mfma_f32_16x16x32_bf16 v[150:153], v[4:7], v[116:119], v[150:153]
	v_mfma_f32_16x16x32_bf16 v[154:157], v[8:11], v[108:111], 0
	v_mfma_f32_16x16x32_bf16 v[0:3], v[4:7], v[124:127], v[0:3]
	v_mfma_f32_16x16x32_bf16 v[4:7], v[8:11], v[120:123], 0
	v_mfma_f32_16x16x32_bf16 v[134:137], v[12:15], v[88:91], v[134:137]
	v_mfma_f32_16x16x32_bf16 v[146:149], v[12:15], v[104:107], v[146:149]
	v_mfma_f32_16x16x32_bf16 v[154:157], v[12:15], v[116:119], v[154:157]
	v_mfma_f32_16x16x32_bf16 v[4:7], v[12:15], v[124:127], v[4:7]
	s_setprio 0
	s_setprio 1
	v_mfma_f32_16x16x32_bf16 v[8:11], v[16:19], v[60:63], 0
	v_mfma_f32_16x16x32_bf16 v[158:161], v[20:23], v[88:91], v[8:11]
	v_mfma_f32_16x16x32_bf16 v[8:11], v[24:27], v[60:63], 0
	v_mfma_f32_16x16x32_bf16 v[162:165], v[28:31], v[88:91], v[8:11]
	v_mfma_f32_16x16x32_bf16 v[8:11], v[16:19], v[92:95], 0
	v_mfma_f32_16x16x32_bf16 v[166:169], v[20:23], v[104:107], v[8:11]
	v_mfma_f32_16x16x32_bf16 v[8:11], v[24:27], v[92:95], 0
	v_mfma_f32_16x16x32_bf16 v[170:173], v[28:31], v[104:107], v[8:11]
	v_mfma_f32_16x16x32_bf16 v[8:11], v[16:19], v[108:111], 0
	v_mfma_f32_16x16x32_bf16 v[174:177], v[20:23], v[116:119], v[8:11]
	v_mfma_f32_16x16x32_bf16 v[8:11], v[24:27], v[108:111], 0
	v_mfma_f32_16x16x32_bf16 v[178:181], v[28:31], v[116:119], v[8:11]
	v_mfma_f32_16x16x32_bf16 v[8:11], v[16:19], v[120:123], 0
	v_mfma_f32_16x16x32_bf16 v[182:185], v[20:23], v[124:127], v[8:11]
	v_mfma_f32_16x16x32_bf16 v[8:11], v[24:27], v[120:123], 0
	v_mfma_f32_16x16x32_bf16 v[186:189], v[28:31], v[124:127], v[8:11]
	s_setprio 0
	s_barrier
	s_add_i32 s34, 0, 0x18000
	s_add_i32 s35, 0, 0x1c000
	v_add_u32_e32 v20, s34, v140
	v_add_u32_e32 v24, s35, v140
	s_nop 0
	ds_read_b128 v[8:11], v20
	ds_read_b128 v[12:15], v20 offset:1024
	ds_read_b128 v[16:19], v20 offset:2048
	ds_read_b128 v[20:23], v20 offset:3072
	ds_read_b128 v[194:197], v24
	ds_read_b128 v[198:201], v24 offset:1024
	ds_read_b128 v[202:205], v24 offset:2048
	ds_read_b128 v[206:209], v24 offset:3072
	s_add_u32 s30, s40, 0x20000
	s_addc_u32 s31, s41, 0
	s_mov_b32 m0, s42
	v_lshl_add_u64 v[88:89], s[30:31], 0, v[192:193]
	ds_read_b128 v[24:27], v141 offset:32768
	ds_read_b128 v[28:31], v141 offset:33792
	ds_read_b128 v[60:63], v141 offset:34816
	ds_read_b128 v[210:213], v141 offset:35840
	ds_read_b128 v[214:217], v141 offset:36864
	ds_read_b128 v[218:221], v141 offset:37888
	ds_read_b128 v[224:227], v141 offset:38912
	ds_read_b128 v[228:231], v141 offset:39936
	global_load_lds_dwordx4 v[88:89], off
	v_lshl_add_u64 v[88:89], s[30:31], 0, v[128:129]
	s_mov_b32 m0, s43
	s_nop 0
	global_load_lds_dwordx4 v[88:89], off
	s_waitcnt vmcnt(8)
	s_waitcnt lgkmcnt(0)
	s_barrier
	s_setprio 1
	s_waitcnt lgkmcnt(0)
	v_mfma_f32_16x16x32_bf16 v[64:67], v[8:11], v[24:27], v[64:67]
	v_mfma_f32_16x16x32_bf16 v[124:127], v[12:15], v[28:31], v[64:67]
	v_mfma_f32_16x16x32_bf16 v[64:67], v[16:19], v[24:27], v[68:71]
	v_mfma_f32_16x16x32_bf16 v[120:123], v[20:23], v[28:31], v[64:67]
	v_mfma_f32_16x16x32_bf16 v[64:67], v[8:11], v[60:63], v[72:75]
	v_mfma_f32_16x16x32_bf16 v[108:111], v[12:15], v[210:213], v[64:67]
	v_mfma_f32_16x16x32_bf16 v[64:67], v[16:19], v[60:63], v[76:79]
	v_mfma_f32_16x16x32_bf16 v[104:107], v[20:23], v[210:213], v[64:67]
	v_mfma_f32_16x16x32_bf16 v[64:67], v[8:11], v[214:217], v[80:83]
	v_mfma_f32_16x16x32_bf16 v[92:95], v[12:15], v[218:221], v[64:67]
	v_mfma_f32_16x16x32_bf16 v[64:67], v[16:19], v[214:217], v[84:87]
	v_mfma_f32_16x16x32_bf16 v[88:91], v[20:23], v[218:221], v[64:67]
	v_mfma_f32_16x16x32_bf16 v[64:67], v[8:11], v[224:227], v[96:99]
	v_mfma_f32_16x16x32_bf16 v[76:79], v[12:15], v[228:231], v[64:67]
	v_mfma_f32_16x16x32_bf16 v[64:67], v[16:19], v[224:227], v[100:103]
	v_mfma_f32_16x16x32_bf16 v[72:75], v[20:23], v[228:231], v[64:67]
	s_setprio 0
	s_setprio 1
	v_mfma_f32_16x16x32_bf16 v[64:67], v[194:197], v[24:27], v[112:115]
	v_mfma_f32_16x16x32_bf16 v[24:27], v[202:205], v[24:27], v[32:35]
	v_mfma_f32_16x16x32_bf16 v[112:115], v[206:209], v[28:31], v[24:27]
	v_mfma_f32_16x16x32_bf16 v[24:27], v[194:197], v[60:63], v[36:39]
	v_mfma_f32_16x16x32_bf16 v[100:103], v[198:201], v[210:213], v[24:27]
	v_mfma_f32_16x16x32_bf16 v[24:27], v[202:205], v[60:63], v[40:43]
	v_mfma_f32_16x16x32_bf16 v[96:99], v[206:209], v[210:213], v[24:27]
	v_mfma_f32_16x16x32_bf16 v[24:27], v[194:197], v[214:217], v[44:47]
	v_mfma_f32_16x16x32_bf16 v[84:87], v[198:201], v[218:221], v[24:27]
	v_mfma_f32_16x16x32_bf16 v[24:27], v[202:205], v[214:217], v[48:51]
	v_mfma_f32_16x16x32_bf16 v[80:83], v[206:209], v[218:221], v[24:27]
	v_mfma_f32_16x16x32_bf16 v[24:27], v[194:197], v[224:227], v[52:55]
	v_mfma_f32_16x16x32_bf16 v[68:71], v[198:201], v[228:231], v[24:27]
	v_mfma_f32_16x16x32_bf16 v[24:27], v[202:205], v[224:227], v[56:59]
	v_mfma_f32_16x16x32_bf16 v[116:119], v[198:201], v[28:31], v[64:67]
	v_mfma_f32_16x16x32_bf16 v[64:67], v[206:209], v[228:231], v[24:27]
	s_setprio 0
	s_barrier
; __device__ __forceinline__ unsigned cvt_pk_bf16(float lo, float hi) { unsigned r; asm volatile("v_cvt_pk_bf16_f32 %0, %1, %2" : "=v"(r) : "v"(lo), "v"(hi)); return r; }
; __device__ __forceinline__ float sigmoidf_(float x) { return __builtin_amdgcn_rcpf(1.0f + __builtin_amdgcn_exp2f(-1.44269504088896f * x)); }
; #define G_STAGE(bufoff, gbase, voff) do { _Pragma("unroll") for (int _i = 0; _i < 2; ++_i) \
;     __builtin_amdgcn_global_load_lds((const unsigned*)((const char*)(gbase) + (voff)[_i]), (LAS unsigned*)(lds + (bufoff) + ldsw + _i * 8192), 16, 0, 0); } while (0)
; #define WAIT_V(n) asm volatile("s_waitcnt vmcnt(" #n ")" ::: "memory")
; #define BAR __builtin_amdgcn_s_barrier()
; template <class Epi>
; __device__ __forceinline__ void gemm_phase(const bf16_t* __restrict__ A, int lda, const bf16_t* __restrict__ Bt, int ldb, int K, int nM, int nN, const Epi& epi, LAS unsigned char* lds, int wv) {
;     ...
;             G_LDA(At, 1, 1); G_STAGE(G_SB(1, 0), b3, voffA); G_STAGE(G_SB(1, 1), b3 + hstep, voffA); G_STAGE(G_SA(1, 0), a3, voffA);
;             WAIT_V(8); WAIT_L(0); BAR; G_MMA(1, 0, At, B0); G_MMA(1, 1, At, B1); BAR; SCHED;
;     __device__ __forceinline__ void operator()(AccRef acc, int pm, int pn, int wr, int wc, int fr, int fq) const {
;         pn += pn_off; const int sec = pn >> 2; const long doff = sec == 0 ? 0 : (sec == 1 ? offAA : offG); bf16_t* dst = E + doff; const float* bias = w0 + (sec == 0 ? 0 : offa0);
; #pragma unroll
;         for (int ai = 0; ai < 2; ++ai)
; #pragma unroll
;             for (int m = 0; m < 4; ++m) { bf16_t* rp = dst + (size_t)EPI_ROW(ai, m) * 1024;
; #pragma unroll
;                 for (int bj = 0; bj < 2; ++bj) { const int c0 = (pn & 3) * 256 + wc * 64 + bj * 32 + 8 * fq; u32x4 w; unsigned pk[4];
; #pragma unroll
;                     for (int n = 0; n < 2; ++n) { const f32x4 v = acc[ai][bj][m][n]; const f32x4 b = *(const f32x4*)(bias + c0 + 4 * n);
;                         f32x4 r;
; #pragma unroll
;                         for (int j = 0; j < 4; ++j) { const float z = b[j] + v[j]; const float sg = sigmoidf_(z);
;                             r[j] = sec == 0 ? sg * 0.60653065971f : (sec == 1 ? sg : v[j]); }
;                         pk[2 * n] = cvt_pk_bf16(r[0], r[1]); pk[2 * n + 1] = cvt_pk_bf16(r[2], r[3]); }
;                     w.x = pk[0]; w.y = pk[1]; w.z = pk[2]; w.w = pk[3]; *(u32x4*)(rp + c0) = w; } }
	s_add_i32 s30, s34, s33
	s_nop 2
	v_lshl_add_u64 v[24:25], v[190:191], 0, s[10:11]
	s_mov_b32 m0, s30
	ds_read_b128 v[32:35], v141 offset:49152
	ds_read_b128 v[36:39], v141 offset:50176
	ds_read_b128 v[210:213], v141 offset:51200
	ds_read_b128 v[214:217], v141 offset:52224
	ds_read_b128 v[218:221], v141 offset:53248
	ds_read_b128 v[224:227], v141 offset:54272
	ds_read_b128 v[228:231], v141 offset:55296
	ds_read_b128 v[232:235], v141 offset:56320
	global_load_lds_dwordx4 v[24:25], off
	s_add_i32 m0, s30, 0x2000
	s_add_u32 s20, s20, 0x20080
	v_lshl_add_u64 v[24:25], v[236:237], 0, s[10:11]
	s_addc_u32 s21, s21, 0
	s_add_i32 s30, s35, s33
	global_load_lds_dwordx4 v[24:25], off
	v_lshl_add_u64 v[24:25], s[20:21], 0, v[192:193]
	s_mov_b32 m0, s30
	s_nop 0
	global_load_lds_dwordx4 v[24:25], off
	v_lshl_add_u64 v[24:25], s[20:21], 0, v[128:129]
	s_add_i32 m0, s30, 0x2000
	s_nop 0
	global_load_lds_dwordx4 v[24:25], off
	v_lshl_add_u64 v[24:25], v[238:239], 0, s[10:11]
	s_mov_b32 m0, s4
	s_nop 0
	global_load_lds_dwordx4 v[24:25], off
	v_lshl_add_u64 v[24:25], v[240:241], 0, s[10:11]
	s_mov_b32 m0, s55
	s_nop 0
	global_load_lds_dwordx4 v[24:25], off
	s_waitcnt vmcnt(8)
	s_waitcnt lgkmcnt(0)
	s_barrier
	s_setprio 1
	s_waitcnt lgkmcnt(0)
	v_mfma_f32_16x16x32_bf16 v[24:27], v[8:11], v[32:35], v[130:133]
	v_mfma_f32_16x16x32_bf16 v[60:63], v[12:15], v[36:39], v[24:27]
	v_mfma_f32_16x16x32_bf16 v[24:27], v[16:19], v[32:35], v[134:137]
	v_mfma_f32_16x16x32_bf16 v[56:59], v[20:23], v[36:39], v[24:27]
	v_mfma_f32_16x16x32_bf16 v[24:27], v[8:11], v[210:213], v[142:145]
	v_mfma_f32_16x16x32_bf16 v[44:47], v[12:15], v[214:217], v[24:27]
	v_mfma_f32_16x16x32_bf16 v[24:27], v[16:19], v[210:213], v[146:149]
	v_mfma_f32_16x16x32_bf16 v[40:43], v[20:23], v[214:217], v[24:27]
	v_mfma_f32_16x16x32_bf16 v[24:27], v[8:11], v[218:221], v[150:153]
	v_mfma_f32_16x16x32_bf16 v[0:3], v[8:11], v[228:231], v[0:3]
	v_mfma_f32_16x16x32_bf16 v[28:31], v[12:15], v[224:227], v[24:27]
	v_mfma_f32_16x16x32_bf16 v[24:27], v[16:19], v[218:221], v[154:157]
	v_mfma_f32_16x16x32_bf16 v[12:15], v[12:15], v[232:235], v[0:3]
	v_mfma_f32_16x16x32_bf16 v[0:3], v[16:19], v[228:231], v[4:7]
	v_mfma_f32_16x16x32_bf16 v[24:27], v[20:23], v[224:227], v[24:27]
	v_mfma_f32_16x16x32_bf16 v[8:11], v[20:23], v[232:235], v[0:3]
	s_setprio 0
	s_setprio 1
	v_mfma_f32_16x16x32_bf16 v[0:3], v[194:197], v[32:35], v[158:161]
	v_mfma_f32_16x16x32_bf16 v[52:55], v[198:201], v[36:39], v[0:3]
	v_mfma_f32_16x16x32_bf16 v[0:3], v[202:205], v[32:35], v[162:165]
	v_mfma_f32_16x16x32_bf16 v[48:51], v[206:209], v[36:39], v[0:3]
	v_mfma_f32_16x16x32_bf16 v[0:3], v[194:197], v[210:213], v[166:169]
	v_mfma_f32_16x16x32_bf16 v[36:39], v[198:201], v[214:217], v[0:3]
	v_mfma_f32_16x16x32_bf16 v[0:3], v[202:205], v[210:213], v[170:173]
	v_mfma_f32_16x16x32_bf16 v[32:35], v[206:209], v[214:217], v[0:3]
	v_mfma_f32_16x16x32_bf16 v[0:3], v[194:197], v[218:221], v[174:177]
	v_mfma_f32_16x16x32_bf16 v[20:23], v[198:201], v[224:227], v[0:3]
	v_mfma_f32_16x16x32_bf16 v[0:3], v[202:205], v[218:221], v[178:181]
	v_mfma_f32_16x16x32_bf16 v[16:19], v[206:209], v[224:227], v[0:3]
	v_mfma_f32_16x16x32_bf16 v[0:3], v[194:197], v[228:231], v[182:185]
	v_mfma_f32_16x16x32_bf16 v[4:7], v[198:201], v[232:235], v[0:3]
	v_mfma_f32_16x16x32_bf16 v[0:3], v[202:205], v[228:231], v[186:189]
	v_mfma_f32_16x16x32_bf16 v[0:3], v[206:209], v[232:235], v[0:3]
	s_setprio 0
	s_barrier
	s_and_b32 s20, s29, -4
	s_cmp_eq_u32 s20, 4
	s_cselect_b64 vcc, -1, 0
	s_and_b64 s[20:21], vcc, exec
	s_cselect_b32 s30, 0x4000000, s58
	s_cmp_lt_u32 s29, 4
	s_cselect_b64 s[40:41], -1, 0
	s_and_b64 s[20:21], s[40:41], exec
	s_cselect_b32 s20, 0, s30
	s_cselect_b32 s30, 0, s60
	s_cselect_b32 s31, 0, s61
	s_or_b64 s[34:35], s[40:41], vcc
	s_and_b64 s[34:35], s[34:35], exec
	s_cselect_b32 s21, 0, s59
	s_lshl_b64 s[20:21], s[20:21], 1
	s_add_u32 s20, s12, s20
	s_addc_u32 s21, s13, s21
	s_lshl_b64 s[30:31], s[30:31], 2
	s_add_u32 s30, s46, s30
	s_addc_u32 s31, s47, s31
	s_lshl_b32 s34, s54, 8
	v_readlane_b32 s35, v253, 5
	v_mov_b32_e32 v130, v138
	v_mov_b32_e32 v131, v139
	s_add_i32 s34, s34, s35
	s_lshl_b32 s29, s29, 8
	s_and_b32 s29, s29, 0x300
	v_add_u32_e32 v132, s34, v130
	v_readlane_b32 s34, v253, 19
	s_or_b32 s29, s29, s34
	v_lshl_add_u32 v134, v131, 3, s29
	v_ashrrev_i32_e32 v133, 31, v132
	v_lshlrev_b64 v[130:131], 11, v[132:133]
	v_ashrrev_i32_e32 v135, 31, v134
	v_lshl_add_u64 v[136:137], s[20:21], 0, v[130:131]
	v_lshl_add_u64 v[130:131], v[134:135], 2, s[30:31]
	global_load_dwordx4 v[148:151], v[130:131], off
	global_load_dwordx4 v[152:155], v[130:131], off offset:16
	global_load_dwordx4 v[156:159], v[130:131], off offset:128
	global_load_dwordx4 v[160:163], v[130:131], off offset:144
	s_mov_b32 s54, s52
	s_mov_b32 s29, s36
	s_waitcnt vmcnt(0)
; __device__ __forceinline__ unsigned cvt_pk_bf16(float lo, float hi) { unsigned r; asm volatile("v_cvt_pk_bf16_f32 %0, %1, %2" : "=v"(r) : "v"(lo), "v"(hi)); return r; }
; __device__ __forceinline__ float sigmoidf_(float x) { return __builtin_amdgcn_rcpf(1.0f + __builtin_amdgcn_exp2f(-1.44269504088896f * x)); }
;     __device__ __forceinline__ void operator()(AccRef acc, int pm, int pn, int wr, int wc, int fr, int fq) const {
;     ...
;             for (int m = 0; m < 4; ++m) { bf16_t* rp = dst + (size_t)EPI_ROW(ai, m) * 1024;
; #pragma unroll
;                 for (int bj = 0; bj < 2; ++bj) { const int c0 = (pn & 3) * 256 + wc * 64 + bj * 32 + 8 * fq; u32x4 w; unsigned pk[4];
; #pragma unroll
;                     for (int n = 0; n < 2; ++n) { const f32x4 v = acc[ai][bj][m][n]; const f32x4 b = *(const f32x4*)(bias + c0 + 4 * n);
;                         f32x4 r;
; #pragma unroll
;                         for (int j = 0; j < 4; ++j) { const float z = b[j] + v[j]; const float sg = sigmoidf_(z);
;                             r[j] = sec == 0 ? sg * 0.60653065971f : (sec == 1 ? sg : v[j]); }
;                         pk[2 * n] = cvt_pk_bf16(r[0], r[1]); pk[2 * n + 1] = cvt_pk_bf16(r[2], r[3]); }
;                     w.x = pk[0]; w.y = pk[1]; w.z = pk[2]; w.w = pk[3]; *(u32x4*)(rp + c0) = w; } }
	v_add_f32_e32 v133, v124, v148
	v_mul_f32_e32 v133, 0xbfb8aa3b, v133
	v_exp_f32_e32 v133, v133
	s_nop 0
	v_add_f32_e32 v133, 1.0, v133
	v_rcp_f32_e32 v133, v133
	s_nop 0
	v_mul_f32_e32 v142, 0x3f1b4598, v133
	v_cndmask_b32_e32 v124, v124, v133, vcc
	v_add_f32_e32 v133, v125, v149
	v_mul_f32_e32 v133, 0xbfb8aa3b, v133
	v_exp_f32_e32 v133, v133
	v_cndmask_b32_e64 v124, v124, v142, s[40:41]
	v_add_f32_e32 v133, 1.0, v133
	v_rcp_f32_e32 v133, v133
	s_nop 0
	v_mul_f32_e32 v142, 0x3f1b4598, v133
	v_cndmask_b32_e32 v125, v125, v133, vcc
	v_add_f32_e32 v133, v126, v150
	v_mul_f32_e32 v133, 0xbfb8aa3b, v133
	v_exp_f32_e32 v133, v133
	v_cndmask_b32_e64 v125, v125, v142, s[40:41]
	v_cvt_pk_bf16_f32 v124, v124, v125
	v_add_f32_e32 v133, 1.0, v133
	v_rcp_f32_e32 v133, v133
	s_nop 0
	v_mul_f32_e32 v142, 0x3f1b4598, v133
	v_cndmask_b32_e32 v126, v126, v133, vcc
	v_add_f32_e32 v133, v127, v151
	v_mul_f32_e32 v133, 0xbfb8aa3b, v133
	v_exp_f32_e32 v133, v133
	v_cndmask_b32_e64 v126, v126, v142, s[40:41]
	v_add_f32_e32 v133, 1.0, v133
	v_rcp_f32_e32 v133, v133
	s_nop 0
	v_mul_f32_e32 v142, 0x3f1b4598, v133
	v_cndmask_b32_e32 v127, v127, v133, vcc
	v_cndmask_b32_e64 v127, v127, v142, s[40:41]
	v_cvt_pk_bf16_f32 v125, v126, v127
	v_add_f32_e32 v126, v120, v152
	v_mul_f32_e32 v126, 0xbfb8aa3b, v126
	v_exp_f32_e32 v126, v126
	s_nop 0
	v_add_f32_e32 v126, 1.0, v126
	v_rcp_f32_e32 v126, v126
	s_nop 0
	v_mul_f32_e32 v127, 0x3f1b4598, v126
	v_cndmask_b32_e32 v120, v120, v126, vcc
	v_add_f32_e32 v126, v121, v153
	v_mul_f32_e32 v126, 0xbfb8aa3b, v126
	v_exp_f32_e32 v126, v126
	v_cndmask_b32_e64 v120, v120, v127, s[40:41]
	v_add_f32_e32 v126, 1.0, v126
	v_rcp_f32_e32 v126, v126
	s_nop 0
	v_mul_f32_e32 v127, 0x3f1b4598, v126
	v_cndmask_b32_e32 v121, v121, v126, vcc
	v_add_f32_e32 v126, v122, v154
	v_mul_f32_e32 v126, 0xbfb8aa3b, v126
	v_exp_f32_e32 v126, v126
	v_cndmask_b32_e64 v121, v121, v127, s[40:41]
	v_add_f32_e32 v126, 1.0, v126
	v_rcp_f32_e32 v126, v126
	s_nop 0
	v_mul_f32_e32 v127, 0x3f1b4598, v126
	v_cndmask_b32_e32 v122, v122, v126, vcc
	v_add_f32_e32 v126, v123, v155
	v_mul_f32_e32 v126, 0xbfb8aa3b, v126
	v_exp_f32_e32 v126, v126
	v_cndmask_b32_e64 v122, v122, v127, s[40:41]
	v_add_f32_e32 v126, 1.0, v126
	v_rcp_f32_e32 v126, v126
	s_nop 0
	v_mul_f32_e32 v127, 0x3f1b4598, v126
	v_cndmask_b32_e32 v123, v123, v126, vcc
	v_cndmask_b32_e64 v123, v123, v127, s[40:41]
	v_cvt_pk_bf16_f32 v126, v120, v121
	v_lshlrev_b64 v[120:121], 1, v[134:135]
	v_cvt_pk_bf16_f32 v127, v122, v123
	v_lshl_add_u64 v[122:123], v[136:137], 0, v[120:121]
	flat_store_dwordx4 v[122:123], v[124:127]
	s_nop 1
	v_add_f32_e32 v124, v116, v156
	v_mul_f32_e32 v124, 0xbfb8aa3b, v124
	v_exp_f32_e32 v124, v124
	s_nop 0
	v_add_f32_e32 v124, 1.0, v124
	v_rcp_f32_e32 v124, v124
	s_nop 0
	v_mul_f32_e32 v133, 0x3f1b4598, v124
	v_cndmask_b32_e32 v116, v116, v124, vcc
	v_add_f32_e32 v124, v117, v157
	v_mul_f32_e32 v124, 0xbfb8aa3b, v124
	v_exp_f32_e32 v124, v124
	v_cndmask_b32_e64 v116, v116, v133, s[40:41]
	v_add_f32_e32 v124, 1.0, v124
	v_rcp_f32_e32 v124, v124
	s_nop 0
	v_mul_f32_e32 v125, 0x3f1b4598, v124
	v_cndmask_b32_e32 v117, v117, v124, vcc
	v_add_f32_e32 v124, v118, v158
	v_mul_f32_e32 v124, 0xbfb8aa3b, v124
	v_exp_f32_e32 v124, v124
	v_cndmask_b32_e64 v117, v117, v125, s[40:41]
	v_cvt_pk_bf16_f32 v116, v116, v117
	v_add_f32_e32 v124, 1.0, v124
	v_rcp_f32_e32 v124, v124
	s_nop 0
	v_mul_f32_e32 v125, 0x3f1b4598, v124
	v_cndmask_b32_e32 v118, v118, v124, vcc
	v_add_f32_e32 v124, v119, v159
	v_mul_f32_e32 v124, 0xbfb8aa3b, v124
	v_exp_f32_e32 v124, v124
	v_cndmask_b32_e64 v118, v118, v125, s[40:41]
	v_add_f32_e32 v124, 1.0, v124
	v_rcp_f32_e32 v124, v124
	s_nop 0
	v_mul_f32_e32 v125, 0x3f1b4598, v124
	v_cndmask_b32_e32 v119, v119, v124, vcc
	v_cndmask_b32_e64 v119, v119, v125, s[40:41]
	v_cvt_pk_bf16_f32 v117, v118, v119
	v_add_f32_e32 v118, v112, v160
	v_mul_f32_e32 v118, 0xbfb8aa3b, v118
	v_exp_f32_e32 v118, v118
	s_nop 0
	v_add_f32_e32 v118, 1.0, v118
	v_rcp_f32_e32 v118, v118
	s_nop 0
	v_mul_f32_e32 v119, 0x3f1b4598, v118
	v_cndmask_b32_e32 v112, v112, v118, vcc
	v_add_f32_e32 v118, v113, v161
	v_mul_f32_e32 v118, 0xbfb8aa3b, v118
	v_exp_f32_e32 v118, v118
	v_cndmask_b32_e64 v112, v112, v119, s[40:41]
	v_add_f32_e32 v118, 1.0, v118
	v_rcp_f32_e32 v118, v118
	s_nop 0
	v_mul_f32_e32 v119, 0x3f1b4598, v118
	v_cndmask_b32_e32 v113, v113, v118, vcc
	v_add_f32_e32 v118, v114, v162
	v_mul_f32_e32 v118, 0xbfb8aa3b, v118
	v_exp_f32_e32 v118, v118
	v_cndmask_b32_e64 v113, v113, v119, s[40:41]
	v_add_f32_e32 v118, 1.0, v118
	v_rcp_f32_e32 v118, v118
	s_nop 0
	v_mul_f32_e32 v119, 0x3f1b4598, v118
	v_cndmask_b32_e32 v114, v114, v118, vcc
	v_add_f32_e32 v118, v115, v163
	v_mul_f32_e32 v118, 0xbfb8aa3b, v118
	v_exp_f32_e32 v118, v118
	v_cndmask_b32_e64 v114, v114, v119, s[40:41]
	v_add_f32_e32 v118, 1.0, v118
	v_rcp_f32_e32 v118, v118
	s_nop 0
	v_mul_f32_e32 v119, 0x3f1b4598, v118
	v_cndmask_b32_e32 v115, v115, v118, vcc
	v_cndmask_b32_e64 v115, v115, v119, s[40:41]
	v_cvt_pk_bf16_f32 v118, v112, v113
	v_cvt_pk_bf16_f32 v119, v114, v115
	flat_store_dwordx4 v[122:123], v[116:119] offset:64
	s_nop 1
	v_add_u32_e32 v112, 16, v132
	v_ashrrev_i32_e32 v113, 31, v112
	v_lshlrev_b64 v[112:113], 11, v[112:113]
	v_lshl_add_u64 v[112:113], s[20:21], 0, v[112:113]
	v_add_f32_e32 v114, v108, v148
	v_mul_f32_e32 v114, 0xbfb8aa3b, v114
	v_exp_f32_e32 v114, v114
	s_nop 0
	v_add_f32_e32 v114, 1.0, v114
	v_rcp_f32_e32 v114, v114
	s_nop 0
	v_mul_f32_e32 v118, 0x3f1b4598, v114
	v_cndmask_b32_e32 v108, v108, v114, vcc
	v_add_f32_e32 v114, v109, v149
	v_mul_f32_e32 v114, 0xbfb8aa3b, v114
	v_exp_f32_e32 v114, v114
; __device__ __forceinline__ unsigned cvt_pk_bf16(float lo, float hi) { unsigned r; asm volatile("v_cvt_pk_bf16_f32 %0, %1, %2" : "=v"(r) : "v"(lo), "v"(hi)); return r; }
; __device__ __forceinline__ float sigmoidf_(float x) { return __builtin_amdgcn_rcpf(1.0f + __builtin_amdgcn_exp2f(-1.44269504088896f * x)); }
;     __device__ __forceinline__ void operator()(AccRef acc, int pm, int pn, int wr, int wc, int fr, int fq) const {
;     ...
;             for (int m = 0; m < 4; ++m) { bf16_t* rp = dst + (size_t)EPI_ROW(ai, m) * 1024;
; #pragma unroll
;                 for (int bj = 0; bj < 2; ++bj) { const int c0 = (pn & 3) * 256 + wc * 64 + bj * 32 + 8 * fq; u32x4 w; unsigned pk[4];
; #pragma unroll
;                     for (int n = 0; n < 2; ++n) { const f32x4 v = acc[ai][bj][m][n]; const f32x4 b = *(const f32x4*)(bias + c0 + 4 * n);
;                         f32x4 r;
; #pragma unroll
;                         for (int j = 0; j < 4; ++j) { const float z = b[j] + v[j]; const float sg = sigmoidf_(z);
;                             r[j] = sec == 0 ? sg * 0.60653065971f : (sec == 1 ? sg : v[j]); }
;                         pk[2 * n] = cvt_pk_bf16(r[0], r[1]); pk[2 * n + 1] = cvt_pk_bf16(r[2], r[3]); }
;                     w.x = pk[0]; w.y = pk[1]; w.z = pk[2]; w.w = pk[3]; *(u32x4*)(rp + c0) = w; } }
	v_cndmask_b32_e64 v108, v108, v118, s[40:41]
	v_add_f32_e32 v114, 1.0, v114
	v_rcp_f32_e32 v114, v114
	s_nop 0
	v_mul_f32_e32 v115, 0x3f1b4598, v114
	v_cndmask_b32_e32 v109, v109, v114, vcc
	v_add_f32_e32 v114, v110, v150
	v_mul_f32_e32 v114, 0xbfb8aa3b, v114
	v_exp_f32_e32 v114, v114
	v_cndmask_b32_e64 v109, v109, v115, s[40:41]
	v_cvt_pk_bf16_f32 v108, v108, v109
	v_add_f32_e32 v114, 1.0, v114
	v_rcp_f32_e32 v114, v114
	s_nop 0
	v_mul_f32_e32 v115, 0x3f1b4598, v114
	v_cndmask_b32_e32 v110, v110, v114, vcc
	v_add_f32_e32 v114, v111, v151
	v_mul_f32_e32 v114, 0xbfb8aa3b, v114
	v_exp_f32_e32 v114, v114
	v_cndmask_b32_e64 v110, v110, v115, s[40:41]
	v_add_f32_e32 v114, 1.0, v114
	v_rcp_f32_e32 v114, v114
	s_nop 0
	v_mul_f32_e32 v115, 0x3f1b4598, v114
	v_cndmask_b32_e32 v111, v111, v114, vcc
	v_cndmask_b32_e64 v111, v111, v115, s[40:41]
	v_cvt_pk_bf16_f32 v109, v110, v111
	v_add_f32_e32 v110, v104, v152
	v_mul_f32_e32 v110, 0xbfb8aa3b, v110
	v_exp_f32_e32 v110, v110
	s_nop 0
	v_add_f32_e32 v110, 1.0, v110
	v_rcp_f32_e32 v110, v110
	s_nop 0
	v_mul_f32_e32 v111, 0x3f1b4598, v110
	v_cndmask_b32_e32 v104, v104, v110, vcc
	v_add_f32_e32 v110, v105, v153
	v_mul_f32_e32 v110, 0xbfb8aa3b, v110
	v_exp_f32_e32 v110, v110
	v_cndmask_b32_e64 v104, v104, v111, s[40:41]
	v_add_f32_e32 v110, 1.0, v110
	v_rcp_f32_e32 v110, v110
	s_nop 0
	v_mul_f32_e32 v111, 0x3f1b4598, v110
	v_cndmask_b32_e32 v105, v105, v110, vcc
	v_add_f32_e32 v110, v106, v154
	v_mul_f32_e32 v110, 0xbfb8aa3b, v110
	v_exp_f32_e32 v110, v110
	v_cndmask_b32_e64 v105, v105, v111, s[40:41]
	v_add_f32_e32 v110, 1.0, v110
	v_rcp_f32_e32 v110, v110
	s_nop 0
	v_mul_f32_e32 v111, 0x3f1b4598, v110
	v_cndmask_b32_e32 v106, v106, v110, vcc
	v_add_f32_e32 v110, v107, v155
	v_mul_f32_e32 v110, 0xbfb8aa3b, v110
	v_exp_f32_e32 v110, v110
	v_cndmask_b32_e64 v106, v106, v111, s[40:41]
	v_add_f32_e32 v110, 1.0, v110
	v_rcp_f32_e32 v110, v110
	s_nop 0
	v_mul_f32_e32 v111, 0x3f1b4598, v110
	v_cndmask_b32_e32 v107, v107, v110, vcc
	v_cvt_pk_bf16_f32 v110, v104, v105
	v_lshl_add_u64 v[104:105], v[112:113], 0, v[120:121]
	v_cndmask_b32_e64 v107, v107, v111, s[40:41]
	v_cvt_pk_bf16_f32 v111, v106, v107
	flat_store_dwordx4 v[104:105], v[108:111]
	s_nop 1
	v_add_f32_e32 v106, v100, v156
	v_mul_f32_e32 v106, 0xbfb8aa3b, v106
	v_exp_f32_e32 v106, v106
	s_nop 0
	v_add_f32_e32 v106, 1.0, v106
	v_rcp_f32_e32 v106, v106
	s_nop 0
	v_mul_f32_e32 v110, 0x3f1b4598, v106
	v_cndmask_b32_e32 v100, v100, v106, vcc
	v_add_f32_e32 v106, v101, v157
	v_mul_f32_e32 v106, 0xbfb8aa3b, v106
	v_exp_f32_e32 v106, v106
	v_cndmask_b32_e64 v100, v100, v110, s[40:41]
	v_add_f32_e32 v106, 1.0, v106
	v_rcp_f32_e32 v106, v106
	s_nop 0
	v_mul_f32_e32 v107, 0x3f1b4598, v106
	v_cndmask_b32_e32 v101, v101, v106, vcc
	v_add_f32_e32 v106, v102, v158
	v_mul_f32_e32 v106, 0xbfb8aa3b, v106
	v_exp_f32_e32 v106, v106
	v_cndmask_b32_e64 v101, v101, v107, s[40:41]
	v_cvt_pk_bf16_f32 v100, v100, v101
	v_add_f32_e32 v106, 1.0, v106
	v_rcp_f32_e32 v106, v106
	s_nop 0
	v_mul_f32_e32 v107, 0x3f1b4598, v106
	v_cndmask_b32_e32 v102, v102, v106, vcc
	v_add_f32_e32 v106, v103, v159
	v_mul_f32_e32 v106, 0xbfb8aa3b, v106
	v_exp_f32_e32 v106, v106
	v_cndmask_b32_e64 v102, v102, v107, s[40:41]
	v_add_f32_e32 v106, 1.0, v106
	v_rcp_f32_e32 v106, v106
	s_nop 0
	v_mul_f32_e32 v107, 0x3f1b4598, v106
	v_cndmask_b32_e32 v103, v103, v106, vcc
	v_cndmask_b32_e64 v103, v103, v107, s[40:41]
	v_cvt_pk_bf16_f32 v101, v102, v103
	v_add_f32_e32 v102, v96, v160
	v_mul_f32_e32 v102, 0xbfb8aa3b, v102
	v_exp_f32_e32 v102, v102
	s_nop 0
	v_add_f32_e32 v102, 1.0, v102
	v_rcp_f32_e32 v102, v102
	s_nop 0
	v_mul_f32_e32 v103, 0x3f1b4598, v102
	v_cndmask_b32_e32 v96, v96, v102, vcc
	v_add_f32_e32 v102, v97, v161
	v_mul_f32_e32 v102, 0xbfb8aa3b, v102
	v_exp_f32_e32 v102, v102
	v_cndmask_b32_e64 v96, v96, v103, s[40:41]
	v_add_f32_e32 v102, 1.0, v102
	v_rcp_f32_e32 v102, v102
	s_nop 0
	v_mul_f32_e32 v103, 0x3f1b4598, v102
	v_cndmask_b32_e32 v97, v97, v102, vcc
	v_add_f32_e32 v102, v98, v162
	v_mul_f32_e32 v102, 0xbfb8aa3b, v102
	v_exp_f32_e32 v102, v102
	v_cndmask_b32_e64 v97, v97, v103, s[40:41]
	v_add_f32_e32 v102, 1.0, v102
	v_rcp_f32_e32 v102, v102
	s_nop 0
	v_mul_f32_e32 v103, 0x3f1b4598, v102
	v_cndmask_b32_e32 v98, v98, v102, vcc
	v_add_f32_e32 v102, v99, v163
	v_mul_f32_e32 v102, 0xbfb8aa3b, v102
	v_exp_f32_e32 v102, v102
	v_cndmask_b32_e64 v98, v98, v103, s[40:41]
	v_add_f32_e32 v102, 1.0, v102
	v_rcp_f32_e32 v102, v102
	s_nop 0
	v_mul_f32_e32 v103, 0x3f1b4598, v102
	v_cndmask_b32_e32 v99, v99, v102, vcc
	v_cndmask_b32_e64 v99, v99, v103, s[40:41]
	v_cvt_pk_bf16_f32 v102, v96, v97
	v_cvt_pk_bf16_f32 v103, v98, v99
	flat_store_dwordx4 v[104:105], v[100:103] offset:64
	s_nop 1
	v_add_u32_e32 v96, 32, v132
	v_ashrrev_i32_e32 v97, 31, v96
	v_lshlrev_b64 v[96:97], 11, v[96:97]
	v_lshl_add_u64 v[96:97], s[20:21], 0, v[96:97]
	v_add_f32_e32 v98, v92, v148
	v_mul_f32_e32 v98, 0xbfb8aa3b, v98
	v_exp_f32_e32 v98, v98
	s_nop 0
	v_add_f32_e32 v98, 1.0, v98
	v_rcp_f32_e32 v98, v98
	s_nop 0
	v_mul_f32_e32 v102, 0x3f1b4598, v98
	v_cndmask_b32_e32 v92, v92, v98, vcc
	v_add_f32_e32 v98, v93, v149
	v_mul_f32_e32 v98, 0xbfb8aa3b, v98
	v_exp_f32_e32 v98, v98
	v_cndmask_b32_e64 v92, v92, v102, s[40:41]
	v_add_f32_e32 v98, 1.0, v98
	v_rcp_f32_e32 v98, v98
	s_nop 0
	v_mul_f32_e32 v99, 0x3f1b4598, v98
	v_cndmask_b32_e32 v93, v93, v98, vcc
	v_add_f32_e32 v98, v94, v150
	v_mul_f32_e32 v98, 0xbfb8aa3b, v98
	v_exp_f32_e32 v98, v98
	v_cndmask_b32_e64 v93, v93, v99, s[40:41]
	v_cvt_pk_bf16_f32 v92, v92, v93
	v_add_f32_e32 v98, 1.0, v98
	v_rcp_f32_e32 v98, v98
	s_nop 0
	v_mul_f32_e32 v99, 0x3f1b4598, v98
; __device__ __forceinline__ unsigned cvt_pk_bf16(float lo, float hi) { unsigned r; asm volatile("v_cvt_pk_bf16_f32 %0, %1, %2" : "=v"(r) : "v"(lo), "v"(hi)); return r; }
; __device__ __forceinline__ float sigmoidf_(float x) { return __builtin_amdgcn_rcpf(1.0f + __builtin_amdgcn_exp2f(-1.44269504088896f * x)); }
;     __device__ __forceinline__ void operator()(AccRef acc, int pm, int pn, int wr, int wc, int fr, int fq) const {
;     ...
;             for (int m = 0; m < 4; ++m) { bf16_t* rp = dst + (size_t)EPI_ROW(ai, m) * 1024;
; #pragma unroll
;                 for (int bj = 0; bj < 2; ++bj) { const int c0 = (pn & 3) * 256 + wc * 64 + bj * 32 + 8 * fq; u32x4 w; unsigned pk[4];
; #pragma unroll
;                     for (int n = 0; n < 2; ++n) { const f32x4 v = acc[ai][bj][m][n]; const f32x4 b = *(const f32x4*)(bias + c0 + 4 * n);
;                         f32x4 r;
; #pragma unroll
;                         for (int j = 0; j < 4; ++j) { const float z = b[j] + v[j]; const float sg = sigmoidf_(z);
;                             r[j] = sec == 0 ? sg * 0.60653065971f : (sec == 1 ? sg : v[j]); }
;                         pk[2 * n] = cvt_pk_bf16(r[0], r[1]); pk[2 * n + 1] = cvt_pk_bf16(r[2], r[3]); }
;                     w.x = pk[0]; w.y = pk[1]; w.z = pk[2]; w.w = pk[3]; *(u32x4*)(rp + c0) = w; } }
	v_cndmask_b32_e32 v94, v94, v98, vcc
	v_add_f32_e32 v98, v95, v151
	v_mul_f32_e32 v98, 0xbfb8aa3b, v98
	v_exp_f32_e32 v98, v98
	v_cndmask_b32_e64 v94, v94, v99, s[40:41]
	v_add_f32_e32 v98, 1.0, v98
	v_rcp_f32_e32 v98, v98
	s_nop 0
	v_mul_f32_e32 v99, 0x3f1b4598, v98
	v_cndmask_b32_e32 v95, v95, v98, vcc
	v_cndmask_b32_e64 v95, v95, v99, s[40:41]
	v_cvt_pk_bf16_f32 v93, v94, v95
	v_add_f32_e32 v94, v88, v152
	v_mul_f32_e32 v94, 0xbfb8aa3b, v94
	v_exp_f32_e32 v94, v94
	s_nop 0
	v_add_f32_e32 v94, 1.0, v94
	v_rcp_f32_e32 v94, v94
	s_nop 0
	v_mul_f32_e32 v95, 0x3f1b4598, v94
	v_cndmask_b32_e32 v88, v88, v94, vcc
	v_add_f32_e32 v94, v89, v153
	v_mul_f32_e32 v94, 0xbfb8aa3b, v94
	v_exp_f32_e32 v94, v94
	v_cndmask_b32_e64 v88, v88, v95, s[40:41]
	v_add_f32_e32 v94, 1.0, v94
	v_rcp_f32_e32 v94, v94
	s_nop 0
	v_mul_f32_e32 v95, 0x3f1b4598, v94
	v_cndmask_b32_e32 v89, v89, v94, vcc
	v_add_f32_e32 v94, v90, v154
	v_mul_f32_e32 v94, 0xbfb8aa3b, v94
	v_exp_f32_e32 v94, v94
	v_cndmask_b32_e64 v89, v89, v95, s[40:41]
	v_add_f32_e32 v94, 1.0, v94
	v_rcp_f32_e32 v94, v94
	s_nop 0
	v_mul_f32_e32 v95, 0x3f1b4598, v94
	v_cndmask_b32_e32 v90, v90, v94, vcc
	v_add_f32_e32 v94, v91, v155
	v_mul_f32_e32 v94, 0xbfb8aa3b, v94
	v_exp_f32_e32 v94, v94
	v_cndmask_b32_e64 v90, v90, v95, s[40:41]
	v_add_f32_e32 v94, 1.0, v94
	v_rcp_f32_e32 v94, v94
	s_nop 0
	v_mul_f32_e32 v95, 0x3f1b4598, v94
	v_cndmask_b32_e32 v91, v91, v94, vcc
	v_cvt_pk_bf16_f32 v94, v88, v89
	v_lshl_add_u64 v[88:89], v[96:97], 0, v[120:121]
	v_cndmask_b32_e64 v91, v91, v95, s[40:41]
	v_cvt_pk_bf16_f32 v95, v90, v91
	flat_store_dwordx4 v[88:89], v[92:95]
	s_nop 1
	v_add_f32_e32 v90, v84, v156
	v_mul_f32_e32 v90, 0xbfb8aa3b, v90
	v_exp_f32_e32 v90, v90
	s_nop 0
	v_add_f32_e32 v90, 1.0, v90
	v_rcp_f32_e32 v90, v90
	s_nop 0
	v_mul_f32_e32 v94, 0x3f1b4598, v90
	v_cndmask_b32_e32 v84, v84, v90, vcc
	v_add_f32_e32 v90, v85, v157
	v_mul_f32_e32 v90, 0xbfb8aa3b, v90
	v_exp_f32_e32 v90, v90
	v_cndmask_b32_e64 v84, v84, v94, s[40:41]
	v_add_f32_e32 v90, 1.0, v90
	v_rcp_f32_e32 v90, v90
	s_nop 0
	v_mul_f32_e32 v91, 0x3f1b4598, v90
	v_cndmask_b32_e32 v85, v85, v90, vcc
	v_add_f32_e32 v90, v86, v158
	v_mul_f32_e32 v90, 0xbfb8aa3b, v90
	v_exp_f32_e32 v90, v90
	v_cndmask_b32_e64 v85, v85, v91, s[40:41]
	v_cvt_pk_bf16_f32 v84, v84, v85
	v_add_f32_e32 v90, 1.0, v90
	v_rcp_f32_e32 v90, v90
	s_nop 0
	v_mul_f32_e32 v91, 0x3f1b4598, v90
	v_cndmask_b32_e32 v86, v86, v90, vcc
	v_add_f32_e32 v90, v87, v159
	v_mul_f32_e32 v90, 0xbfb8aa3b, v90
	v_exp_f32_e32 v90, v90
	v_cndmask_b32_e64 v86, v86, v91, s[40:41]
	v_add_f32_e32 v90, 1.0, v90
	v_rcp_f32_e32 v90, v90
	s_nop 0
	v_mul_f32_e32 v91, 0x3f1b4598, v90
	v_cndmask_b32_e32 v87, v87, v90, vcc
	v_cndmask_b32_e64 v87, v87, v91, s[40:41]
	v_cvt_pk_bf16_f32 v85, v86, v87
	v_add_f32_e32 v86, v80, v160
	v_mul_f32_e32 v86, 0xbfb8aa3b, v86
	v_exp_f32_e32 v86, v86
	s_nop 0
	v_add_f32_e32 v86, 1.0, v86
	v_rcp_f32_e32 v86, v86
	s_nop 0
	v_mul_f32_e32 v87, 0x3f1b4598, v86
	v_cndmask_b32_e32 v80, v80, v86, vcc
	v_add_f32_e32 v86, v81, v161
	v_mul_f32_e32 v86, 0xbfb8aa3b, v86
	v_exp_f32_e32 v86, v86
	v_cndmask_b32_e64 v80, v80, v87, s[40:41]
	v_add_f32_e32 v86, 1.0, v86
	v_rcp_f32_e32 v86, v86
	s_nop 0
	v_mul_f32_e32 v87, 0x3f1b4598, v86
	v_cndmask_b32_e32 v81, v81, v86, vcc
	v_add_f32_e32 v86, v82, v162
	v_mul_f32_e32 v86, 0xbfb8aa3b, v86
	v_exp_f32_e32 v86, v86
	v_cndmask_b32_e64 v81, v81, v87, s[40:41]
	v_add_f32_e32 v86, 1.0, v86
	v_rcp_f32_e32 v86, v86
	s_nop 0
	v_mul_f32_e32 v87, 0x3f1b4598, v86
	v_cndmask_b32_e32 v82, v82, v86, vcc
	v_add_f32_e32 v86, v83, v163
	v_mul_f32_e32 v86, 0xbfb8aa3b, v86
	v_exp_f32_e32 v86, v86
	v_cndmask_b32_e64 v82, v82, v87, s[40:41]
	v_add_f32_e32 v86, 1.0, v86
	v_rcp_f32_e32 v86, v86
	s_nop 0
	v_mul_f32_e32 v87, 0x3f1b4598, v86
	v_cndmask_b32_e32 v83, v83, v86, vcc
	v_cndmask_b32_e64 v83, v83, v87, s[40:41]
	v_cvt_pk_bf16_f32 v86, v80, v81
	v_cvt_pk_bf16_f32 v87, v82, v83
	flat_store_dwordx4 v[88:89], v[84:87] offset:64
	s_nop 1
	v_add_u32_e32 v80, 48, v132
	v_ashrrev_i32_e32 v81, 31, v80
	v_lshlrev_b64 v[80:81], 11, v[80:81]
	v_lshl_add_u64 v[80:81], s[20:21], 0, v[80:81]
	v_add_f32_e32 v82, v76, v148
	v_mul_f32_e32 v82, 0xbfb8aa3b, v82
	v_exp_f32_e32 v82, v82
	s_nop 0
	v_add_f32_e32 v82, 1.0, v82
	v_rcp_f32_e32 v82, v82
	s_nop 0
	v_mul_f32_e32 v86, 0x3f1b4598, v82
	v_cndmask_b32_e32 v76, v76, v82, vcc
	v_add_f32_e32 v82, v77, v149
	v_mul_f32_e32 v82, 0xbfb8aa3b, v82
	v_exp_f32_e32 v82, v82
	v_cndmask_b32_e64 v76, v76, v86, s[40:41]
	v_add_f32_e32 v82, 1.0, v82
	v_rcp_f32_e32 v82, v82
	s_nop 0
	v_mul_f32_e32 v83, 0x3f1b4598, v82
	v_cndmask_b32_e32 v77, v77, v82, vcc
	v_add_f32_e32 v82, v78, v150
	v_mul_f32_e32 v82, 0xbfb8aa3b, v82
	v_exp_f32_e32 v82, v82
	v_cndmask_b32_e64 v77, v77, v83, s[40:41]
	v_cvt_pk_bf16_f32 v76, v76, v77
	v_add_f32_e32 v82, 1.0, v82
	v_rcp_f32_e32 v82, v82
	s_nop 0
	v_mul_f32_e32 v83, 0x3f1b4598, v82
	v_cndmask_b32_e32 v78, v78, v82, vcc
	v_add_f32_e32 v82, v79, v151
	v_mul_f32_e32 v82, 0xbfb8aa3b, v82
	v_exp_f32_e32 v82, v82
	v_cndmask_b32_e64 v78, v78, v83, s[40:41]
	v_add_f32_e32 v82, 1.0, v82
	v_rcp_f32_e32 v82, v82
	s_nop 0
	v_mul_f32_e32 v83, 0x3f1b4598, v82
	v_cndmask_b32_e32 v79, v79, v82, vcc
	v_cndmask_b32_e64 v79, v79, v83, s[40:41]
	v_cvt_pk_bf16_f32 v77, v78, v79
	v_add_f32_e32 v78, v72, v152
	v_mul_f32_e32 v78, 0xbfb8aa3b, v78
	v_exp_f32_e32 v78, v78
	s_nop 0
	v_add_f32_e32 v78, 1.0, v78
	v_rcp_f32_e32 v78, v78
	s_nop 0
	v_mul_f32_e32 v79, 0x3f1b4598, v78
	v_cndmask_b32_e32 v72, v72, v78, vcc
	v_add_f32_e32 v78, v73, v153
	v_mul_f32_e32 v78, 0xbfb8aa3b, v78
	v_exp_f32_e32 v78, v78
	v_cndmask_b32_e64 v72, v72, v79, s[40:41]
; __device__ __forceinline__ unsigned cvt_pk_bf16(float lo, float hi) { unsigned r; asm volatile("v_cvt_pk_bf16_f32 %0, %1, %2" : "=v"(r) : "v"(lo), "v"(hi)); return r; }
; __device__ __forceinline__ float sigmoidf_(float x) { return __builtin_amdgcn_rcpf(1.0f + __builtin_amdgcn_exp2f(-1.44269504088896f * x)); }
;     __device__ __forceinline__ void operator()(AccRef acc, int pm, int pn, int wr, int wc, int fr, int fq) const {
;     ...
;             for (int m = 0; m < 4; ++m) { bf16_t* rp = dst + (size_t)EPI_ROW(ai, m) * 1024;
; #pragma unroll
;                 for (int bj = 0; bj < 2; ++bj) { const int c0 = (pn & 3) * 256 + wc * 64 + bj * 32 + 8 * fq; u32x4 w; unsigned pk[4];
; #pragma unroll
;                     for (int n = 0; n < 2; ++n) { const f32x4 v = acc[ai][bj][m][n]; const f32x4 b = *(const f32x4*)(bias + c0 + 4 * n);
;                         f32x4 r;
; #pragma unroll
;                         for (int j = 0; j < 4; ++j) { const float z = b[j] + v[j]; const float sg = sigmoidf_(z);
;                             r[j] = sec == 0 ? sg * 0.60653065971f : (sec == 1 ? sg : v[j]); }
;                         pk[2 * n] = cvt_pk_bf16(r[0], r[1]); pk[2 * n + 1] = cvt_pk_bf16(r[2], r[3]); }
;                     w.x = pk[0]; w.y = pk[1]; w.z = pk[2]; w.w = pk[3]; *(u32x4*)(rp + c0) = w; } }
	v_add_f32_e32 v78, 1.0, v78
	v_rcp_f32_e32 v78, v78
	s_nop 0
	v_mul_f32_e32 v79, 0x3f1b4598, v78
	v_cndmask_b32_e32 v73, v73, v78, vcc
	v_add_f32_e32 v78, v74, v154
	v_mul_f32_e32 v78, 0xbfb8aa3b, v78
	v_exp_f32_e32 v78, v78
	v_cndmask_b32_e64 v73, v73, v79, s[40:41]
	v_add_f32_e32 v78, 1.0, v78
	v_rcp_f32_e32 v78, v78
	s_nop 0
	v_mul_f32_e32 v79, 0x3f1b4598, v78
	v_cndmask_b32_e32 v74, v74, v78, vcc
	v_add_f32_e32 v78, v75, v155
	v_mul_f32_e32 v78, 0xbfb8aa3b, v78
	v_exp_f32_e32 v78, v78
	v_cndmask_b32_e64 v74, v74, v79, s[40:41]
	v_add_f32_e32 v78, 1.0, v78
	v_rcp_f32_e32 v78, v78
	s_nop 0
	v_mul_f32_e32 v79, 0x3f1b4598, v78
	v_cndmask_b32_e32 v75, v75, v78, vcc
	v_cvt_pk_bf16_f32 v78, v72, v73
	v_lshl_add_u64 v[72:73], v[80:81], 0, v[120:121]
	v_cndmask_b32_e64 v75, v75, v79, s[40:41]
	v_cvt_pk_bf16_f32 v79, v74, v75
	flat_store_dwordx4 v[72:73], v[76:79]
	s_nop 1
	v_add_f32_e32 v74, v68, v156
	v_mul_f32_e32 v74, 0xbfb8aa3b, v74
	v_exp_f32_e32 v74, v74
	s_nop 0
	v_add_f32_e32 v74, 1.0, v74
	v_rcp_f32_e32 v74, v74
	s_nop 0
	v_mul_f32_e32 v78, 0x3f1b4598, v74
	v_cndmask_b32_e32 v68, v68, v74, vcc
	v_add_f32_e32 v74, v69, v157
	v_mul_f32_e32 v74, 0xbfb8aa3b, v74
	v_exp_f32_e32 v74, v74
	v_cndmask_b32_e64 v68, v68, v78, s[40:41]
	v_add_f32_e32 v74, 1.0, v74
	v_rcp_f32_e32 v74, v74
	s_nop 0
	v_mul_f32_e32 v75, 0x3f1b4598, v74
	v_cndmask_b32_e32 v69, v69, v74, vcc
	v_add_f32_e32 v74, v70, v158
	v_mul_f32_e32 v74, 0xbfb8aa3b, v74
	v_exp_f32_e32 v74, v74
	v_cndmask_b32_e64 v69, v69, v75, s[40:41]
	v_cvt_pk_bf16_f32 v68, v68, v69
	v_add_f32_e32 v74, 1.0, v74
	v_rcp_f32_e32 v74, v74
	s_nop 0
	v_mul_f32_e32 v75, 0x3f1b4598, v74
	v_cndmask_b32_e32 v70, v70, v74, vcc
	v_add_f32_e32 v74, v71, v159
	v_mul_f32_e32 v74, 0xbfb8aa3b, v74
	v_exp_f32_e32 v74, v74
	v_cndmask_b32_e64 v70, v70, v75, s[40:41]
	v_add_f32_e32 v74, 1.0, v74
	v_rcp_f32_e32 v74, v74
	s_nop 0
	v_mul_f32_e32 v75, 0x3f1b4598, v74
	v_cndmask_b32_e32 v71, v71, v74, vcc
	v_cndmask_b32_e64 v71, v71, v75, s[40:41]
	v_cvt_pk_bf16_f32 v69, v70, v71
	v_add_f32_e32 v70, v64, v160
	v_mul_f32_e32 v70, 0xbfb8aa3b, v70
	v_exp_f32_e32 v70, v70
	s_nop 0
	v_add_f32_e32 v70, 1.0, v70
	v_rcp_f32_e32 v70, v70
	s_nop 0
	v_mul_f32_e32 v71, 0x3f1b4598, v70
	v_cndmask_b32_e32 v64, v64, v70, vcc
	v_add_f32_e32 v70, v65, v161
	v_mul_f32_e32 v70, 0xbfb8aa3b, v70
	v_exp_f32_e32 v70, v70
	v_cndmask_b32_e64 v64, v64, v71, s[40:41]
	v_add_f32_e32 v70, 1.0, v70
	v_rcp_f32_e32 v70, v70
	s_nop 0
	v_mul_f32_e32 v71, 0x3f1b4598, v70
	v_cndmask_b32_e32 v65, v65, v70, vcc
	v_add_f32_e32 v70, v66, v162
	v_mul_f32_e32 v70, 0xbfb8aa3b, v70
	v_exp_f32_e32 v70, v70
	v_cndmask_b32_e64 v65, v65, v71, s[40:41]
	v_add_f32_e32 v70, 1.0, v70
	v_rcp_f32_e32 v70, v70
	s_nop 0
	v_mul_f32_e32 v71, 0x3f1b4598, v70
	v_cndmask_b32_e32 v66, v66, v70, vcc
	v_add_f32_e32 v70, v67, v163
	v_mul_f32_e32 v70, 0xbfb8aa3b, v70
	v_exp_f32_e32 v70, v70
	v_cndmask_b32_e64 v66, v66, v71, s[40:41]
	v_add_f32_e32 v70, 1.0, v70
	v_rcp_f32_e32 v70, v70
	s_nop 0
	v_mul_f32_e32 v71, 0x3f1b4598, v70
	v_cndmask_b32_e32 v67, v67, v70, vcc
	v_cndmask_b32_e64 v67, v67, v71, s[40:41]
	v_cvt_pk_bf16_f32 v70, v64, v65
	v_cvt_pk_bf16_f32 v71, v66, v67
	flat_store_dwordx4 v[72:73], v[68:71] offset:64
	s_nop 1
	v_add_u32_e32 v64, 0x80, v132
	v_ashrrev_i32_e32 v65, 31, v64
	v_lshlrev_b64 v[64:65], 11, v[64:65]
	v_lshl_add_u64 v[64:65], s[20:21], 0, v[64:65]
	v_add_f32_e32 v66, v60, v148
	v_mul_f32_e32 v66, 0xbfb8aa3b, v66
	v_exp_f32_e32 v66, v66
	s_nop 0
	v_add_f32_e32 v66, 1.0, v66
	v_rcp_f32_e32 v66, v66
	s_nop 0
	v_mul_f32_e32 v70, 0x3f1b4598, v66
	v_cndmask_b32_e32 v60, v60, v66, vcc
	v_add_f32_e32 v66, v61, v149
	v_mul_f32_e32 v66, 0xbfb8aa3b, v66
	v_exp_f32_e32 v66, v66
	v_cndmask_b32_e64 v60, v60, v70, s[40:41]
	v_add_f32_e32 v66, 1.0, v66
	v_rcp_f32_e32 v66, v66
	s_nop 0
	v_mul_f32_e32 v67, 0x3f1b4598, v66
	v_cndmask_b32_e32 v61, v61, v66, vcc
	v_add_f32_e32 v66, v62, v150
	v_mul_f32_e32 v66, 0xbfb8aa3b, v66
	v_exp_f32_e32 v66, v66
	v_cndmask_b32_e64 v61, v61, v67, s[40:41]
	v_cvt_pk_bf16_f32 v60, v60, v61
	v_add_f32_e32 v66, 1.0, v66
	v_rcp_f32_e32 v66, v66
	s_nop 0
	v_mul_f32_e32 v67, 0x3f1b4598, v66
	v_cndmask_b32_e32 v62, v62, v66, vcc
	v_add_f32_e32 v66, v63, v151
	v_mul_f32_e32 v66, 0xbfb8aa3b, v66
	v_exp_f32_e32 v66, v66
	v_cndmask_b32_e64 v62, v62, v67, s[40:41]
	v_add_f32_e32 v66, 1.0, v66
	v_rcp_f32_e32 v66, v66
	s_nop 0
	v_mul_f32_e32 v67, 0x3f1b4598, v66
	v_cndmask_b32_e32 v63, v63, v66, vcc
	v_cndmask_b32_e64 v63, v63, v67, s[40:41]
	v_cvt_pk_bf16_f32 v61, v62, v63
	v_add_f32_e32 v62, v56, v152
	v_mul_f32_e32 v62, 0xbfb8aa3b, v62
	v_exp_f32_e32 v62, v62
	s_nop 0
	v_add_f32_e32 v62, 1.0, v62
	v_rcp_f32_e32 v62, v62
	s_nop 0
	v_mul_f32_e32 v63, 0x3f1b4598, v62
	v_cndmask_b32_e32 v56, v56, v62, vcc
	v_add_f32_e32 v62, v57, v153
	v_mul_f32_e32 v62, 0xbfb8aa3b, v62
	v_exp_f32_e32 v62, v62
	v_cndmask_b32_e64 v56, v56, v63, s[40:41]
	v_add_f32_e32 v62, 1.0, v62
	v_rcp_f32_e32 v62, v62
	s_nop 0
	v_mul_f32_e32 v63, 0x3f1b4598, v62
	v_cndmask_b32_e32 v57, v57, v62, vcc
	v_add_f32_e32 v62, v58, v154
	v_mul_f32_e32 v62, 0xbfb8aa3b, v62
	v_exp_f32_e32 v62, v62
	v_cndmask_b32_e64 v57, v57, v63, s[40:41]
	v_add_f32_e32 v62, 1.0, v62
	v_rcp_f32_e32 v62, v62
	s_nop 0
	v_mul_f32_e32 v63, 0x3f1b4598, v62
	v_cndmask_b32_e32 v58, v58, v62, vcc
	v_add_f32_e32 v62, v59, v155
	v_mul_f32_e32 v62, 0xbfb8aa3b, v62
	v_exp_f32_e32 v62, v62
	v_cndmask_b32_e64 v58, v58, v63, s[40:41]
	v_add_f32_e32 v62, 1.0, v62
	v_rcp_f32_e32 v62, v62
	s_nop 0
	v_mul_f32_e32 v63, 0x3f1b4598, v62
	v_cndmask_b32_e32 v59, v59, v62, vcc
	v_cvt_pk_bf16_f32 v62, v56, v57
; __device__ __forceinline__ unsigned cvt_pk_bf16(float lo, float hi) { unsigned r; asm volatile("v_cvt_pk_bf16_f32 %0, %1, %2" : "=v"(r) : "v"(lo), "v"(hi)); return r; }
; __device__ __forceinline__ float sigmoidf_(float x) { return __builtin_amdgcn_rcpf(1.0f + __builtin_amdgcn_exp2f(-1.44269504088896f * x)); }
;     __device__ __forceinline__ void operator()(AccRef acc, int pm, int pn, int wr, int wc, int fr, int fq) const {
;     ...
;             for (int m = 0; m < 4; ++m) { bf16_t* rp = dst + (size_t)EPI_ROW(ai, m) * 1024;
; #pragma unroll
;                 for (int bj = 0; bj < 2; ++bj) { const int c0 = (pn & 3) * 256 + wc * 64 + bj * 32 + 8 * fq; u32x4 w; unsigned pk[4];
; #pragma unroll
;                     for (int n = 0; n < 2; ++n) { const f32x4 v = acc[ai][bj][m][n]; const f32x4 b = *(const f32x4*)(bias + c0 + 4 * n);
;                         f32x4 r;
; #pragma unroll
;                         for (int j = 0; j < 4; ++j) { const float z = b[j] + v[j]; const float sg = sigmoidf_(z);
;                             r[j] = sec == 0 ? sg * 0.60653065971f : (sec == 1 ? sg : v[j]); }
;                         pk[2 * n] = cvt_pk_bf16(r[0], r[1]); pk[2 * n + 1] = cvt_pk_bf16(r[2], r[3]); }
;                     w.x = pk[0]; w.y = pk[1]; w.z = pk[2]; w.w = pk[3]; *(u32x4*)(rp + c0) = w; } }
	v_lshl_add_u64 v[56:57], v[64:65], 0, v[120:121]
	v_cndmask_b32_e64 v59, v59, v63, s[40:41]
	v_cvt_pk_bf16_f32 v63, v58, v59
	flat_store_dwordx4 v[56:57], v[60:63]
	s_nop 1
	v_add_f32_e32 v58, v52, v156
	v_mul_f32_e32 v58, 0xbfb8aa3b, v58
	v_exp_f32_e32 v58, v58
	s_nop 0
	v_add_f32_e32 v58, 1.0, v58
	v_rcp_f32_e32 v58, v58
	s_nop 0
	v_mul_f32_e32 v62, 0x3f1b4598, v58
	v_cndmask_b32_e32 v52, v52, v58, vcc
	v_add_f32_e32 v58, v53, v157
	v_mul_f32_e32 v58, 0xbfb8aa3b, v58
	v_exp_f32_e32 v58, v58
	v_cndmask_b32_e64 v52, v52, v62, s[40:41]
	v_add_f32_e32 v58, 1.0, v58
	v_rcp_f32_e32 v58, v58
	s_nop 0
	v_mul_f32_e32 v59, 0x3f1b4598, v58
	v_cndmask_b32_e32 v53, v53, v58, vcc
	v_add_f32_e32 v58, v54, v158
	v_mul_f32_e32 v58, 0xbfb8aa3b, v58
	v_exp_f32_e32 v58, v58
	v_cndmask_b32_e64 v53, v53, v59, s[40:41]
	v_cvt_pk_bf16_f32 v52, v52, v53
	v_add_f32_e32 v58, 1.0, v58
	v_rcp_f32_e32 v58, v58
	s_nop 0
	v_mul_f32_e32 v59, 0x3f1b4598, v58
	v_cndmask_b32_e32 v54, v54, v58, vcc
	v_add_f32_e32 v58, v55, v159
	v_mul_f32_e32 v58, 0xbfb8aa3b, v58
	v_exp_f32_e32 v58, v58
	v_cndmask_b32_e64 v54, v54, v59, s[40:41]
	v_add_f32_e32 v58, 1.0, v58
	v_rcp_f32_e32 v58, v58
	s_nop 0
	v_mul_f32_e32 v59, 0x3f1b4598, v58
	v_cndmask_b32_e32 v55, v55, v58, vcc
	v_cndmask_b32_e64 v55, v55, v59, s[40:41]
	v_cvt_pk_bf16_f32 v53, v54, v55
	v_add_f32_e32 v54, v48, v160
	v_mul_f32_e32 v54, 0xbfb8aa3b, v54
	v_exp_f32_e32 v54, v54
	s_nop 0
	v_add_f32_e32 v54, 1.0, v54
	v_rcp_f32_e32 v54, v54
	s_nop 0
	v_mul_f32_e32 v55, 0x3f1b4598, v54
	v_cndmask_b32_e32 v48, v48, v54, vcc
	v_add_f32_e32 v54, v49, v161
	v_mul_f32_e32 v54, 0xbfb8aa3b, v54
	v_exp_f32_e32 v54, v54
	v_cndmask_b32_e64 v48, v48, v55, s[40:41]
	v_add_f32_e32 v54, 1.0, v54
	v_rcp_f32_e32 v54, v54
	s_nop 0
	v_mul_f32_e32 v55, 0x3f1b4598, v54
	v_cndmask_b32_e32 v49, v49, v54, vcc
	v_add_f32_e32 v54, v50, v162
	v_mul_f32_e32 v54, 0xbfb8aa3b, v54
	v_exp_f32_e32 v54, v54
	v_cndmask_b32_e64 v49, v49, v55, s[40:41]
	v_add_f32_e32 v54, 1.0, v54
	v_rcp_f32_e32 v54, v54
	s_nop 0
	v_mul_f32_e32 v55, 0x3f1b4598, v54
	v_cndmask_b32_e32 v50, v50, v54, vcc
	v_add_f32_e32 v54, v51, v163
	v_mul_f32_e32 v54, 0xbfb8aa3b, v54
	v_exp_f32_e32 v54, v54
	v_cndmask_b32_e64 v50, v50, v55, s[40:41]
	v_add_f32_e32 v54, 1.0, v54
	v_rcp_f32_e32 v54, v54
	s_nop 0
	v_mul_f32_e32 v55, 0x3f1b4598, v54
	v_cndmask_b32_e32 v51, v51, v54, vcc
	v_cndmask_b32_e64 v51, v51, v55, s[40:41]
	v_cvt_pk_bf16_f32 v54, v48, v49
	v_cvt_pk_bf16_f32 v55, v50, v51
	flat_store_dwordx4 v[56:57], v[52:55] offset:64
	s_nop 1
	v_add_u32_e32 v48, 0x90, v132
	v_ashrrev_i32_e32 v49, 31, v48
	v_lshlrev_b64 v[48:49], 11, v[48:49]
	v_lshl_add_u64 v[48:49], s[20:21], 0, v[48:49]
	v_add_f32_e32 v50, v44, v148
	v_mul_f32_e32 v50, 0xbfb8aa3b, v50
	v_exp_f32_e32 v50, v50
	s_nop 0
	v_add_f32_e32 v50, 1.0, v50
	v_rcp_f32_e32 v50, v50
	s_nop 0
	v_mul_f32_e32 v54, 0x3f1b4598, v50
	v_cndmask_b32_e32 v44, v44, v50, vcc
	v_add_f32_e32 v50, v45, v149
	v_mul_f32_e32 v50, 0xbfb8aa3b, v50
	v_exp_f32_e32 v50, v50
	v_cndmask_b32_e64 v44, v44, v54, s[40:41]
	v_add_f32_e32 v50, 1.0, v50
	v_rcp_f32_e32 v50, v50
	s_nop 0
	v_mul_f32_e32 v51, 0x3f1b4598, v50
	v_cndmask_b32_e32 v45, v45, v50, vcc
	v_add_f32_e32 v50, v46, v150
	v_mul_f32_e32 v50, 0xbfb8aa3b, v50
	v_exp_f32_e32 v50, v50
	v_cndmask_b32_e64 v45, v45, v51, s[40:41]
	v_cvt_pk_bf16_f32 v44, v44, v45
	v_add_f32_e32 v50, 1.0, v50
	v_rcp_f32_e32 v50, v50
	s_nop 0
	v_mul_f32_e32 v51, 0x3f1b4598, v50
	v_cndmask_b32_e32 v46, v46, v50, vcc
	v_add_f32_e32 v50, v47, v151
	v_mul_f32_e32 v50, 0xbfb8aa3b, v50
	v_exp_f32_e32 v50, v50
	v_cndmask_b32_e64 v46, v46, v51, s[40:41]
	v_add_f32_e32 v50, 1.0, v50
	v_rcp_f32_e32 v50, v50
	s_nop 0
	v_mul_f32_e32 v51, 0x3f1b4598, v50
	v_cndmask_b32_e32 v47, v47, v50, vcc
	v_cndmask_b32_e64 v47, v47, v51, s[40:41]
	v_cvt_pk_bf16_f32 v45, v46, v47
	v_add_f32_e32 v46, v40, v152
	v_mul_f32_e32 v46, 0xbfb8aa3b, v46
	v_exp_f32_e32 v46, v46
	s_nop 0
	v_add_f32_e32 v46, 1.0, v46
	v_rcp_f32_e32 v46, v46
	s_nop 0
	v_mul_f32_e32 v47, 0x3f1b4598, v46
	v_cndmask_b32_e32 v40, v40, v46, vcc
	v_add_f32_e32 v46, v41, v153
	v_mul_f32_e32 v46, 0xbfb8aa3b, v46
	v_exp_f32_e32 v46, v46
	v_cndmask_b32_e64 v40, v40, v47, s[40:41]
	v_add_f32_e32 v46, 1.0, v46
	v_rcp_f32_e32 v46, v46
	s_nop 0
	v_mul_f32_e32 v47, 0x3f1b4598, v46
	v_cndmask_b32_e32 v41, v41, v46, vcc
	v_add_f32_e32 v46, v42, v154
	v_mul_f32_e32 v46, 0xbfb8aa3b, v46
	v_exp_f32_e32 v46, v46
	v_cndmask_b32_e64 v41, v41, v47, s[40:41]
	v_add_f32_e32 v46, 1.0, v46
	v_rcp_f32_e32 v46, v46
	s_nop 0
	v_mul_f32_e32 v47, 0x3f1b4598, v46
	v_cndmask_b32_e32 v42, v42, v46, vcc
	v_add_f32_e32 v46, v43, v155
	v_mul_f32_e32 v46, 0xbfb8aa3b, v46
	v_exp_f32_e32 v46, v46
	v_cndmask_b32_e64 v42, v42, v47, s[40:41]
	v_add_f32_e32 v46, 1.0, v46
	v_rcp_f32_e32 v46, v46
	s_nop 0
	v_mul_f32_e32 v47, 0x3f1b4598, v46
	v_cndmask_b32_e32 v43, v43, v46, vcc
	v_cvt_pk_bf16_f32 v46, v40, v41
	v_lshl_add_u64 v[40:41], v[48:49], 0, v[120:121]
	v_cndmask_b32_e64 v43, v43, v47, s[40:41]
	v_cvt_pk_bf16_f32 v47, v42, v43
	flat_store_dwordx4 v[40:41], v[44:47]
	s_nop 1
	v_add_f32_e32 v42, v36, v156
	v_mul_f32_e32 v42, 0xbfb8aa3b, v42
	v_exp_f32_e32 v42, v42
	s_nop 0
	v_add_f32_e32 v42, 1.0, v42
	v_rcp_f32_e32 v42, v42
	s_nop 0
	v_mul_f32_e32 v46, 0x3f1b4598, v42
	v_cndmask_b32_e32 v36, v36, v42, vcc
	v_add_f32_e32 v42, v37, v157
	v_mul_f32_e32 v42, 0xbfb8aa3b, v42
	v_exp_f32_e32 v42, v42
	v_cndmask_b32_e64 v36, v36, v46, s[40:41]
	v_add_f32_e32 v42, 1.0, v42
	v_rcp_f32_e32 v42, v42
	s_nop 0
	v_mul_f32_e32 v43, 0x3f1b4598, v42
	v_cndmask_b32_e32 v37, v37, v42, vcc
	v_add_f32_e32 v42, v38, v158
	v_mul_f32_e32 v42, 0xbfb8aa3b, v42
; __device__ __forceinline__ unsigned cvt_pk_bf16(float lo, float hi) { unsigned r; asm volatile("v_cvt_pk_bf16_f32 %0, %1, %2" : "=v"(r) : "v"(lo), "v"(hi)); return r; }
; __device__ __forceinline__ float sigmoidf_(float x) { return __builtin_amdgcn_rcpf(1.0f + __builtin_amdgcn_exp2f(-1.44269504088896f * x)); }
;     __device__ __forceinline__ void operator()(AccRef acc, int pm, int pn, int wr, int wc, int fr, int fq) const {
;     ...
;             for (int m = 0; m < 4; ++m) { bf16_t* rp = dst + (size_t)EPI_ROW(ai, m) * 1024;
; #pragma unroll
;                 for (int bj = 0; bj < 2; ++bj) { const int c0 = (pn & 3) * 256 + wc * 64 + bj * 32 + 8 * fq; u32x4 w; unsigned pk[4];
; #pragma unroll
;                     for (int n = 0; n < 2; ++n) { const f32x4 v = acc[ai][bj][m][n]; const f32x4 b = *(const f32x4*)(bias + c0 + 4 * n);
;                         f32x4 r;
; #pragma unroll
;                         for (int j = 0; j < 4; ++j) { const float z = b[j] + v[j]; const float sg = sigmoidf_(z);
;                             r[j] = sec == 0 ? sg * 0.60653065971f : (sec == 1 ? sg : v[j]); }
;                         pk[2 * n] = cvt_pk_bf16(r[0], r[1]); pk[2 * n + 1] = cvt_pk_bf16(r[2], r[3]); }
;                     w.x = pk[0]; w.y = pk[1]; w.z = pk[2]; w.w = pk[3]; *(u32x4*)(rp + c0) = w; } }
	v_exp_f32_e32 v42, v42
	v_cndmask_b32_e64 v37, v37, v43, s[40:41]
	v_cvt_pk_bf16_f32 v36, v36, v37
	v_add_f32_e32 v42, 1.0, v42
	v_rcp_f32_e32 v42, v42
	s_nop 0
	v_mul_f32_e32 v43, 0x3f1b4598, v42
	v_cndmask_b32_e32 v38, v38, v42, vcc
	v_add_f32_e32 v42, v39, v159
	v_mul_f32_e32 v42, 0xbfb8aa3b, v42
	v_exp_f32_e32 v42, v42
	v_cndmask_b32_e64 v38, v38, v43, s[40:41]
	v_add_f32_e32 v42, 1.0, v42
	v_rcp_f32_e32 v42, v42
	s_nop 0
	v_mul_f32_e32 v43, 0x3f1b4598, v42
	v_cndmask_b32_e32 v39, v39, v42, vcc
	v_cndmask_b32_e64 v39, v39, v43, s[40:41]
	v_cvt_pk_bf16_f32 v37, v38, v39
	v_add_f32_e32 v38, v32, v160
	v_mul_f32_e32 v38, 0xbfb8aa3b, v38
	v_exp_f32_e32 v38, v38
	s_nop 0
	v_add_f32_e32 v38, 1.0, v38
	v_rcp_f32_e32 v38, v38
	s_nop 0
	v_mul_f32_e32 v39, 0x3f1b4598, v38
	v_cndmask_b32_e32 v32, v32, v38, vcc
	v_add_f32_e32 v38, v33, v161
	v_mul_f32_e32 v38, 0xbfb8aa3b, v38
	v_exp_f32_e32 v38, v38
	v_cndmask_b32_e64 v32, v32, v39, s[40:41]
	v_add_f32_e32 v38, 1.0, v38
	v_rcp_f32_e32 v38, v38
	s_nop 0
	v_mul_f32_e32 v39, 0x3f1b4598, v38
	v_cndmask_b32_e32 v33, v33, v38, vcc
	v_add_f32_e32 v38, v34, v162
	v_mul_f32_e32 v38, 0xbfb8aa3b, v38
	v_exp_f32_e32 v38, v38
	v_cndmask_b32_e64 v33, v33, v39, s[40:41]
	v_add_f32_e32 v38, 1.0, v38
	v_rcp_f32_e32 v38, v38
	s_nop 0
	v_mul_f32_e32 v39, 0x3f1b4598, v38
	v_cndmask_b32_e32 v34, v34, v38, vcc
	v_add_f32_e32 v38, v35, v163
	v_mul_f32_e32 v38, 0xbfb8aa3b, v38
	v_exp_f32_e32 v38, v38
	v_cndmask_b32_e64 v34, v34, v39, s[40:41]
	v_add_f32_e32 v38, 1.0, v38
	v_rcp_f32_e32 v38, v38
	s_nop 0
	v_mul_f32_e32 v39, 0x3f1b4598, v38
	v_cndmask_b32_e32 v35, v35, v38, vcc
	v_cndmask_b32_e64 v35, v35, v39, s[40:41]
	v_cvt_pk_bf16_f32 v38, v32, v33
	v_cvt_pk_bf16_f32 v39, v34, v35
	flat_store_dwordx4 v[40:41], v[36:39] offset:64
	s_nop 1
	v_add_u32_e32 v32, 0xa0, v132
	v_ashrrev_i32_e32 v33, 31, v32
	v_lshlrev_b64 v[32:33], 11, v[32:33]
	v_lshl_add_u64 v[32:33], s[20:21], 0, v[32:33]
	v_add_f32_e32 v34, v28, v148
	v_mul_f32_e32 v34, 0xbfb8aa3b, v34
	v_exp_f32_e32 v34, v34
	s_nop 0
	v_add_f32_e32 v34, 1.0, v34
	v_rcp_f32_e32 v34, v34
	s_nop 0
	v_mul_f32_e32 v38, 0x3f1b4598, v34
	v_cndmask_b32_e32 v28, v28, v34, vcc
	v_add_f32_e32 v34, v29, v149
	v_mul_f32_e32 v34, 0xbfb8aa3b, v34
	v_exp_f32_e32 v34, v34
	v_cndmask_b32_e64 v28, v28, v38, s[40:41]
	v_add_f32_e32 v34, 1.0, v34
	v_rcp_f32_e32 v34, v34
	s_nop 0
	v_mul_f32_e32 v35, 0x3f1b4598, v34
	v_cndmask_b32_e32 v29, v29, v34, vcc
	v_add_f32_e32 v34, v30, v150
	v_mul_f32_e32 v34, 0xbfb8aa3b, v34
	v_exp_f32_e32 v34, v34
	v_cndmask_b32_e64 v29, v29, v35, s[40:41]
	v_cvt_pk_bf16_f32 v28, v28, v29
	v_add_f32_e32 v34, 1.0, v34
	v_rcp_f32_e32 v34, v34
	s_nop 0
	v_mul_f32_e32 v35, 0x3f1b4598, v34
	v_cndmask_b32_e32 v30, v30, v34, vcc
	v_add_f32_e32 v34, v31, v151
	v_mul_f32_e32 v34, 0xbfb8aa3b, v34
	v_exp_f32_e32 v34, v34
	v_cndmask_b32_e64 v30, v30, v35, s[40:41]
	v_add_f32_e32 v34, 1.0, v34
	v_rcp_f32_e32 v34, v34
	s_nop 0
	v_mul_f32_e32 v35, 0x3f1b4598, v34
	v_cndmask_b32_e32 v31, v31, v34, vcc
	v_cndmask_b32_e64 v31, v31, v35, s[40:41]
	v_cvt_pk_bf16_f32 v29, v30, v31
	v_add_f32_e32 v30, v24, v152
	v_mul_f32_e32 v30, 0xbfb8aa3b, v30
	v_exp_f32_e32 v30, v30
	s_nop 0
	v_add_f32_e32 v30, 1.0, v30
	v_rcp_f32_e32 v30, v30
	s_nop 0
	v_mul_f32_e32 v31, 0x3f1b4598, v30
	v_cndmask_b32_e32 v24, v24, v30, vcc
	v_add_f32_e32 v30, v25, v153
	v_mul_f32_e32 v30, 0xbfb8aa3b, v30
	v_exp_f32_e32 v30, v30
	v_cndmask_b32_e64 v24, v24, v31, s[40:41]
	v_add_f32_e32 v30, 1.0, v30
	v_rcp_f32_e32 v30, v30
	s_nop 0
	v_mul_f32_e32 v31, 0x3f1b4598, v30
	v_cndmask_b32_e32 v25, v25, v30, vcc
	v_add_f32_e32 v30, v26, v154
	v_mul_f32_e32 v30, 0xbfb8aa3b, v30
	v_exp_f32_e32 v30, v30
	v_cndmask_b32_e64 v25, v25, v31, s[40:41]
	v_add_f32_e32 v30, 1.0, v30
	v_rcp_f32_e32 v30, v30
	s_nop 0
	v_mul_f32_e32 v31, 0x3f1b4598, v30
	v_cndmask_b32_e32 v26, v26, v30, vcc
	v_add_f32_e32 v30, v27, v155
	v_mul_f32_e32 v30, 0xbfb8aa3b, v30
	v_exp_f32_e32 v30, v30
	v_cndmask_b32_e64 v26, v26, v31, s[40:41]
	v_add_f32_e32 v30, 1.0, v30
	v_rcp_f32_e32 v30, v30
	s_nop 0
	v_mul_f32_e32 v31, 0x3f1b4598, v30
	v_cndmask_b32_e32 v27, v27, v30, vcc
	v_cvt_pk_bf16_f32 v30, v24, v25
	v_lshl_add_u64 v[24:25], v[32:33], 0, v[120:121]
	v_cndmask_b32_e64 v27, v27, v31, s[40:41]
	v_cvt_pk_bf16_f32 v31, v26, v27
	flat_store_dwordx4 v[24:25], v[28:31]
	s_nop 1
	v_add_f32_e32 v26, v20, v156
	v_mul_f32_e32 v26, 0xbfb8aa3b, v26
	v_exp_f32_e32 v26, v26
	s_nop 0
	v_add_f32_e32 v26, 1.0, v26
	v_rcp_f32_e32 v26, v26
	s_nop 0
	v_mul_f32_e32 v30, 0x3f1b4598, v26
	v_cndmask_b32_e32 v20, v20, v26, vcc
	v_add_f32_e32 v26, v21, v157
	v_mul_f32_e32 v26, 0xbfb8aa3b, v26
	v_exp_f32_e32 v26, v26
	v_cndmask_b32_e64 v20, v20, v30, s[40:41]
	v_add_f32_e32 v26, 1.0, v26
	v_rcp_f32_e32 v26, v26
	s_nop 0
	v_mul_f32_e32 v27, 0x3f1b4598, v26
	v_cndmask_b32_e32 v21, v21, v26, vcc
	v_add_f32_e32 v26, v22, v158
	v_mul_f32_e32 v26, 0xbfb8aa3b, v26
	v_exp_f32_e32 v26, v26
	v_cndmask_b32_e64 v21, v21, v27, s[40:41]
	v_cvt_pk_bf16_f32 v20, v20, v21
	v_add_f32_e32 v26, 1.0, v26
	v_rcp_f32_e32 v26, v26
	s_nop 0
	v_mul_f32_e32 v27, 0x3f1b4598, v26
	v_cndmask_b32_e32 v22, v22, v26, vcc
	v_add_f32_e32 v26, v23, v159
	v_mul_f32_e32 v26, 0xbfb8aa3b, v26
	v_exp_f32_e32 v26, v26
	v_cndmask_b32_e64 v22, v22, v27, s[40:41]
	v_add_f32_e32 v26, 1.0, v26
	v_rcp_f32_e32 v26, v26
	s_nop 0
	v_mul_f32_e32 v27, 0x3f1b4598, v26
	v_cndmask_b32_e32 v23, v23, v26, vcc
	v_cndmask_b32_e64 v23, v23, v27, s[40:41]
	v_cvt_pk_bf16_f32 v21, v22, v23
	v_add_f32_e32 v22, v16, v160
	v_mul_f32_e32 v22, 0xbfb8aa3b, v22
	v_exp_f32_e32 v22, v22
	s_nop 0
	v_add_f32_e32 v22, 1.0, v22
	v_rcp_f32_e32 v22, v22
; __device__ __forceinline__ unsigned cvt_pk_bf16(float lo, float hi) { unsigned r; asm volatile("v_cvt_pk_bf16_f32 %0, %1, %2" : "=v"(r) : "v"(lo), "v"(hi)); return r; }
; __device__ __forceinline__ float sigmoidf_(float x) { return __builtin_amdgcn_rcpf(1.0f + __builtin_amdgcn_exp2f(-1.44269504088896f * x)); }
;     __device__ __forceinline__ void operator()(AccRef acc, int pm, int pn, int wr, int wc, int fr, int fq) const {
;     ...
;             for (int m = 0; m < 4; ++m) { bf16_t* rp = dst + (size_t)EPI_ROW(ai, m) * 1024;
; #pragma unroll
;                 for (int bj = 0; bj < 2; ++bj) { const int c0 = (pn & 3) * 256 + wc * 64 + bj * 32 + 8 * fq; u32x4 w; unsigned pk[4];
; #pragma unroll
;                     for (int n = 0; n < 2; ++n) { const f32x4 v = acc[ai][bj][m][n]; const f32x4 b = *(const f32x4*)(bias + c0 + 4 * n);
;                         f32x4 r;
; #pragma unroll
;                         for (int j = 0; j < 4; ++j) { const float z = b[j] + v[j]; const float sg = sigmoidf_(z);
;                             r[j] = sec == 0 ? sg * 0.60653065971f : (sec == 1 ? sg : v[j]); }
;                         pk[2 * n] = cvt_pk_bf16(r[0], r[1]); pk[2 * n + 1] = cvt_pk_bf16(r[2], r[3]); }
;                     w.x = pk[0]; w.y = pk[1]; w.z = pk[2]; w.w = pk[3]; *(u32x4*)(rp + c0) = w; } }
	s_nop 0
	v_mul_f32_e32 v23, 0x3f1b4598, v22
	v_cndmask_b32_e32 v16, v16, v22, vcc
	v_add_f32_e32 v22, v17, v161
	v_mul_f32_e32 v22, 0xbfb8aa3b, v22
	v_exp_f32_e32 v22, v22
	v_cndmask_b32_e64 v16, v16, v23, s[40:41]
	v_add_f32_e32 v22, 1.0, v22
	v_rcp_f32_e32 v22, v22
	s_nop 0
	v_mul_f32_e32 v23, 0x3f1b4598, v22
	v_cndmask_b32_e32 v17, v17, v22, vcc
	v_add_f32_e32 v22, v18, v162
	v_mul_f32_e32 v22, 0xbfb8aa3b, v22
	v_exp_f32_e32 v22, v22
	v_cndmask_b32_e64 v17, v17, v23, s[40:41]
	v_add_f32_e32 v22, 1.0, v22
	v_rcp_f32_e32 v22, v22
	s_nop 0
	v_mul_f32_e32 v23, 0x3f1b4598, v22
	v_cndmask_b32_e32 v18, v18, v22, vcc
	v_add_f32_e32 v22, v19, v163
	v_mul_f32_e32 v22, 0xbfb8aa3b, v22
	v_exp_f32_e32 v22, v22
	v_cndmask_b32_e64 v18, v18, v23, s[40:41]
	v_add_f32_e32 v22, 1.0, v22
	v_rcp_f32_e32 v22, v22
	s_nop 0
	v_mul_f32_e32 v23, 0x3f1b4598, v22
	v_cndmask_b32_e32 v19, v19, v22, vcc
	v_cndmask_b32_e64 v19, v19, v23, s[40:41]
	v_cvt_pk_bf16_f32 v22, v16, v17
	v_cvt_pk_bf16_f32 v23, v18, v19
	flat_store_dwordx4 v[24:25], v[20:23] offset:64
	s_nop 1
	v_add_u32_e32 v16, 0xb0, v132
	v_ashrrev_i32_e32 v17, 31, v16
	v_lshlrev_b64 v[16:17], 11, v[16:17]
	v_lshl_add_u64 v[16:17], s[20:21], 0, v[16:17]
	v_add_f32_e32 v18, v12, v148
	v_mul_f32_e32 v18, 0xbfb8aa3b, v18
	v_exp_f32_e32 v18, v18
	s_nop 0
	v_add_f32_e32 v18, 1.0, v18
	v_rcp_f32_e32 v18, v18
	s_nop 0
	v_mul_f32_e32 v22, 0x3f1b4598, v18
	v_cndmask_b32_e32 v12, v12, v18, vcc
	v_add_f32_e32 v18, v13, v149
	v_mul_f32_e32 v18, 0xbfb8aa3b, v18
	v_exp_f32_e32 v18, v18
	v_cndmask_b32_e64 v12, v12, v22, s[40:41]
	v_add_f32_e32 v18, 1.0, v18
	v_rcp_f32_e32 v18, v18
	s_nop 0
	v_mul_f32_e32 v19, 0x3f1b4598, v18
	v_cndmask_b32_e32 v13, v13, v18, vcc
	v_add_f32_e32 v18, v14, v150
	v_mul_f32_e32 v18, 0xbfb8aa3b, v18
	v_exp_f32_e32 v18, v18
	v_cndmask_b32_e64 v13, v13, v19, s[40:41]
	v_cvt_pk_bf16_f32 v12, v12, v13
	v_add_f32_e32 v18, 1.0, v18
	v_rcp_f32_e32 v18, v18
	s_nop 0
	v_mul_f32_e32 v19, 0x3f1b4598, v18
	v_cndmask_b32_e32 v14, v14, v18, vcc
	v_add_f32_e32 v18, v15, v151
	v_mul_f32_e32 v18, 0xbfb8aa3b, v18
	v_exp_f32_e32 v18, v18
	v_cndmask_b32_e64 v14, v14, v19, s[40:41]
	v_add_f32_e32 v18, 1.0, v18
	v_rcp_f32_e32 v18, v18
	s_nop 0
	v_mul_f32_e32 v19, 0x3f1b4598, v18
	v_cndmask_b32_e32 v15, v15, v18, vcc
	v_cndmask_b32_e64 v15, v15, v19, s[40:41]
	v_cvt_pk_bf16_f32 v13, v14, v15
	v_add_f32_e32 v14, v8, v152
	v_mul_f32_e32 v14, 0xbfb8aa3b, v14
	v_exp_f32_e32 v14, v14
	s_nop 0
	v_add_f32_e32 v14, 1.0, v14
	v_rcp_f32_e32 v14, v14
	s_nop 0
	v_mul_f32_e32 v15, 0x3f1b4598, v14
	v_cndmask_b32_e32 v8, v8, v14, vcc
	v_add_f32_e32 v14, v9, v153
	v_mul_f32_e32 v14, 0xbfb8aa3b, v14
	v_exp_f32_e32 v14, v14
	v_cndmask_b32_e64 v8, v8, v15, s[40:41]
	v_add_f32_e32 v14, 1.0, v14
	v_rcp_f32_e32 v14, v14
	s_nop 0
	v_mul_f32_e32 v15, 0x3f1b4598, v14
	v_cndmask_b32_e32 v9, v9, v14, vcc
	v_add_f32_e32 v14, v10, v154
	v_mul_f32_e32 v14, 0xbfb8aa3b, v14
	v_exp_f32_e32 v14, v14
	v_cndmask_b32_e64 v9, v9, v15, s[40:41]
	v_add_f32_e32 v14, 1.0, v14
	v_rcp_f32_e32 v14, v14
	s_nop 0
	v_mul_f32_e32 v15, 0x3f1b4598, v14
	v_cndmask_b32_e32 v10, v10, v14, vcc
	v_add_f32_e32 v14, v11, v155
	v_mul_f32_e32 v14, 0xbfb8aa3b, v14
	v_exp_f32_e32 v14, v14
	v_cndmask_b32_e64 v10, v10, v15, s[40:41]
	v_add_f32_e32 v14, 1.0, v14
	v_rcp_f32_e32 v14, v14
	s_nop 0
	v_mul_f32_e32 v15, 0x3f1b4598, v14
	v_cndmask_b32_e32 v11, v11, v14, vcc
	v_cvt_pk_bf16_f32 v14, v8, v9
	v_lshl_add_u64 v[8:9], v[16:17], 0, v[120:121]
	v_cndmask_b32_e64 v11, v11, v15, s[40:41]
	v_cvt_pk_bf16_f32 v15, v10, v11
	flat_store_dwordx4 v[8:9], v[12:15]
	s_nop 1
	v_add_f32_e32 v10, v4, v156
	v_mul_f32_e32 v10, 0xbfb8aa3b, v10
	v_exp_f32_e32 v10, v10
	s_nop 0
	v_add_f32_e32 v10, 1.0, v10
	v_rcp_f32_e32 v10, v10
	s_nop 0
	v_mul_f32_e32 v14, 0x3f1b4598, v10
	v_cndmask_b32_e32 v4, v4, v10, vcc
	v_add_f32_e32 v10, v5, v157
	v_mul_f32_e32 v10, 0xbfb8aa3b, v10
	v_exp_f32_e32 v10, v10
	v_cndmask_b32_e64 v4, v4, v14, s[40:41]
	v_add_f32_e32 v10, 1.0, v10
	v_rcp_f32_e32 v10, v10
	s_nop 0
	v_mul_f32_e32 v11, 0x3f1b4598, v10
	v_cndmask_b32_e32 v5, v5, v10, vcc
	v_add_f32_e32 v10, v6, v158
	v_mul_f32_e32 v10, 0xbfb8aa3b, v10
	v_exp_f32_e32 v10, v10
	v_cndmask_b32_e64 v5, v5, v11, s[40:41]
	v_cvt_pk_bf16_f32 v4, v4, v5
	v_add_f32_e32 v10, 1.0, v10
	v_rcp_f32_e32 v10, v10
	s_nop 0
	v_mul_f32_e32 v11, 0x3f1b4598, v10
	v_cndmask_b32_e32 v6, v6, v10, vcc
	v_add_f32_e32 v10, v7, v159
	v_mul_f32_e32 v10, 0xbfb8aa3b, v10
	v_exp_f32_e32 v10, v10
	v_cndmask_b32_e64 v6, v6, v11, s[40:41]
	v_add_f32_e32 v10, 1.0, v10
	v_rcp_f32_e32 v10, v10
	s_nop 0
	v_mul_f32_e32 v11, 0x3f1b4598, v10
	v_cndmask_b32_e32 v7, v7, v10, vcc
	v_cndmask_b32_e64 v7, v7, v11, s[40:41]
	v_cvt_pk_bf16_f32 v5, v6, v7
	v_add_f32_e32 v6, v0, v160
	v_mul_f32_e32 v6, 0xbfb8aa3b, v6
	v_exp_f32_e32 v6, v6
	s_nop 0
	v_add_f32_e32 v6, 1.0, v6
	v_rcp_f32_e32 v6, v6
	s_nop 0
	v_mul_f32_e32 v7, 0x3f1b4598, v6
	v_cndmask_b32_e32 v0, v0, v6, vcc
	v_add_f32_e32 v6, v1, v161
	v_mul_f32_e32 v6, 0xbfb8aa3b, v6
	v_exp_f32_e32 v6, v6
	v_cndmask_b32_e64 v0, v0, v7, s[40:41]
	v_add_f32_e32 v6, 1.0, v6
	v_rcp_f32_e32 v6, v6
	s_nop 0
	v_mul_f32_e32 v7, 0x3f1b4598, v6
	v_cndmask_b32_e32 v1, v1, v6, vcc
	v_add_f32_e32 v6, v2, v162
	v_mul_f32_e32 v6, 0xbfb8aa3b, v6
	v_exp_f32_e32 v6, v6
	v_cndmask_b32_e64 v1, v1, v7, s[40:41]
	v_add_f32_e32 v6, 1.0, v6
	v_rcp_f32_e32 v6, v6
	s_nop 0
	v_mul_f32_e32 v7, 0x3f1b4598, v6
	v_cndmask_b32_e32 v2, v2, v6, vcc
	v_add_f32_e32 v6, v3, v163
	v_mul_f32_e32 v6, 0xbfb8aa3b, v6
	v_exp_f32_e32 v6, v6
	v_cndmask_b32_e64 v2, v2, v7, s[40:41]
	v_add_f32_e32 v6, 1.0, v6
	v_rcp_f32_e32 v6, v6
	s_nop 0
	v_mul_f32_e32 v7, 0x3f1b4598, v6
	v_cndmask_b32_e32 v3, v3, v6, vcc
	s_andn2_b64 vcc, exec, s[50:51]
	v_cndmask_b32_e64 v3, v3, v7, s[40:41]
	v_cvt_pk_bf16_f32 v6, v0, v1
	v_cvt_pk_bf16_f32 v7, v2, v3
	flat_store_dwordx4 v[8:9], v[4:7] offset:64
	s_nop 1
	s_cbranch_vccz .LBB0_309

; #define G_STAGE(bufoff, gbase, voff) do { _Pragma("unroll") for (int _i = 0; _i < 2; ++_i) \
;     __builtin_amdgcn_global_load_lds((const unsigned*)((const char*)(gbase) + (voff)[_i]), (LAS unsigned*)(lds + (bufoff) + ldsw + _i * 8192), 16, 0, 0); } while (0)
; #define G_LDA(dst, b, h) do { _Pragma("unroll") for (int m = 0; m < 4; ++m) _Pragma("unroll") for (int k = 0; k < 2; ++k) dst[m][k] = *(const LAS bf16x8*)(lds + G_SA(b, h) + aoff + m * 2048 + k * 1024); } while (0)
; #define G_LDB(dst, b, h) do { _Pragma("unroll") for (int n = 0; n < 2; ++n) _Pragma("unroll") for (int k = 0; k < 2; ++k) dst[n][k] = *(const LAS bf16x8*)(lds + G_SB(b, h) + boff + n * 2048 + k * 1024); } while (0)
; #define G_MMA(ai, bj, At, Bt) do { __builtin_amdgcn_s_setprio(1); _Pragma("unroll") for (int m = 0; m < 4; ++m) _Pragma("unroll") for (int n = 0; n < 2; ++n) _Pragma("unroll") for (int k = 0; k < 2; ++k) \
;     acc[ai][bj][m][n] = __builtin_amdgcn_mfma_f32_16x16x32_bf16(Bt[n][k], At[m][k], acc[ai][bj][m][n], 0, 0, 0); __builtin_amdgcn_s_setprio(0); } while (0)
; #define WAIT_V(n) asm volatile("s_waitcnt vmcnt(" #n ")" ::: "memory")
; #define WAIT_L(n) asm volatile("s_waitcnt lgkmcnt(" #n ")" ::: "memory")
; #define BAR __builtin_amdgcn_s_barrier()
; #define SCHED __builtin_amdgcn_sched_barrier(0)
; template <class Epi>
; __device__ __forceinline__ void gemm_phase(const bf16_t* __restrict__ A, int lda, const bf16_t* __restrict__ Bt, int ldb, int K, int nM, int nN, const Epi& epi, LAS unsigned char* lds, int wv) {
;     ...
;             const char* a1 = cA + (size_t)(t + 1) * kstep;
;             const char* a2 = last ? nA : cA + (size_t)(t + 2) * kstep; const char* b2 = last ? nB : cB + (size_t)(t + 2) * kstep;
;             const char* a3 = a2 + kstep; const char* b3 = b2 + kstep;
;             G_LDB(B0, 0, 0); G_LDB(B1, 0, 1); SCHED; G_LDA(At, 0, 0); G_STAGE(G_SA(1, 1), a1 + hstep, voffA);
;             WAIT_V(8); WAIT_L(0); BAR; G_MMA(0, 0, At, B0); G_MMA(0, 1, At, B1); BAR; SCHED;
;             G_LDA(At, 0, 1); G_STAGE(G_SB(0, 0), b2, voffA); G_STAGE(G_SB(0, 1), b2 + hstep, voffA); G_STAGE(G_SA(0, 0), a2, voffA);
;             WAIT_V(8); WAIT_L(0); BAR; G_MMA(1, 0, At, B0); G_MMA(1, 1, At, B1); BAR; SCHED;
.LBB0_319:
	s_add_u32 s46, s20, s30
	s_addc_u32 s47, s21, 0
	s_add_u32 s31, s46, 0x100
	s_addc_u32 s55, s47, 0
	s_and_b64 s[44:45], s[58:59], exec
	s_cselect_b32 s63, s49, s55
	s_cselect_b32 s62, s48, s31
	s_add_u32 s30, s38, s30
	s_addc_u32 s31, s39, 0
	s_add_u32 s44, s30, 0x100
	s_addc_u32 s45, s31, 0
	s_add_i32 s66, 0, 0x10000
	s_and_b64 s[30:31], s[58:59], exec
	s_cselect_b32 s73, s35, s45
	s_cselect_b32 s72, s34, s44
	s_add_i32 s45, 0, 0x14000
	s_add_u32 s94, s46, 0x20080
	s_addc_u32 s95, s47, 0
	s_add_i32 s47, s66, s33
	s_add_i32 m0, s52, 0xc000
	s_add_i32 s37, s52, 0xe000
	s_add_i32 s44, s47, 0x2000
	s_add_u32 s82, s72, 0x20000
	v_add_u32_e32 v146, s66, v140
	v_add_u32_e32 v162, s45, v140
	s_addc_u32 s83, s73, 0
	s_add_i32 vcc_hi, s45, s33
	ds_read_b128 v[130:133], v146
	ds_read_b128 v[134:137], v146 offset:1024
	ds_read_b128 v[142:145], v146 offset:2048
	ds_read_b128 v[146:149], v146 offset:3072
	ds_read_b128 v[150:153], v162
	ds_read_b128 v[154:157], v162 offset:1024
	ds_read_b128 v[158:161], v162 offset:2048
	ds_read_b128 v[162:165], v162 offset:3072
	s_add_i32 vcc_lo, vcc_hi, 0x2000
	s_add_i32 s57, 0, 0x18000
	s_add_i32 s55, 0, 0x1c000
	s_add_u32 s60, s62, 0x20000
	s_addc_u32 s61, s63, 0
	s_add_i32 s31, s57, s33
	s_add_i32 s30, s31, 0x2000
	s_add_u32 s58, s72, 0x20080
	s_addc_u32 s59, s73, 0
	s_add_i32 s45, s55, s33
	s_add_i32 s46, s45, 0x2000
	v_lshl_add_u64 v[190:191], s[94:95], 0, v[192:193]
	ds_read_b128 v[166:169], v141
	ds_read_b128 v[170:173], v141 offset:1024
	ds_read_b128 v[174:177], v141 offset:2048
	ds_read_b128 v[178:181], v141 offset:3072
	ds_read_b128 v[182:185], v141 offset:4096
	ds_read_b128 v[186:189], v141 offset:5120
	ds_read_b128 v[194:197], v141 offset:6144
	ds_read_b128 v[198:201], v141 offset:7168
	global_load_lds_dwordx4 v[190:191], off
	v_lshl_add_u64 v[190:191], s[94:95], 0, v[128:129]
	s_mov_b32 m0, s37
	s_nop 0
	global_load_lds_dwordx4 v[190:191], off
	s_waitcnt vmcnt(8)
	s_waitcnt lgkmcnt(0)
	s_barrier
	s_setprio 1
	s_waitcnt lgkmcnt(0)
	v_mfma_f32_16x16x32_bf16 v[124:127], v[130:133], v[166:169], v[124:127]
	v_mfma_f32_16x16x32_bf16 v[120:123], v[142:145], v[166:169], v[120:123]
	v_mfma_f32_16x16x32_bf16 v[108:111], v[130:133], v[174:177], v[108:111]
	v_mfma_f32_16x16x32_bf16 v[104:107], v[142:145], v[174:177], v[104:107]
	v_mfma_f32_16x16x32_bf16 v[92:95], v[130:133], v[182:185], v[92:95]
	v_mfma_f32_16x16x32_bf16 v[88:91], v[142:145], v[182:185], v[88:91]
	v_mfma_f32_16x16x32_bf16 v[76:79], v[130:133], v[194:197], v[76:79]
	v_mfma_f32_16x16x32_bf16 v[72:75], v[142:145], v[194:197], v[72:75]
	v_mfma_f32_16x16x32_bf16 v[124:127], v[134:137], v[170:173], v[124:127]
	v_mfma_f32_16x16x32_bf16 v[120:123], v[146:149], v[170:173], v[120:123]
	v_mfma_f32_16x16x32_bf16 v[108:111], v[134:137], v[178:181], v[108:111]
	v_mfma_f32_16x16x32_bf16 v[104:107], v[146:149], v[178:181], v[104:107]
	v_mfma_f32_16x16x32_bf16 v[92:95], v[134:137], v[186:189], v[92:95]
	v_mfma_f32_16x16x32_bf16 v[88:91], v[146:149], v[186:189], v[88:91]
	v_mfma_f32_16x16x32_bf16 v[76:79], v[134:137], v[198:201], v[76:79]
	v_mfma_f32_16x16x32_bf16 v[72:75], v[146:149], v[198:201], v[72:75]
	s_setprio 0
	s_setprio 1
	v_mfma_f32_16x16x32_bf16 v[116:119], v[150:153], v[166:169], v[116:119]
	v_mfma_f32_16x16x32_bf16 v[112:115], v[158:161], v[166:169], v[112:115]
	v_mfma_f32_16x16x32_bf16 v[100:103], v[150:153], v[174:177], v[100:103]
	v_mfma_f32_16x16x32_bf16 v[96:99], v[158:161], v[174:177], v[96:99]
	v_mfma_f32_16x16x32_bf16 v[84:87], v[150:153], v[182:185], v[84:87]
	v_mfma_f32_16x16x32_bf16 v[80:83], v[158:161], v[182:185], v[80:83]
	v_mfma_f32_16x16x32_bf16 v[68:71], v[150:153], v[194:197], v[68:71]
	v_mfma_f32_16x16x32_bf16 v[64:67], v[158:161], v[194:197], v[64:67]
	v_mfma_f32_16x16x32_bf16 v[116:119], v[154:157], v[170:173], v[116:119]
	v_mfma_f32_16x16x32_bf16 v[112:115], v[162:165], v[170:173], v[112:115]
	v_mfma_f32_16x16x32_bf16 v[100:103], v[154:157], v[178:181], v[100:103]
	v_mfma_f32_16x16x32_bf16 v[96:99], v[162:165], v[178:181], v[96:99]
	v_mfma_f32_16x16x32_bf16 v[84:87], v[154:157], v[186:189], v[84:87]
	v_mfma_f32_16x16x32_bf16 v[80:83], v[162:165], v[186:189], v[80:83]
	v_mfma_f32_16x16x32_bf16 v[68:71], v[154:157], v[198:201], v[68:71]
	v_mfma_f32_16x16x32_bf16 v[64:67], v[162:165], v[198:201], v[64:67]
	s_setprio 0
	s_barrier
	s_mov_b32 m0, s47
	v_lshl_add_u64 v[190:191], s[72:73], 0, v[192:193]
	ds_read_b128 v[166:169], v141 offset:16384
	ds_read_b128 v[170:173], v141 offset:17408
	ds_read_b128 v[174:177], v141 offset:18432
	ds_read_b128 v[178:181], v141 offset:19456
	ds_read_b128 v[182:185], v141 offset:20480
	ds_read_b128 v[186:189], v141 offset:21504
	ds_read_b128 v[194:197], v141 offset:22528
	ds_read_b128 v[198:201], v141 offset:23552
	global_load_lds_dwordx4 v[190:191], off
	v_lshl_add_u64 v[202:203], s[72:73], 0, v[128:129]
	s_mov_b32 m0, s44
	v_lshl_add_u64 v[204:205], s[82:83], 0, v[192:193]
	global_load_lds_dwordx4 v[202:203], off
	s_mov_b32 m0, vcc_hi
	v_lshl_add_u64 v[206:207], s[62:63], 0, v[128:129]
	global_load_lds_dwordx4 v[204:205], off
	v_lshl_add_u64 v[204:205], s[82:83], 0, v[128:129]
	s_mov_b32 m0, vcc_lo
	s_nop 0
	global_load_lds_dwordx4 v[204:205], off
	v_lshl_add_u64 v[204:205], s[62:63], 0, v[192:193]
	s_mov_b32 m0, s52
	s_nop 0
	global_load_lds_dwordx4 v[204:205], off
	s_mov_b32 m0, s42
	s_nop 0
	global_load_lds_dwordx4 v[206:207], off
	s_waitcnt vmcnt(8)
	s_waitcnt lgkmcnt(0)
	s_barrier
; #define G_STAGE(bufoff, gbase, voff) do { _Pragma("unroll") for (int _i = 0; _i < 2; ++_i) \
;     __builtin_amdgcn_global_load_lds((const unsigned*)((const char*)(gbase) + (voff)[_i]), (LAS unsigned*)(lds + (bufoff) + ldsw + _i * 8192), 16, 0, 0); } while (0)
; #define G_LDA(dst, b, h) do { _Pragma("unroll") for (int m = 0; m < 4; ++m) _Pragma("unroll") for (int k = 0; k < 2; ++k) dst[m][k] = *(const LAS bf16x8*)(lds + G_SA(b, h) + aoff + m * 2048 + k * 1024); } while (0)
; #define G_LDB(dst, b, h) do { _Pragma("unroll") for (int n = 0; n < 2; ++n) _Pragma("unroll") for (int k = 0; k < 2; ++k) dst[n][k] = *(const LAS bf16x8*)(lds + G_SB(b, h) + boff + n * 2048 + k * 1024); } while (0)
; #define G_MMA(ai, bj, At, Bt) do { __builtin_amdgcn_s_setprio(1); _Pragma("unroll") for (int m = 0; m < 4; ++m) _Pragma("unroll") for (int n = 0; n < 2; ++n) _Pragma("unroll") for (int k = 0; k < 2; ++k) \
;     acc[ai][bj][m][n] = __builtin_amdgcn_mfma_f32_16x16x32_bf16(Bt[n][k], At[m][k], acc[ai][bj][m][n], 0, 0, 0); __builtin_amdgcn_s_setprio(0); } while (0)
; #define WAIT_V(n) asm volatile("s_waitcnt vmcnt(" #n ")" ::: "memory")
; #define WAIT_L(n) asm volatile("s_waitcnt lgkmcnt(" #n ")" ::: "memory")
; #define BAR __builtin_amdgcn_s_barrier()
; #define SCHED __builtin_amdgcn_sched_barrier(0)
; template <class Epi>
; __device__ __forceinline__ void gemm_phase(const bf16_t* __restrict__ A, int lda, const bf16_t* __restrict__ Bt, int ldb, int K, int nM, int nN, const Epi& epi, LAS unsigned char* lds, int wv) {
;     ...
;             WAIT_V(8); WAIT_L(0); BAR; G_MMA(1, 0, At, B0); G_MMA(1, 1, At, B1); BAR; SCHED;
;             G_LDB(B0, 1, 0); G_LDB(B1, 1, 1); SCHED; G_LDA(At, 1, 0); G_STAGE(G_SA(0, 1), a2 + hstep, voffA);
;             WAIT_V(8); WAIT_L(0); BAR; G_MMA(0, 0, At, B0); G_MMA(0, 1, At, B1); BAR; SCHED;
;             G_LDA(At, 1, 1); G_STAGE(G_SB(1, 0), b3, voffA); G_STAGE(G_SB(1, 1), b3 + hstep, voffA); G_STAGE(G_SA(1, 0), a3, voffA);
	s_setprio 1
	s_waitcnt lgkmcnt(0)
	v_mfma_f32_16x16x32_bf16 v[60:63], v[130:133], v[166:169], v[60:63]
	v_mfma_f32_16x16x32_bf16 v[56:59], v[142:145], v[166:169], v[56:59]
	v_mfma_f32_16x16x32_bf16 v[44:47], v[130:133], v[174:177], v[44:47]
	v_mfma_f32_16x16x32_bf16 v[40:43], v[142:145], v[174:177], v[40:43]
	v_mfma_f32_16x16x32_bf16 v[28:31], v[130:133], v[182:185], v[28:31]
	v_mfma_f32_16x16x32_bf16 v[24:27], v[142:145], v[182:185], v[24:27]
	v_mfma_f32_16x16x32_bf16 v[12:15], v[130:133], v[194:197], v[12:15]
	v_mfma_f32_16x16x32_bf16 v[8:11], v[142:145], v[194:197], v[8:11]
	v_mfma_f32_16x16x32_bf16 v[60:63], v[134:137], v[170:173], v[60:63]
	v_mfma_f32_16x16x32_bf16 v[56:59], v[146:149], v[170:173], v[56:59]
	v_mfma_f32_16x16x32_bf16 v[44:47], v[134:137], v[178:181], v[44:47]
	v_mfma_f32_16x16x32_bf16 v[40:43], v[146:149], v[178:181], v[40:43]
	v_mfma_f32_16x16x32_bf16 v[28:31], v[134:137], v[186:189], v[28:31]
	v_mfma_f32_16x16x32_bf16 v[24:27], v[146:149], v[186:189], v[24:27]
	v_mfma_f32_16x16x32_bf16 v[12:15], v[134:137], v[198:201], v[12:15]
	v_mfma_f32_16x16x32_bf16 v[8:11], v[146:149], v[198:201], v[8:11]
	s_setprio 0
	s_setprio 1
	v_mfma_f32_16x16x32_bf16 v[52:55], v[150:153], v[166:169], v[52:55]
	v_mfma_f32_16x16x32_bf16 v[48:51], v[158:161], v[166:169], v[48:51]
	v_mfma_f32_16x16x32_bf16 v[36:39], v[150:153], v[174:177], v[36:39]
	v_mfma_f32_16x16x32_bf16 v[32:35], v[158:161], v[174:177], v[32:35]
	v_mfma_f32_16x16x32_bf16 v[20:23], v[150:153], v[182:185], v[20:23]
	v_mfma_f32_16x16x32_bf16 v[16:19], v[158:161], v[182:185], v[16:19]
	v_mfma_f32_16x16x32_bf16 v[4:7], v[150:153], v[194:197], v[4:7]
	v_mfma_f32_16x16x32_bf16 v[0:3], v[158:161], v[194:197], v[0:3]
	v_mfma_f32_16x16x32_bf16 v[52:55], v[154:157], v[170:173], v[52:55]
	v_mfma_f32_16x16x32_bf16 v[48:51], v[162:165], v[170:173], v[48:51]
	v_mfma_f32_16x16x32_bf16 v[36:39], v[154:157], v[178:181], v[36:39]
	v_mfma_f32_16x16x32_bf16 v[32:35], v[162:165], v[178:181], v[32:35]
	v_mfma_f32_16x16x32_bf16 v[20:23], v[154:157], v[186:189], v[20:23]
	v_mfma_f32_16x16x32_bf16 v[16:19], v[162:165], v[186:189], v[16:19]
	v_mfma_f32_16x16x32_bf16 v[4:7], v[154:157], v[198:201], v[4:7]
	v_mfma_f32_16x16x32_bf16 v[0:3], v[162:165], v[198:201], v[0:3]
	s_setprio 0
	s_barrier
	v_add_u32_e32 v146, s57, v140
	v_add_u32_e32 v162, s55, v140
	ds_read_b128 v[130:133], v146
	ds_read_b128 v[134:137], v146 offset:1024
	ds_read_b128 v[142:145], v146 offset:2048
	ds_read_b128 v[146:149], v146 offset:3072
	ds_read_b128 v[150:153], v162
	ds_read_b128 v[154:157], v162 offset:1024
	ds_read_b128 v[158:161], v162 offset:2048
	ds_read_b128 v[162:165], v162 offset:3072
	s_mov_b32 m0, s43
	v_lshl_add_u64 v[208:209], s[60:61], 0, v[192:193]
	ds_read_b128 v[166:169], v141 offset:32768
	ds_read_b128 v[170:173], v141 offset:33792
	ds_read_b128 v[174:177], v141 offset:34816
	ds_read_b128 v[178:181], v141 offset:35840
	ds_read_b128 v[182:185], v141 offset:36864
	ds_read_b128 v[186:189], v141 offset:37888
	ds_read_b128 v[194:197], v141 offset:38912
	ds_read_b128 v[198:201], v141 offset:39936
	global_load_lds_dwordx4 v[208:209], off
	v_lshl_add_u64 v[208:209], s[60:61], 0, v[128:129]
	s_mov_b32 m0, s7
	s_nop 0
	global_load_lds_dwordx4 v[208:209], off
	s_waitcnt vmcnt(8)
	s_waitcnt lgkmcnt(0)
	s_barrier
	s_setprio 1
	s_waitcnt lgkmcnt(0)
	v_mfma_f32_16x16x32_bf16 v[124:127], v[130:133], v[166:169], v[124:127]
	v_mfma_f32_16x16x32_bf16 v[120:123], v[142:145], v[166:169], v[120:123]
	v_mfma_f32_16x16x32_bf16 v[108:111], v[130:133], v[174:177], v[108:111]
	v_mfma_f32_16x16x32_bf16 v[104:107], v[142:145], v[174:177], v[104:107]
	v_mfma_f32_16x16x32_bf16 v[92:95], v[130:133], v[182:185], v[92:95]
	v_mfma_f32_16x16x32_bf16 v[88:91], v[142:145], v[182:185], v[88:91]
	v_mfma_f32_16x16x32_bf16 v[76:79], v[130:133], v[194:197], v[76:79]
	v_mfma_f32_16x16x32_bf16 v[72:75], v[142:145], v[194:197], v[72:75]
	v_mfma_f32_16x16x32_bf16 v[124:127], v[134:137], v[170:173], v[124:127]
	v_mfma_f32_16x16x32_bf16 v[120:123], v[146:149], v[170:173], v[120:123]
	v_mfma_f32_16x16x32_bf16 v[108:111], v[134:137], v[178:181], v[108:111]
	v_mfma_f32_16x16x32_bf16 v[104:107], v[146:149], v[178:181], v[104:107]
	v_mfma_f32_16x16x32_bf16 v[92:95], v[134:137], v[186:189], v[92:95]
	v_mfma_f32_16x16x32_bf16 v[88:91], v[146:149], v[186:189], v[88:91]
	v_mfma_f32_16x16x32_bf16 v[76:79], v[134:137], v[198:201], v[76:79]
	v_mfma_f32_16x16x32_bf16 v[72:75], v[146:149], v[198:201], v[72:75]
	s_setprio 0
	s_setprio 1
	v_mfma_f32_16x16x32_bf16 v[116:119], v[150:153], v[166:169], v[116:119]
	v_mfma_f32_16x16x32_bf16 v[112:115], v[158:161], v[166:169], v[112:115]
	v_mfma_f32_16x16x32_bf16 v[100:103], v[150:153], v[174:177], v[100:103]
	v_mfma_f32_16x16x32_bf16 v[96:99], v[158:161], v[174:177], v[96:99]
	v_mfma_f32_16x16x32_bf16 v[84:87], v[150:153], v[182:185], v[84:87]
	v_mfma_f32_16x16x32_bf16 v[80:83], v[158:161], v[182:185], v[80:83]
	v_mfma_f32_16x16x32_bf16 v[68:71], v[150:153], v[194:197], v[68:71]
	v_mfma_f32_16x16x32_bf16 v[64:67], v[158:161], v[194:197], v[64:67]
	v_mfma_f32_16x16x32_bf16 v[116:119], v[154:157], v[170:173], v[116:119]
	v_mfma_f32_16x16x32_bf16 v[112:115], v[162:165], v[170:173], v[112:115]
	v_mfma_f32_16x16x32_bf16 v[100:103], v[154:157], v[178:181], v[100:103]
	v_mfma_f32_16x16x32_bf16 v[96:99], v[162:165], v[178:181], v[96:99]
	v_mfma_f32_16x16x32_bf16 v[84:87], v[154:157], v[186:189], v[84:87]
	v_mfma_f32_16x16x32_bf16 v[80:83], v[162:165], v[186:189], v[80:83]
	v_mfma_f32_16x16x32_bf16 v[68:71], v[154:157], v[198:201], v[68:71]
	v_mfma_f32_16x16x32_bf16 v[64:67], v[162:165], v[198:201], v[64:67]
	s_setprio 0
	s_barrier
; #define G_STAGE(bufoff, gbase, voff) do { _Pragma("unroll") for (int _i = 0; _i < 2; ++_i) \
;     __builtin_amdgcn_global_load_lds((const unsigned*)((const char*)(gbase) + (voff)[_i]), (LAS unsigned*)(lds + (bufoff) + ldsw + _i * 8192), 16, 0, 0); } while (0)
; #define G_LDA(dst, b, h) do { _Pragma("unroll") for (int m = 0; m < 4; ++m) _Pragma("unroll") for (int k = 0; k < 2; ++k) dst[m][k] = *(const LAS bf16x8*)(lds + G_SA(b, h) + aoff + m * 2048 + k * 1024); } while (0)
; #define G_MMA(ai, bj, At, Bt) do { __builtin_amdgcn_s_setprio(1); _Pragma("unroll") for (int m = 0; m < 4; ++m) _Pragma("unroll") for (int n = 0; n < 2; ++n) _Pragma("unroll") for (int k = 0; k < 2; ++k) \
;     acc[ai][bj][m][n] = __builtin_amdgcn_mfma_f32_16x16x32_bf16(Bt[n][k], At[m][k], acc[ai][bj][m][n], 0, 0, 0); __builtin_amdgcn_s_setprio(0); } while (0)
; #define WAIT_V(n) asm volatile("s_waitcnt vmcnt(" #n ")" ::: "memory")
; #define WAIT_L(n) asm volatile("s_waitcnt lgkmcnt(" #n ")" ::: "memory")
; #define BAR __builtin_amdgcn_s_barrier()
; #define SCHED __builtin_amdgcn_sched_barrier(0)
; template <class Epi>
; __device__ __forceinline__ void gemm_phase(const bf16_t* __restrict__ A, int lda, const bf16_t* __restrict__ Bt, int ldb, int K, int nM, int nN, const Epi& epi, LAS unsigned char* lds, int wv) {
;     ...
;             G_LDA(At, 1, 1); G_STAGE(G_SB(1, 0), b3, voffA); G_STAGE(G_SB(1, 1), b3 + hstep, voffA); G_STAGE(G_SA(1, 0), a3, voffA);
;             WAIT_V(8); WAIT_L(0); BAR; G_MMA(1, 0, At, B0); G_MMA(1, 1, At, B1); BAR; SCHED;
;     __device__ __forceinline__ void operator()(AccRef acc, int pm, int pn, int wr, int wc, int fr, int fq) const {
;         pn += pn_off; const int sec = pn >> 2; const long doff = sec == 0 ? 0 : (sec == 1 ? offAA : offG); bf16_t* dst = E + doff; const float* bias = w0 + (sec == 0 ? 0 : offa0);
; #pragma unroll
;         for (int ai = 0; ai < 2; ++ai)
; #pragma unroll
;             for (int m = 0; m < 4; ++m) { bf16_t* rp = dst + (size_t)EPI_ROW(ai, m) * 1024;
; #pragma unroll
;                 for (int bj = 0; bj < 2; ++bj) { const int c0 = (pn & 3) * 256 + wc * 64 + bj * 32 + 8 * fq; u32x4 w; unsigned pk[4];
; #pragma unroll
;                     for (int n = 0; n < 2; ++n) { const f32x4 v = acc[ai][bj][m][n]; const f32x4 b = *(const f32x4*)(bias + c0 + 4 * n);
	s_mov_b32 m0, s31
	v_lshl_add_u64 v[190:191], v[190:191], 0, s[10:11]
	ds_read_b128 v[166:169], v141 offset:49152
	ds_read_b128 v[170:173], v141 offset:50176
	ds_read_b128 v[174:177], v141 offset:51200
	ds_read_b128 v[178:181], v141 offset:52224
	ds_read_b128 v[182:185], v141 offset:53248
	ds_read_b128 v[186:189], v141 offset:54272
	ds_read_b128 v[194:197], v141 offset:55296
	ds_read_b128 v[198:201], v141 offset:56320
	global_load_lds_dwordx4 v[190:191], off
	v_lshl_add_u64 v[190:191], v[202:203], 0, s[10:11]
	s_mov_b32 m0, s30
	s_nop 0
	global_load_lds_dwordx4 v[190:191], off
	v_lshl_add_u64 v[190:191], s[58:59], 0, v[192:193]
	s_mov_b32 m0, s45
	s_nop 0
	global_load_lds_dwordx4 v[190:191], off
	v_lshl_add_u64 v[190:191], s[58:59], 0, v[128:129]
	s_mov_b32 m0, s46
	s_nop 0
	global_load_lds_dwordx4 v[190:191], off
	v_lshl_add_u64 v[190:191], v[204:205], 0, s[10:11]
	s_mov_b32 m0, s4
	s_nop 0
	global_load_lds_dwordx4 v[190:191], off
	v_lshl_add_u64 v[190:191], v[206:207], 0, s[10:11]
	s_mov_b32 m0, s8
	s_nop 0
	global_load_lds_dwordx4 v[190:191], off
	s_waitcnt vmcnt(8)
	s_waitcnt lgkmcnt(0)
	s_barrier
	s_setprio 1
	s_waitcnt lgkmcnt(0)
	v_mfma_f32_16x16x32_bf16 v[60:63], v[130:133], v[166:169], v[60:63]
	v_mfma_f32_16x16x32_bf16 v[56:59], v[142:145], v[166:169], v[56:59]
	v_mfma_f32_16x16x32_bf16 v[44:47], v[130:133], v[174:177], v[44:47]
	v_mfma_f32_16x16x32_bf16 v[40:43], v[142:145], v[174:177], v[40:43]
	v_mfma_f32_16x16x32_bf16 v[28:31], v[130:133], v[182:185], v[28:31]
	v_mfma_f32_16x16x32_bf16 v[24:27], v[142:145], v[182:185], v[24:27]
	v_mfma_f32_16x16x32_bf16 v[12:15], v[130:133], v[194:197], v[12:15]
	v_mfma_f32_16x16x32_bf16 v[8:11], v[142:145], v[194:197], v[8:11]
	v_mfma_f32_16x16x32_bf16 v[60:63], v[134:137], v[170:173], v[60:63]
	v_mfma_f32_16x16x32_bf16 v[56:59], v[146:149], v[170:173], v[56:59]
	v_mfma_f32_16x16x32_bf16 v[44:47], v[134:137], v[178:181], v[44:47]
	v_mfma_f32_16x16x32_bf16 v[40:43], v[146:149], v[178:181], v[40:43]
	v_mfma_f32_16x16x32_bf16 v[28:31], v[134:137], v[186:189], v[28:31]
	v_mfma_f32_16x16x32_bf16 v[24:27], v[146:149], v[186:189], v[24:27]
	v_mfma_f32_16x16x32_bf16 v[12:15], v[134:137], v[198:201], v[12:15]
	v_mfma_f32_16x16x32_bf16 v[8:11], v[146:149], v[198:201], v[8:11]
	s_setprio 0
	s_setprio 1
	v_mfma_f32_16x16x32_bf16 v[52:55], v[150:153], v[166:169], v[52:55]
	v_mfma_f32_16x16x32_bf16 v[48:51], v[158:161], v[166:169], v[48:51]
	v_mfma_f32_16x16x32_bf16 v[36:39], v[150:153], v[174:177], v[36:39]
	v_mfma_f32_16x16x32_bf16 v[32:35], v[158:161], v[174:177], v[32:35]
	v_mfma_f32_16x16x32_bf16 v[20:23], v[150:153], v[182:185], v[20:23]
	v_mfma_f32_16x16x32_bf16 v[16:19], v[158:161], v[182:185], v[16:19]
	v_mfma_f32_16x16x32_bf16 v[4:7], v[150:153], v[194:197], v[4:7]
	v_mfma_f32_16x16x32_bf16 v[0:3], v[158:161], v[194:197], v[0:3]
	v_mfma_f32_16x16x32_bf16 v[52:55], v[154:157], v[170:173], v[52:55]
	v_mfma_f32_16x16x32_bf16 v[48:51], v[162:165], v[170:173], v[48:51]
	v_mfma_f32_16x16x32_bf16 v[36:39], v[154:157], v[178:181], v[36:39]
	v_mfma_f32_16x16x32_bf16 v[32:35], v[162:165], v[178:181], v[32:35]
	v_mfma_f32_16x16x32_bf16 v[20:23], v[154:157], v[186:189], v[20:23]
	v_mfma_f32_16x16x32_bf16 v[16:19], v[162:165], v[186:189], v[16:19]
	v_mfma_f32_16x16x32_bf16 v[4:7], v[154:157], v[198:201], v[4:7]
	v_mfma_f32_16x16x32_bf16 v[0:3], v[162:165], v[198:201], v[0:3]
	s_setprio 0
	s_barrier
	s_movk_i32 s30, 0x100
	s_andn2_b64 vcc, exec, s[40:41]
	s_mov_b64 s[58:59], -1
	s_mov_b64 s[40:41], 0
	s_cbranch_vccz .LBB0_319
	s_add_i32 s20, s29, 8
	s_cmp_lt_u32 s20, 4
	s_cselect_b64 vcc, -1, 0
	s_and_b32 s20, s20, -4
	s_cmp_eq_u32 s20, 4
	s_cselect_b64 s[40:41], -1, 0
	s_and_b64 s[20:21], s[40:41], exec
	s_mov_b64 s[58:59], s[80:81]
	s_cselect_b32 s34, 0x4000000, s58
	s_or_b64 s[20:21], vcc, s[40:41]
	s_and_b64 s[20:21], s[20:21], exec
	s_cselect_b32 s21, 0, s59
	s_and_b64 s[30:31], vcc, exec
	s_cselect_b32 s20, 0, s34
	s_lshl_b64 s[20:21], s[20:21], 1
	s_add_u32 s20, s12, s20
	s_addc_u32 s21, s13, s21
	s_and_b64 s[30:31], vcc, exec
	s_mov_b64 s[60:61], s[70:71]
	s_cselect_b32 s31, 0, s61
	s_cselect_b32 s30, 0, s60
	s_lshl_b64 s[30:31], s[30:31], 2
	s_mov_b64 s[46:47], s[50:51]
	s_add_u32 s30, s46, s30
	s_addc_u32 s31, s47, s31
	s_lshl_b32 s34, s36, 8
	v_readlane_b32 s35, v253, 5
	v_mov_b32_e32 v130, v138
	v_mov_b32_e32 v131, v139
	s_add_i32 s34, s34, s35
	s_lshl_b32 s29, s29, 8
	s_and_b32 s29, s29, 0x300
	v_add_u32_e32 v132, s34, v130
	v_readlane_b32 s34, v253, 19
	s_or_b32 s29, s29, s34
	v_lshl_add_u32 v134, v131, 3, s29
	v_ashrrev_i32_e32 v133, 31, v132
	v_lshlrev_b64 v[130:131], 11, v[132:133]
	v_ashrrev_i32_e32 v135, 31, v134
	v_lshl_add_u64 v[136:137], s[20:21], 0, v[130:131]
	v_lshl_add_u64 v[130:131], v[134:135], 2, s[30:31]
	global_load_dwordx4 v[148:151], v[130:131], off
	global_load_dwordx4 v[152:155], v[130:131], off offset:16
	global_load_dwordx4 v[156:159], v[130:131], off offset:128
	global_load_dwordx4 v[160:163], v[130:131], off offset:144
	s_mov_b32 s36, s56
	s_mov_b32 s29, s54
	s_waitcnt vmcnt(0)
; __device__ __forceinline__ unsigned cvt_pk_bf16(float lo, float hi) { unsigned r; asm volatile("v_cvt_pk_bf16_f32 %0, %1, %2" : "=v"(r) : "v"(lo), "v"(hi)); return r; }
; __device__ __forceinline__ float sigmoidf_(float x) { return __builtin_amdgcn_rcpf(1.0f + __builtin_amdgcn_exp2f(-1.44269504088896f * x)); }
;     __device__ __forceinline__ void operator()(AccRef acc, int pm, int pn, int wr, int wc, int fr, int fq) const {
;     ...
;             for (int m = 0; m < 4; ++m) { bf16_t* rp = dst + (size_t)EPI_ROW(ai, m) * 1024;
; #pragma unroll
;                 for (int bj = 0; bj < 2; ++bj) { const int c0 = (pn & 3) * 256 + wc * 64 + bj * 32 + 8 * fq; u32x4 w; unsigned pk[4];
; #pragma unroll
;                     for (int n = 0; n < 2; ++n) { const f32x4 v = acc[ai][bj][m][n]; const f32x4 b = *(const f32x4*)(bias + c0 + 4 * n);
;                         f32x4 r;
; #pragma unroll
;                         for (int j = 0; j < 4; ++j) { const float z = b[j] + v[j]; const float sg = sigmoidf_(z);
;                             r[j] = sec == 0 ? sg * 0.60653065971f : (sec == 1 ? sg : v[j]); }
;                         pk[2 * n] = cvt_pk_bf16(r[0], r[1]); pk[2 * n + 1] = cvt_pk_bf16(r[2], r[3]); }
;                     w.x = pk[0]; w.y = pk[1]; w.z = pk[2]; w.w = pk[3]; *(u32x4*)(rp + c0) = w; } }
	v_add_f32_e32 v133, v124, v148
	v_mul_f32_e32 v133, 0xbfb8aa3b, v133
	v_exp_f32_e32 v133, v133
	s_nop 0
	v_add_f32_e32 v133, 1.0, v133
	v_rcp_f32_e32 v133, v133
	s_nop 0
	v_mul_f32_e32 v142, 0x3f1b4598, v133
	v_cndmask_b32_e64 v124, v124, v133, s[40:41]
	v_add_f32_e32 v133, v125, v149
	v_mul_f32_e32 v133, 0xbfb8aa3b, v133
	v_exp_f32_e32 v133, v133
	v_cndmask_b32_e32 v124, v124, v142, vcc
	v_add_f32_e32 v133, 1.0, v133
	v_rcp_f32_e32 v133, v133
	s_nop 0
	v_mul_f32_e32 v142, 0x3f1b4598, v133
	v_cndmask_b32_e64 v125, v125, v133, s[40:41]
	v_add_f32_e32 v133, v126, v150
	v_mul_f32_e32 v133, 0xbfb8aa3b, v133
	v_exp_f32_e32 v133, v133
	v_cndmask_b32_e32 v125, v125, v142, vcc
	v_cvt_pk_bf16_f32 v124, v124, v125
	v_add_f32_e32 v133, 1.0, v133
	v_rcp_f32_e32 v133, v133
	s_nop 0
	v_mul_f32_e32 v142, 0x3f1b4598, v133
	v_cndmask_b32_e64 v126, v126, v133, s[40:41]
	v_add_f32_e32 v133, v127, v151
	v_mul_f32_e32 v133, 0xbfb8aa3b, v133
	v_exp_f32_e32 v133, v133
	v_cndmask_b32_e32 v126, v126, v142, vcc
	v_add_f32_e32 v133, 1.0, v133
	v_rcp_f32_e32 v133, v133
	s_nop 0
	v_mul_f32_e32 v142, 0x3f1b4598, v133
	v_cndmask_b32_e64 v127, v127, v133, s[40:41]
	v_cndmask_b32_e32 v127, v127, v142, vcc
	v_cvt_pk_bf16_f32 v125, v126, v127
	v_add_f32_e32 v126, v120, v152
	v_mul_f32_e32 v126, 0xbfb8aa3b, v126
	v_exp_f32_e32 v126, v126
	s_nop 0
	v_add_f32_e32 v126, 1.0, v126
	v_rcp_f32_e32 v126, v126
	s_nop 0
	v_mul_f32_e32 v127, 0x3f1b4598, v126
	v_cndmask_b32_e64 v120, v120, v126, s[40:41]
	v_add_f32_e32 v126, v121, v153
	v_mul_f32_e32 v126, 0xbfb8aa3b, v126
	v_exp_f32_e32 v126, v126
	v_cndmask_b32_e32 v120, v120, v127, vcc
	v_add_f32_e32 v126, 1.0, v126
	v_rcp_f32_e32 v126, v126
	s_nop 0
	v_mul_f32_e32 v127, 0x3f1b4598, v126
	v_cndmask_b32_e64 v121, v121, v126, s[40:41]
	v_add_f32_e32 v126, v122, v154
	v_mul_f32_e32 v126, 0xbfb8aa3b, v126
	v_exp_f32_e32 v126, v126
	v_cndmask_b32_e32 v121, v121, v127, vcc
	v_add_f32_e32 v126, 1.0, v126
	v_rcp_f32_e32 v126, v126
	s_nop 0
	v_mul_f32_e32 v127, 0x3f1b4598, v126
	v_cndmask_b32_e64 v122, v122, v126, s[40:41]
	v_add_f32_e32 v126, v123, v155
	v_mul_f32_e32 v126, 0xbfb8aa3b, v126
	v_exp_f32_e32 v126, v126
	v_cndmask_b32_e32 v122, v122, v127, vcc
	v_add_f32_e32 v126, 1.0, v126
	v_rcp_f32_e32 v126, v126
	s_nop 0
	v_mul_f32_e32 v127, 0x3f1b4598, v126
	v_cndmask_b32_e64 v123, v123, v126, s[40:41]
	v_cndmask_b32_e32 v123, v123, v127, vcc
	v_cvt_pk_bf16_f32 v126, v120, v121
	v_lshlrev_b64 v[120:121], 1, v[134:135]
	v_cvt_pk_bf16_f32 v127, v122, v123
	v_lshl_add_u64 v[122:123], v[136:137], 0, v[120:121]
	flat_store_dwordx4 v[122:123], v[124:127]
	s_nop 1
	v_add_f32_e32 v124, v116, v156
	v_mul_f32_e32 v124, 0xbfb8aa3b, v124
	v_exp_f32_e32 v124, v124
	s_nop 0
	v_add_f32_e32 v124, 1.0, v124
	v_rcp_f32_e32 v124, v124
	s_nop 0
	v_mul_f32_e32 v133, 0x3f1b4598, v124
	v_cndmask_b32_e64 v116, v116, v124, s[40:41]
	v_add_f32_e32 v124, v117, v157
	v_mul_f32_e32 v124, 0xbfb8aa3b, v124
	v_exp_f32_e32 v124, v124
	v_cndmask_b32_e32 v116, v116, v133, vcc
	v_add_f32_e32 v124, 1.0, v124
	v_rcp_f32_e32 v124, v124
	s_nop 0
	v_mul_f32_e32 v125, 0x3f1b4598, v124
	v_cndmask_b32_e64 v117, v117, v124, s[40:41]
	v_add_f32_e32 v124, v118, v158
	v_mul_f32_e32 v124, 0xbfb8aa3b, v124
	v_exp_f32_e32 v124, v124
	v_cndmask_b32_e32 v117, v117, v125, vcc
	v_cvt_pk_bf16_f32 v116, v116, v117
	v_add_f32_e32 v124, 1.0, v124
	v_rcp_f32_e32 v124, v124
	s_nop 0
	v_mul_f32_e32 v125, 0x3f1b4598, v124
	v_cndmask_b32_e64 v118, v118, v124, s[40:41]
	v_add_f32_e32 v124, v119, v159
	v_mul_f32_e32 v124, 0xbfb8aa3b, v124
	v_exp_f32_e32 v124, v124
	v_cndmask_b32_e32 v118, v118, v125, vcc
	v_add_f32_e32 v124, 1.0, v124
	v_rcp_f32_e32 v124, v124
	s_nop 0
	v_mul_f32_e32 v125, 0x3f1b4598, v124
	v_cndmask_b32_e64 v119, v119, v124, s[40:41]
	v_cndmask_b32_e32 v119, v119, v125, vcc
	v_cvt_pk_bf16_f32 v117, v118, v119
	v_add_f32_e32 v118, v112, v160
	v_mul_f32_e32 v118, 0xbfb8aa3b, v118
	v_exp_f32_e32 v118, v118
	s_nop 0
	v_add_f32_e32 v118, 1.0, v118
	v_rcp_f32_e32 v118, v118
	s_nop 0
	v_mul_f32_e32 v119, 0x3f1b4598, v118
	v_cndmask_b32_e64 v112, v112, v118, s[40:41]
	v_add_f32_e32 v118, v113, v161
	v_mul_f32_e32 v118, 0xbfb8aa3b, v118
	v_exp_f32_e32 v118, v118
	v_cndmask_b32_e32 v112, v112, v119, vcc
	v_add_f32_e32 v118, 1.0, v118
	v_rcp_f32_e32 v118, v118
	s_nop 0
	v_mul_f32_e32 v119, 0x3f1b4598, v118
	v_cndmask_b32_e64 v113, v113, v118, s[40:41]
	v_add_f32_e32 v118, v114, v162
	v_mul_f32_e32 v118, 0xbfb8aa3b, v118
	v_exp_f32_e32 v118, v118
	v_cndmask_b32_e32 v113, v113, v119, vcc
	v_add_f32_e32 v118, 1.0, v118
	v_rcp_f32_e32 v118, v118
	s_nop 0
	v_mul_f32_e32 v119, 0x3f1b4598, v118
	v_cndmask_b32_e64 v114, v114, v118, s[40:41]
	v_add_f32_e32 v118, v115, v163
	v_mul_f32_e32 v118, 0xbfb8aa3b, v118
	v_exp_f32_e32 v118, v118
	v_cndmask_b32_e32 v114, v114, v119, vcc
	v_add_f32_e32 v118, 1.0, v118
	v_rcp_f32_e32 v118, v118
	s_nop 0
	v_mul_f32_e32 v119, 0x3f1b4598, v118
	v_cndmask_b32_e64 v115, v115, v118, s[40:41]
	v_cndmask_b32_e32 v115, v115, v119, vcc
	v_cvt_pk_bf16_f32 v118, v112, v113
	v_cvt_pk_bf16_f32 v119, v114, v115
	flat_store_dwordx4 v[122:123], v[116:119] offset:64
	s_nop 1
	v_add_u32_e32 v112, 16, v132
	v_ashrrev_i32_e32 v113, 31, v112
	v_lshlrev_b64 v[112:113], 11, v[112:113]
	v_lshl_add_u64 v[112:113], s[20:21], 0, v[112:113]
	v_add_f32_e32 v114, v108, v148
	v_mul_f32_e32 v114, 0xbfb8aa3b, v114
	v_exp_f32_e32 v114, v114
	s_nop 0
	v_add_f32_e32 v114, 1.0, v114
	v_rcp_f32_e32 v114, v114
	s_nop 0
	v_mul_f32_e32 v118, 0x3f1b4598, v114
	v_cndmask_b32_e64 v108, v108, v114, s[40:41]
	v_add_f32_e32 v114, v109, v149
	v_mul_f32_e32 v114, 0xbfb8aa3b, v114
	v_exp_f32_e32 v114, v114
; __device__ __forceinline__ unsigned cvt_pk_bf16(float lo, float hi) { unsigned r; asm volatile("v_cvt_pk_bf16_f32 %0, %1, %2" : "=v"(r) : "v"(lo), "v"(hi)); return r; }
; __device__ __forceinline__ float sigmoidf_(float x) { return __builtin_amdgcn_rcpf(1.0f + __builtin_amdgcn_exp2f(-1.44269504088896f * x)); }
;     __device__ __forceinline__ void operator()(AccRef acc, int pm, int pn, int wr, int wc, int fr, int fq) const {
;     ...
;             for (int m = 0; m < 4; ++m) { bf16_t* rp = dst + (size_t)EPI_ROW(ai, m) * 1024;
; #pragma unroll
;                 for (int bj = 0; bj < 2; ++bj) { const int c0 = (pn & 3) * 256 + wc * 64 + bj * 32 + 8 * fq; u32x4 w; unsigned pk[4];
; #pragma unroll
;                     for (int n = 0; n < 2; ++n) { const f32x4 v = acc[ai][bj][m][n]; const f32x4 b = *(const f32x4*)(bias + c0 + 4 * n);
;                         f32x4 r;
; #pragma unroll
;                         for (int j = 0; j < 4; ++j) { const float z = b[j] + v[j]; const float sg = sigmoidf_(z);
;                             r[j] = sec == 0 ? sg * 0.60653065971f : (sec == 1 ? sg : v[j]); }
;                         pk[2 * n] = cvt_pk_bf16(r[0], r[1]); pk[2 * n + 1] = cvt_pk_bf16(r[2], r[3]); }
;                     w.x = pk[0]; w.y = pk[1]; w.z = pk[2]; w.w = pk[3]; *(u32x4*)(rp + c0) = w; } }
	v_cndmask_b32_e32 v108, v108, v118, vcc
	v_add_f32_e32 v114, 1.0, v114
	v_rcp_f32_e32 v114, v114
	s_nop 0
	v_mul_f32_e32 v115, 0x3f1b4598, v114
	v_cndmask_b32_e64 v109, v109, v114, s[40:41]
	v_add_f32_e32 v114, v110, v150
	v_mul_f32_e32 v114, 0xbfb8aa3b, v114
	v_exp_f32_e32 v114, v114
	v_cndmask_b32_e32 v109, v109, v115, vcc
	v_cvt_pk_bf16_f32 v108, v108, v109
	v_add_f32_e32 v114, 1.0, v114
	v_rcp_f32_e32 v114, v114
	s_nop 0
	v_mul_f32_e32 v115, 0x3f1b4598, v114
	v_cndmask_b32_e64 v110, v110, v114, s[40:41]
	v_add_f32_e32 v114, v111, v151
	v_mul_f32_e32 v114, 0xbfb8aa3b, v114
	v_exp_f32_e32 v114, v114
	v_cndmask_b32_e32 v110, v110, v115, vcc
	v_add_f32_e32 v114, 1.0, v114
	v_rcp_f32_e32 v114, v114
	s_nop 0
	v_mul_f32_e32 v115, 0x3f1b4598, v114
	v_cndmask_b32_e64 v111, v111, v114, s[40:41]
	v_cndmask_b32_e32 v111, v111, v115, vcc
	v_cvt_pk_bf16_f32 v109, v110, v111
	v_add_f32_e32 v110, v104, v152
	v_mul_f32_e32 v110, 0xbfb8aa3b, v110
	v_exp_f32_e32 v110, v110
	s_nop 0
	v_add_f32_e32 v110, 1.0, v110
	v_rcp_f32_e32 v110, v110
	s_nop 0
	v_mul_f32_e32 v111, 0x3f1b4598, v110
	v_cndmask_b32_e64 v104, v104, v110, s[40:41]
	v_add_f32_e32 v110, v105, v153
	v_mul_f32_e32 v110, 0xbfb8aa3b, v110
	v_exp_f32_e32 v110, v110
	v_cndmask_b32_e32 v104, v104, v111, vcc
	v_add_f32_e32 v110, 1.0, v110
	v_rcp_f32_e32 v110, v110
	s_nop 0
	v_mul_f32_e32 v111, 0x3f1b4598, v110
	v_cndmask_b32_e64 v105, v105, v110, s[40:41]
	v_add_f32_e32 v110, v106, v154
	v_mul_f32_e32 v110, 0xbfb8aa3b, v110
	v_exp_f32_e32 v110, v110
	v_cndmask_b32_e32 v105, v105, v111, vcc
	v_add_f32_e32 v110, 1.0, v110
	v_rcp_f32_e32 v110, v110
	s_nop 0
	v_mul_f32_e32 v111, 0x3f1b4598, v110
	v_cndmask_b32_e64 v106, v106, v110, s[40:41]
	v_add_f32_e32 v110, v107, v155
	v_mul_f32_e32 v110, 0xbfb8aa3b, v110
	v_exp_f32_e32 v110, v110
	v_cndmask_b32_e32 v106, v106, v111, vcc
	v_add_f32_e32 v110, 1.0, v110
	v_rcp_f32_e32 v110, v110
	s_nop 0
	v_mul_f32_e32 v111, 0x3f1b4598, v110
	v_cndmask_b32_e64 v107, v107, v110, s[40:41]
	v_cvt_pk_bf16_f32 v110, v104, v105
	v_lshl_add_u64 v[104:105], v[112:113], 0, v[120:121]
	v_cndmask_b32_e32 v107, v107, v111, vcc
	v_cvt_pk_bf16_f32 v111, v106, v107
	flat_store_dwordx4 v[104:105], v[108:111]
	s_nop 1
	v_add_f32_e32 v106, v100, v156
	v_mul_f32_e32 v106, 0xbfb8aa3b, v106
	v_exp_f32_e32 v106, v106
	s_nop 0
	v_add_f32_e32 v106, 1.0, v106
	v_rcp_f32_e32 v106, v106
	s_nop 0
	v_mul_f32_e32 v110, 0x3f1b4598, v106
	v_cndmask_b32_e64 v100, v100, v106, s[40:41]
	v_add_f32_e32 v106, v101, v157
	v_mul_f32_e32 v106, 0xbfb8aa3b, v106
	v_exp_f32_e32 v106, v106
	v_cndmask_b32_e32 v100, v100, v110, vcc
	v_add_f32_e32 v106, 1.0, v106
	v_rcp_f32_e32 v106, v106
	s_nop 0
	v_mul_f32_e32 v107, 0x3f1b4598, v106
	v_cndmask_b32_e64 v101, v101, v106, s[40:41]
	v_add_f32_e32 v106, v102, v158
	v_mul_f32_e32 v106, 0xbfb8aa3b, v106
	v_exp_f32_e32 v106, v106
	v_cndmask_b32_e32 v101, v101, v107, vcc
	v_cvt_pk_bf16_f32 v100, v100, v101
	v_add_f32_e32 v106, 1.0, v106
	v_rcp_f32_e32 v106, v106
	s_nop 0
	v_mul_f32_e32 v107, 0x3f1b4598, v106
	v_cndmask_b32_e64 v102, v102, v106, s[40:41]
	v_add_f32_e32 v106, v103, v159
	v_mul_f32_e32 v106, 0xbfb8aa3b, v106
	v_exp_f32_e32 v106, v106
	v_cndmask_b32_e32 v102, v102, v107, vcc
	v_add_f32_e32 v106, 1.0, v106
	v_rcp_f32_e32 v106, v106
	s_nop 0
	v_mul_f32_e32 v107, 0x3f1b4598, v106
	v_cndmask_b32_e64 v103, v103, v106, s[40:41]
	v_cndmask_b32_e32 v103, v103, v107, vcc
	v_cvt_pk_bf16_f32 v101, v102, v103
	v_add_f32_e32 v102, v96, v160
	v_mul_f32_e32 v102, 0xbfb8aa3b, v102
	v_exp_f32_e32 v102, v102
	s_nop 0
	v_add_f32_e32 v102, 1.0, v102
	v_rcp_f32_e32 v102, v102
	s_nop 0
	v_mul_f32_e32 v103, 0x3f1b4598, v102
	v_cndmask_b32_e64 v96, v96, v102, s[40:41]
	v_add_f32_e32 v102, v97, v161
	v_mul_f32_e32 v102, 0xbfb8aa3b, v102
	v_exp_f32_e32 v102, v102
	v_cndmask_b32_e32 v96, v96, v103, vcc
	v_add_f32_e32 v102, 1.0, v102
	v_rcp_f32_e32 v102, v102
	s_nop 0
	v_mul_f32_e32 v103, 0x3f1b4598, v102
	v_cndmask_b32_e64 v97, v97, v102, s[40:41]
	v_add_f32_e32 v102, v98, v162
	v_mul_f32_e32 v102, 0xbfb8aa3b, v102
	v_exp_f32_e32 v102, v102
	v_cndmask_b32_e32 v97, v97, v103, vcc
	v_add_f32_e32 v102, 1.0, v102
	v_rcp_f32_e32 v102, v102
	s_nop 0
	v_mul_f32_e32 v103, 0x3f1b4598, v102
	v_cndmask_b32_e64 v98, v98, v102, s[40:41]
	v_add_f32_e32 v102, v99, v163
	v_mul_f32_e32 v102, 0xbfb8aa3b, v102
	v_exp_f32_e32 v102, v102
	v_cndmask_b32_e32 v98, v98, v103, vcc
	v_add_f32_e32 v102, 1.0, v102
	v_rcp_f32_e32 v102, v102
	s_nop 0
	v_mul_f32_e32 v103, 0x3f1b4598, v102
	v_cndmask_b32_e64 v99, v99, v102, s[40:41]
	v_cndmask_b32_e32 v99, v99, v103, vcc
	v_cvt_pk_bf16_f32 v102, v96, v97
	v_cvt_pk_bf16_f32 v103, v98, v99
	flat_store_dwordx4 v[104:105], v[100:103] offset:64
	s_nop 1
	v_add_u32_e32 v96, 32, v132
	v_ashrrev_i32_e32 v97, 31, v96
	v_lshlrev_b64 v[96:97], 11, v[96:97]
	v_lshl_add_u64 v[96:97], s[20:21], 0, v[96:97]
	v_add_f32_e32 v98, v92, v148
	v_mul_f32_e32 v98, 0xbfb8aa3b, v98
	v_exp_f32_e32 v98, v98
	s_nop 0
	v_add_f32_e32 v98, 1.0, v98
	v_rcp_f32_e32 v98, v98
	s_nop 0
	v_mul_f32_e32 v102, 0x3f1b4598, v98
	v_cndmask_b32_e64 v92, v92, v98, s[40:41]
	v_add_f32_e32 v98, v93, v149
	v_mul_f32_e32 v98, 0xbfb8aa3b, v98
	v_exp_f32_e32 v98, v98
	v_cndmask_b32_e32 v92, v92, v102, vcc
	v_add_f32_e32 v98, 1.0, v98
	v_rcp_f32_e32 v98, v98
	s_nop 0
	v_mul_f32_e32 v99, 0x3f1b4598, v98
	v_cndmask_b32_e64 v93, v93, v98, s[40:41]
	v_add_f32_e32 v98, v94, v150
	v_mul_f32_e32 v98, 0xbfb8aa3b, v98
	v_exp_f32_e32 v98, v98
	v_cndmask_b32_e32 v93, v93, v99, vcc
	v_cvt_pk_bf16_f32 v92, v92, v93
	v_add_f32_e32 v98, 1.0, v98
	v_rcp_f32_e32 v98, v98
	s_nop 0
	v_mul_f32_e32 v99, 0x3f1b4598, v98
; __device__ __forceinline__ unsigned cvt_pk_bf16(float lo, float hi) { unsigned r; asm volatile("v_cvt_pk_bf16_f32 %0, %1, %2" : "=v"(r) : "v"(lo), "v"(hi)); return r; }
; __device__ __forceinline__ float sigmoidf_(float x) { return __builtin_amdgcn_rcpf(1.0f + __builtin_amdgcn_exp2f(-1.44269504088896f * x)); }
;     __device__ __forceinline__ void operator()(AccRef acc, int pm, int pn, int wr, int wc, int fr, int fq) const {
;     ...
;             for (int m = 0; m < 4; ++m) { bf16_t* rp = dst + (size_t)EPI_ROW(ai, m) * 1024;
; #pragma unroll
;                 for (int bj = 0; bj < 2; ++bj) { const int c0 = (pn & 3) * 256 + wc * 64 + bj * 32 + 8 * fq; u32x4 w; unsigned pk[4];
; #pragma unroll
;                     for (int n = 0; n < 2; ++n) { const f32x4 v = acc[ai][bj][m][n]; const f32x4 b = *(const f32x4*)(bias + c0 + 4 * n);
;                         f32x4 r;
; #pragma unroll
;                         for (int j = 0; j < 4; ++j) { const float z = b[j] + v[j]; const float sg = sigmoidf_(z);
;                             r[j] = sec == 0 ? sg * 0.60653065971f : (sec == 1 ? sg : v[j]); }
;                         pk[2 * n] = cvt_pk_bf16(r[0], r[1]); pk[2 * n + 1] = cvt_pk_bf16(r[2], r[3]); }
;                     w.x = pk[0]; w.y = pk[1]; w.z = pk[2]; w.w = pk[3]; *(u32x4*)(rp + c0) = w; } }
	v_cndmask_b32_e64 v94, v94, v98, s[40:41]
	v_add_f32_e32 v98, v95, v151
	v_mul_f32_e32 v98, 0xbfb8aa3b, v98
	v_exp_f32_e32 v98, v98
	v_cndmask_b32_e32 v94, v94, v99, vcc
	v_add_f32_e32 v98, 1.0, v98
	v_rcp_f32_e32 v98, v98
	s_nop 0
	v_mul_f32_e32 v99, 0x3f1b4598, v98
	v_cndmask_b32_e64 v95, v95, v98, s[40:41]
	v_cndmask_b32_e32 v95, v95, v99, vcc
	v_cvt_pk_bf16_f32 v93, v94, v95
	v_add_f32_e32 v94, v88, v152
	v_mul_f32_e32 v94, 0xbfb8aa3b, v94
	v_exp_f32_e32 v94, v94
	s_nop 0
	v_add_f32_e32 v94, 1.0, v94
	v_rcp_f32_e32 v94, v94
	s_nop 0
	v_mul_f32_e32 v95, 0x3f1b4598, v94
	v_cndmask_b32_e64 v88, v88, v94, s[40:41]
	v_add_f32_e32 v94, v89, v153
	v_mul_f32_e32 v94, 0xbfb8aa3b, v94
	v_exp_f32_e32 v94, v94
	v_cndmask_b32_e32 v88, v88, v95, vcc
	v_add_f32_e32 v94, 1.0, v94
	v_rcp_f32_e32 v94, v94
	s_nop 0
	v_mul_f32_e32 v95, 0x3f1b4598, v94
	v_cndmask_b32_e64 v89, v89, v94, s[40:41]
	v_add_f32_e32 v94, v90, v154
	v_mul_f32_e32 v94, 0xbfb8aa3b, v94
	v_exp_f32_e32 v94, v94
	v_cndmask_b32_e32 v89, v89, v95, vcc
	v_add_f32_e32 v94, 1.0, v94
	v_rcp_f32_e32 v94, v94
	s_nop 0
	v_mul_f32_e32 v95, 0x3f1b4598, v94
	v_cndmask_b32_e64 v90, v90, v94, s[40:41]
	v_add_f32_e32 v94, v91, v155
	v_mul_f32_e32 v94, 0xbfb8aa3b, v94
	v_exp_f32_e32 v94, v94
	v_cndmask_b32_e32 v90, v90, v95, vcc
	v_add_f32_e32 v94, 1.0, v94
	v_rcp_f32_e32 v94, v94
	s_nop 0
	v_mul_f32_e32 v95, 0x3f1b4598, v94
	v_cndmask_b32_e64 v91, v91, v94, s[40:41]
	v_cvt_pk_bf16_f32 v94, v88, v89
	v_lshl_add_u64 v[88:89], v[96:97], 0, v[120:121]
	v_cndmask_b32_e32 v91, v91, v95, vcc
	v_cvt_pk_bf16_f32 v95, v90, v91
	flat_store_dwordx4 v[88:89], v[92:95]
	s_nop 1
	v_add_f32_e32 v90, v84, v156
	v_mul_f32_e32 v90, 0xbfb8aa3b, v90
	v_exp_f32_e32 v90, v90
	s_nop 0
	v_add_f32_e32 v90, 1.0, v90
	v_rcp_f32_e32 v90, v90
	s_nop 0
	v_mul_f32_e32 v94, 0x3f1b4598, v90
	v_cndmask_b32_e64 v84, v84, v90, s[40:41]
	v_add_f32_e32 v90, v85, v157
	v_mul_f32_e32 v90, 0xbfb8aa3b, v90
	v_exp_f32_e32 v90, v90
	v_cndmask_b32_e32 v84, v84, v94, vcc
	v_add_f32_e32 v90, 1.0, v90
	v_rcp_f32_e32 v90, v90
	s_nop 0
	v_mul_f32_e32 v91, 0x3f1b4598, v90
	v_cndmask_b32_e64 v85, v85, v90, s[40:41]
	v_add_f32_e32 v90, v86, v158
	v_mul_f32_e32 v90, 0xbfb8aa3b, v90
	v_exp_f32_e32 v90, v90
	v_cndmask_b32_e32 v85, v85, v91, vcc
	v_cvt_pk_bf16_f32 v84, v84, v85
	v_add_f32_e32 v90, 1.0, v90
	v_rcp_f32_e32 v90, v90
	s_nop 0
	v_mul_f32_e32 v91, 0x3f1b4598, v90
	v_cndmask_b32_e64 v86, v86, v90, s[40:41]
	v_add_f32_e32 v90, v87, v159
	v_mul_f32_e32 v90, 0xbfb8aa3b, v90
	v_exp_f32_e32 v90, v90
	v_cndmask_b32_e32 v86, v86, v91, vcc
	v_add_f32_e32 v90, 1.0, v90
	v_rcp_f32_e32 v90, v90
	s_nop 0
	v_mul_f32_e32 v91, 0x3f1b4598, v90
	v_cndmask_b32_e64 v87, v87, v90, s[40:41]
	v_cndmask_b32_e32 v87, v87, v91, vcc
	v_cvt_pk_bf16_f32 v85, v86, v87
	v_add_f32_e32 v86, v80, v160
	v_mul_f32_e32 v86, 0xbfb8aa3b, v86
	v_exp_f32_e32 v86, v86
	s_nop 0
	v_add_f32_e32 v86, 1.0, v86
	v_rcp_f32_e32 v86, v86
	s_nop 0
	v_mul_f32_e32 v87, 0x3f1b4598, v86
	v_cndmask_b32_e64 v80, v80, v86, s[40:41]
	v_add_f32_e32 v86, v81, v161
	v_mul_f32_e32 v86, 0xbfb8aa3b, v86
	v_exp_f32_e32 v86, v86
	v_cndmask_b32_e32 v80, v80, v87, vcc
	v_add_f32_e32 v86, 1.0, v86
	v_rcp_f32_e32 v86, v86
	s_nop 0
	v_mul_f32_e32 v87, 0x3f1b4598, v86
	v_cndmask_b32_e64 v81, v81, v86, s[40:41]
	v_add_f32_e32 v86, v82, v162
	v_mul_f32_e32 v86, 0xbfb8aa3b, v86
	v_exp_f32_e32 v86, v86
	v_cndmask_b32_e32 v81, v81, v87, vcc
	v_add_f32_e32 v86, 1.0, v86
	v_rcp_f32_e32 v86, v86
	s_nop 0
	v_mul_f32_e32 v87, 0x3f1b4598, v86
	v_cndmask_b32_e64 v82, v82, v86, s[40:41]
	v_add_f32_e32 v86, v83, v163
	v_mul_f32_e32 v86, 0xbfb8aa3b, v86
	v_exp_f32_e32 v86, v86
	v_cndmask_b32_e32 v82, v82, v87, vcc
	v_add_f32_e32 v86, 1.0, v86
	v_rcp_f32_e32 v86, v86
	s_nop 0
	v_mul_f32_e32 v87, 0x3f1b4598, v86
	v_cndmask_b32_e64 v83, v83, v86, s[40:41]
	v_cndmask_b32_e32 v83, v83, v87, vcc
	v_cvt_pk_bf16_f32 v86, v80, v81
	v_cvt_pk_bf16_f32 v87, v82, v83
	flat_store_dwordx4 v[88:89], v[84:87] offset:64
	s_nop 1
	v_add_u32_e32 v80, 48, v132
	v_ashrrev_i32_e32 v81, 31, v80
	v_lshlrev_b64 v[80:81], 11, v[80:81]
	v_lshl_add_u64 v[80:81], s[20:21], 0, v[80:81]
	v_add_f32_e32 v82, v76, v148
	v_mul_f32_e32 v82, 0xbfb8aa3b, v82
	v_exp_f32_e32 v82, v82
	s_nop 0
	v_add_f32_e32 v82, 1.0, v82
	v_rcp_f32_e32 v82, v82
	s_nop 0
	v_mul_f32_e32 v86, 0x3f1b4598, v82
	v_cndmask_b32_e64 v76, v76, v82, s[40:41]
	v_add_f32_e32 v82, v77, v149
	v_mul_f32_e32 v82, 0xbfb8aa3b, v82
	v_exp_f32_e32 v82, v82
	v_cndmask_b32_e32 v76, v76, v86, vcc
	v_add_f32_e32 v82, 1.0, v82
	v_rcp_f32_e32 v82, v82
	s_nop 0
	v_mul_f32_e32 v83, 0x3f1b4598, v82
	v_cndmask_b32_e64 v77, v77, v82, s[40:41]
	v_add_f32_e32 v82, v78, v150
	v_mul_f32_e32 v82, 0xbfb8aa3b, v82
	v_exp_f32_e32 v82, v82
	v_cndmask_b32_e32 v77, v77, v83, vcc
	v_cvt_pk_bf16_f32 v76, v76, v77
	v_add_f32_e32 v82, 1.0, v82
	v_rcp_f32_e32 v82, v82
	s_nop 0
	v_mul_f32_e32 v83, 0x3f1b4598, v82
	v_cndmask_b32_e64 v78, v78, v82, s[40:41]
	v_add_f32_e32 v82, v79, v151
	v_mul_f32_e32 v82, 0xbfb8aa3b, v82
	v_exp_f32_e32 v82, v82
	v_cndmask_b32_e32 v78, v78, v83, vcc
	v_add_f32_e32 v82, 1.0, v82
	v_rcp_f32_e32 v82, v82
	s_nop 0
	v_mul_f32_e32 v83, 0x3f1b4598, v82
	v_cndmask_b32_e64 v79, v79, v82, s[40:41]
	v_cndmask_b32_e32 v79, v79, v83, vcc
	v_cvt_pk_bf16_f32 v77, v78, v79
	v_add_f32_e32 v78, v72, v152
	v_mul_f32_e32 v78, 0xbfb8aa3b, v78
	v_exp_f32_e32 v78, v78
	s_nop 0
	v_add_f32_e32 v78, 1.0, v78
	v_rcp_f32_e32 v78, v78
	s_nop 0
	v_mul_f32_e32 v79, 0x3f1b4598, v78
	v_cndmask_b32_e64 v72, v72, v78, s[40:41]
	v_add_f32_e32 v78, v73, v153
	v_mul_f32_e32 v78, 0xbfb8aa3b, v78
	v_exp_f32_e32 v78, v78
	v_cndmask_b32_e32 v72, v72, v79, vcc
; __device__ __forceinline__ unsigned cvt_pk_bf16(float lo, float hi) { unsigned r; asm volatile("v_cvt_pk_bf16_f32 %0, %1, %2" : "=v"(r) : "v"(lo), "v"(hi)); return r; }
; __device__ __forceinline__ float sigmoidf_(float x) { return __builtin_amdgcn_rcpf(1.0f + __builtin_amdgcn_exp2f(-1.44269504088896f * x)); }
;     __device__ __forceinline__ void operator()(AccRef acc, int pm, int pn, int wr, int wc, int fr, int fq) const {
;     ...
;             for (int m = 0; m < 4; ++m) { bf16_t* rp = dst + (size_t)EPI_ROW(ai, m) * 1024;
; #pragma unroll
;                 for (int bj = 0; bj < 2; ++bj) { const int c0 = (pn & 3) * 256 + wc * 64 + bj * 32 + 8 * fq; u32x4 w; unsigned pk[4];
; #pragma unroll
;                     for (int n = 0; n < 2; ++n) { const f32x4 v = acc[ai][bj][m][n]; const f32x4 b = *(const f32x4*)(bias + c0 + 4 * n);
;                         f32x4 r;
; #pragma unroll
;                         for (int j = 0; j < 4; ++j) { const float z = b[j] + v[j]; const float sg = sigmoidf_(z);
;                             r[j] = sec == 0 ? sg * 0.60653065971f : (sec == 1 ? sg : v[j]); }
;                         pk[2 * n] = cvt_pk_bf16(r[0], r[1]); pk[2 * n + 1] = cvt_pk_bf16(r[2], r[3]); }
;                     w.x = pk[0]; w.y = pk[1]; w.z = pk[2]; w.w = pk[3]; *(u32x4*)(rp + c0) = w; } }
	v_add_f32_e32 v78, 1.0, v78
	v_rcp_f32_e32 v78, v78
	s_nop 0
	v_mul_f32_e32 v79, 0x3f1b4598, v78
	v_cndmask_b32_e64 v73, v73, v78, s[40:41]
	v_add_f32_e32 v78, v74, v154
	v_mul_f32_e32 v78, 0xbfb8aa3b, v78
	v_exp_f32_e32 v78, v78
	v_cndmask_b32_e32 v73, v73, v79, vcc
	v_add_f32_e32 v78, 1.0, v78
	v_rcp_f32_e32 v78, v78
	s_nop 0
	v_mul_f32_e32 v79, 0x3f1b4598, v78
	v_cndmask_b32_e64 v74, v74, v78, s[40:41]
	v_add_f32_e32 v78, v75, v155
	v_mul_f32_e32 v78, 0xbfb8aa3b, v78
	v_exp_f32_e32 v78, v78
	v_cndmask_b32_e32 v74, v74, v79, vcc
	v_add_f32_e32 v78, 1.0, v78
	v_rcp_f32_e32 v78, v78
	s_nop 0
	v_mul_f32_e32 v79, 0x3f1b4598, v78
	v_cndmask_b32_e64 v75, v75, v78, s[40:41]
	v_cvt_pk_bf16_f32 v78, v72, v73
	v_lshl_add_u64 v[72:73], v[80:81], 0, v[120:121]
	v_cndmask_b32_e32 v75, v75, v79, vcc
	v_cvt_pk_bf16_f32 v79, v74, v75
	flat_store_dwordx4 v[72:73], v[76:79]
	s_nop 1
	v_add_f32_e32 v74, v68, v156
	v_mul_f32_e32 v74, 0xbfb8aa3b, v74
	v_exp_f32_e32 v74, v74
	s_nop 0
	v_add_f32_e32 v74, 1.0, v74
	v_rcp_f32_e32 v74, v74
	s_nop 0
	v_mul_f32_e32 v78, 0x3f1b4598, v74
	v_cndmask_b32_e64 v68, v68, v74, s[40:41]
	v_add_f32_e32 v74, v69, v157
	v_mul_f32_e32 v74, 0xbfb8aa3b, v74
	v_exp_f32_e32 v74, v74
	v_cndmask_b32_e32 v68, v68, v78, vcc
	v_add_f32_e32 v74, 1.0, v74
	v_rcp_f32_e32 v74, v74
	s_nop 0
	v_mul_f32_e32 v75, 0x3f1b4598, v74
	v_cndmask_b32_e64 v69, v69, v74, s[40:41]
	v_add_f32_e32 v74, v70, v158
	v_mul_f32_e32 v74, 0xbfb8aa3b, v74
	v_exp_f32_e32 v74, v74
	v_cndmask_b32_e32 v69, v69, v75, vcc
	v_cvt_pk_bf16_f32 v68, v68, v69
	v_add_f32_e32 v74, 1.0, v74
	v_rcp_f32_e32 v74, v74
	s_nop 0
	v_mul_f32_e32 v75, 0x3f1b4598, v74
	v_cndmask_b32_e64 v70, v70, v74, s[40:41]
	v_add_f32_e32 v74, v71, v159
	v_mul_f32_e32 v74, 0xbfb8aa3b, v74
	v_exp_f32_e32 v74, v74
	v_cndmask_b32_e32 v70, v70, v75, vcc
	v_add_f32_e32 v74, 1.0, v74
	v_rcp_f32_e32 v74, v74
	s_nop 0
	v_mul_f32_e32 v75, 0x3f1b4598, v74
	v_cndmask_b32_e64 v71, v71, v74, s[40:41]
	v_cndmask_b32_e32 v71, v71, v75, vcc
	v_cvt_pk_bf16_f32 v69, v70, v71
	v_add_f32_e32 v70, v64, v160
	v_mul_f32_e32 v70, 0xbfb8aa3b, v70
	v_exp_f32_e32 v70, v70
	s_nop 0
	v_add_f32_e32 v70, 1.0, v70
	v_rcp_f32_e32 v70, v70
	s_nop 0
	v_mul_f32_e32 v71, 0x3f1b4598, v70
	v_cndmask_b32_e64 v64, v64, v70, s[40:41]
	v_add_f32_e32 v70, v65, v161
	v_mul_f32_e32 v70, 0xbfb8aa3b, v70
	v_exp_f32_e32 v70, v70
	v_cndmask_b32_e32 v64, v64, v71, vcc
	v_add_f32_e32 v70, 1.0, v70
	v_rcp_f32_e32 v70, v70
	s_nop 0
	v_mul_f32_e32 v71, 0x3f1b4598, v70
	v_cndmask_b32_e64 v65, v65, v70, s[40:41]
	v_add_f32_e32 v70, v66, v162
	v_mul_f32_e32 v70, 0xbfb8aa3b, v70
	v_exp_f32_e32 v70, v70
	v_cndmask_b32_e32 v65, v65, v71, vcc
	v_add_f32_e32 v70, 1.0, v70
	v_rcp_f32_e32 v70, v70
	s_nop 0
	v_mul_f32_e32 v71, 0x3f1b4598, v70
	v_cndmask_b32_e64 v66, v66, v70, s[40:41]
	v_add_f32_e32 v70, v67, v163
	v_mul_f32_e32 v70, 0xbfb8aa3b, v70
	v_exp_f32_e32 v70, v70
	v_cndmask_b32_e32 v66, v66, v71, vcc
	v_add_f32_e32 v70, 1.0, v70
	v_rcp_f32_e32 v70, v70
	s_nop 0
	v_mul_f32_e32 v71, 0x3f1b4598, v70
	v_cndmask_b32_e64 v67, v67, v70, s[40:41]
	v_cndmask_b32_e32 v67, v67, v71, vcc
	v_cvt_pk_bf16_f32 v70, v64, v65
	v_cvt_pk_bf16_f32 v71, v66, v67
	flat_store_dwordx4 v[72:73], v[68:71] offset:64
	s_nop 1
	v_add_u32_e32 v64, 0x80, v132
	v_ashrrev_i32_e32 v65, 31, v64
	v_lshlrev_b64 v[64:65], 11, v[64:65]
	v_lshl_add_u64 v[64:65], s[20:21], 0, v[64:65]
	v_add_f32_e32 v66, v60, v148
	v_mul_f32_e32 v66, 0xbfb8aa3b, v66
	v_exp_f32_e32 v66, v66
	s_nop 0
	v_add_f32_e32 v66, 1.0, v66
	v_rcp_f32_e32 v66, v66
	s_nop 0
	v_mul_f32_e32 v70, 0x3f1b4598, v66
	v_cndmask_b32_e64 v60, v60, v66, s[40:41]
	v_add_f32_e32 v66, v61, v149
	v_mul_f32_e32 v66, 0xbfb8aa3b, v66
	v_exp_f32_e32 v66, v66
	v_cndmask_b32_e32 v60, v60, v70, vcc
	v_add_f32_e32 v66, 1.0, v66
	v_rcp_f32_e32 v66, v66
	s_nop 0
	v_mul_f32_e32 v67, 0x3f1b4598, v66
	v_cndmask_b32_e64 v61, v61, v66, s[40:41]
	v_add_f32_e32 v66, v62, v150
	v_mul_f32_e32 v66, 0xbfb8aa3b, v66
	v_exp_f32_e32 v66, v66
	v_cndmask_b32_e32 v61, v61, v67, vcc
	v_cvt_pk_bf16_f32 v60, v60, v61
	v_add_f32_e32 v66, 1.0, v66
	v_rcp_f32_e32 v66, v66
	s_nop 0
	v_mul_f32_e32 v67, 0x3f1b4598, v66
	v_cndmask_b32_e64 v62, v62, v66, s[40:41]
	v_add_f32_e32 v66, v63, v151
	v_mul_f32_e32 v66, 0xbfb8aa3b, v66
	v_exp_f32_e32 v66, v66
	v_cndmask_b32_e32 v62, v62, v67, vcc
	v_add_f32_e32 v66, 1.0, v66
	v_rcp_f32_e32 v66, v66
	s_nop 0
	v_mul_f32_e32 v67, 0x3f1b4598, v66
	v_cndmask_b32_e64 v63, v63, v66, s[40:41]
	v_cndmask_b32_e32 v63, v63, v67, vcc
	v_cvt_pk_bf16_f32 v61, v62, v63
	v_add_f32_e32 v62, v56, v152
	v_mul_f32_e32 v62, 0xbfb8aa3b, v62
	v_exp_f32_e32 v62, v62
	s_nop 0
	v_add_f32_e32 v62, 1.0, v62
	v_rcp_f32_e32 v62, v62
	s_nop 0
	v_mul_f32_e32 v63, 0x3f1b4598, v62
	v_cndmask_b32_e64 v56, v56, v62, s[40:41]
	v_add_f32_e32 v62, v57, v153
	v_mul_f32_e32 v62, 0xbfb8aa3b, v62
	v_exp_f32_e32 v62, v62
	v_cndmask_b32_e32 v56, v56, v63, vcc
	v_add_f32_e32 v62, 1.0, v62
	v_rcp_f32_e32 v62, v62
	s_nop 0
	v_mul_f32_e32 v63, 0x3f1b4598, v62
	v_cndmask_b32_e64 v57, v57, v62, s[40:41]
	v_add_f32_e32 v62, v58, v154
	v_mul_f32_e32 v62, 0xbfb8aa3b, v62
	v_exp_f32_e32 v62, v62
	v_cndmask_b32_e32 v57, v57, v63, vcc
	v_add_f32_e32 v62, 1.0, v62
	v_rcp_f32_e32 v62, v62
	s_nop 0
	v_mul_f32_e32 v63, 0x3f1b4598, v62
	v_cndmask_b32_e64 v58, v58, v62, s[40:41]
	v_add_f32_e32 v62, v59, v155
	v_mul_f32_e32 v62, 0xbfb8aa3b, v62
	v_exp_f32_e32 v62, v62
	v_cndmask_b32_e32 v58, v58, v63, vcc
	v_add_f32_e32 v62, 1.0, v62
	v_rcp_f32_e32 v62, v62
	s_nop 0
	v_mul_f32_e32 v63, 0x3f1b4598, v62
	v_cndmask_b32_e64 v59, v59, v62, s[40:41]
	v_cvt_pk_bf16_f32 v62, v56, v57
; __device__ __forceinline__ unsigned cvt_pk_bf16(float lo, float hi) { unsigned r; asm volatile("v_cvt_pk_bf16_f32 %0, %1, %2" : "=v"(r) : "v"(lo), "v"(hi)); return r; }
; __device__ __forceinline__ float sigmoidf_(float x) { return __builtin_amdgcn_rcpf(1.0f + __builtin_amdgcn_exp2f(-1.44269504088896f * x)); }
;     __device__ __forceinline__ void operator()(AccRef acc, int pm, int pn, int wr, int wc, int fr, int fq) const {
;     ...
;             for (int m = 0; m < 4; ++m) { bf16_t* rp = dst + (size_t)EPI_ROW(ai, m) * 1024;
; #pragma unroll
;                 for (int bj = 0; bj < 2; ++bj) { const int c0 = (pn & 3) * 256 + wc * 64 + bj * 32 + 8 * fq; u32x4 w; unsigned pk[4];
; #pragma unroll
;                     for (int n = 0; n < 2; ++n) { const f32x4 v = acc[ai][bj][m][n]; const f32x4 b = *(const f32x4*)(bias + c0 + 4 * n);
;                         f32x4 r;
; #pragma unroll
;                         for (int j = 0; j < 4; ++j) { const float z = b[j] + v[j]; const float sg = sigmoidf_(z);
;                             r[j] = sec == 0 ? sg * 0.60653065971f : (sec == 1 ? sg : v[j]); }
;                         pk[2 * n] = cvt_pk_bf16(r[0], r[1]); pk[2 * n + 1] = cvt_pk_bf16(r[2], r[3]); }
;                     w.x = pk[0]; w.y = pk[1]; w.z = pk[2]; w.w = pk[3]; *(u32x4*)(rp + c0) = w; } }
	v_lshl_add_u64 v[56:57], v[64:65], 0, v[120:121]
	v_cndmask_b32_e32 v59, v59, v63, vcc
	v_cvt_pk_bf16_f32 v63, v58, v59
	flat_store_dwordx4 v[56:57], v[60:63]
	s_nop 1
	v_add_f32_e32 v58, v52, v156
	v_mul_f32_e32 v58, 0xbfb8aa3b, v58
	v_exp_f32_e32 v58, v58
	s_nop 0
	v_add_f32_e32 v58, 1.0, v58
	v_rcp_f32_e32 v58, v58
	s_nop 0
	v_mul_f32_e32 v62, 0x3f1b4598, v58
	v_cndmask_b32_e64 v52, v52, v58, s[40:41]
	v_add_f32_e32 v58, v53, v157
	v_mul_f32_e32 v58, 0xbfb8aa3b, v58
	v_exp_f32_e32 v58, v58
	v_cndmask_b32_e32 v52, v52, v62, vcc
	v_add_f32_e32 v58, 1.0, v58
	v_rcp_f32_e32 v58, v58
	s_nop 0
	v_mul_f32_e32 v59, 0x3f1b4598, v58
	v_cndmask_b32_e64 v53, v53, v58, s[40:41]
	v_add_f32_e32 v58, v54, v158
	v_mul_f32_e32 v58, 0xbfb8aa3b, v58
	v_exp_f32_e32 v58, v58
	v_cndmask_b32_e32 v53, v53, v59, vcc
	v_cvt_pk_bf16_f32 v52, v52, v53
	v_add_f32_e32 v58, 1.0, v58
	v_rcp_f32_e32 v58, v58
	s_nop 0
	v_mul_f32_e32 v59, 0x3f1b4598, v58
	v_cndmask_b32_e64 v54, v54, v58, s[40:41]
	v_add_f32_e32 v58, v55, v159
	v_mul_f32_e32 v58, 0xbfb8aa3b, v58
	v_exp_f32_e32 v58, v58
	v_cndmask_b32_e32 v54, v54, v59, vcc
	v_add_f32_e32 v58, 1.0, v58
	v_rcp_f32_e32 v58, v58
	s_nop 0
	v_mul_f32_e32 v59, 0x3f1b4598, v58
	v_cndmask_b32_e64 v55, v55, v58, s[40:41]
	v_cndmask_b32_e32 v55, v55, v59, vcc
	v_cvt_pk_bf16_f32 v53, v54, v55
	v_add_f32_e32 v54, v48, v160
	v_mul_f32_e32 v54, 0xbfb8aa3b, v54
	v_exp_f32_e32 v54, v54
	s_nop 0
	v_add_f32_e32 v54, 1.0, v54
	v_rcp_f32_e32 v54, v54
	s_nop 0
	v_mul_f32_e32 v55, 0x3f1b4598, v54
	v_cndmask_b32_e64 v48, v48, v54, s[40:41]
	v_add_f32_e32 v54, v49, v161
	v_mul_f32_e32 v54, 0xbfb8aa3b, v54
	v_exp_f32_e32 v54, v54
	v_cndmask_b32_e32 v48, v48, v55, vcc
	v_add_f32_e32 v54, 1.0, v54
	v_rcp_f32_e32 v54, v54
	s_nop 0
	v_mul_f32_e32 v55, 0x3f1b4598, v54
	v_cndmask_b32_e64 v49, v49, v54, s[40:41]
	v_add_f32_e32 v54, v50, v162
	v_mul_f32_e32 v54, 0xbfb8aa3b, v54
	v_exp_f32_e32 v54, v54
	v_cndmask_b32_e32 v49, v49, v55, vcc
	v_add_f32_e32 v54, 1.0, v54
	v_rcp_f32_e32 v54, v54
	s_nop 0
	v_mul_f32_e32 v55, 0x3f1b4598, v54
	v_cndmask_b32_e64 v50, v50, v54, s[40:41]
	v_add_f32_e32 v54, v51, v163
	v_mul_f32_e32 v54, 0xbfb8aa3b, v54
	v_exp_f32_e32 v54, v54
	v_cndmask_b32_e32 v50, v50, v55, vcc
	v_add_f32_e32 v54, 1.0, v54
	v_rcp_f32_e32 v54, v54
	s_nop 0
	v_mul_f32_e32 v55, 0x3f1b4598, v54
	v_cndmask_b32_e64 v51, v51, v54, s[40:41]
	v_cndmask_b32_e32 v51, v51, v55, vcc
	v_cvt_pk_bf16_f32 v54, v48, v49
	v_cvt_pk_bf16_f32 v55, v50, v51
	flat_store_dwordx4 v[56:57], v[52:55] offset:64
	s_nop 1
	v_add_u32_e32 v48, 0x90, v132
	v_ashrrev_i32_e32 v49, 31, v48
	v_lshlrev_b64 v[48:49], 11, v[48:49]
	v_lshl_add_u64 v[48:49], s[20:21], 0, v[48:49]
	v_add_f32_e32 v50, v44, v148
	v_mul_f32_e32 v50, 0xbfb8aa3b, v50
	v_exp_f32_e32 v50, v50
	s_nop 0
	v_add_f32_e32 v50, 1.0, v50
	v_rcp_f32_e32 v50, v50
	s_nop 0
	v_mul_f32_e32 v54, 0x3f1b4598, v50
	v_cndmask_b32_e64 v44, v44, v50, s[40:41]
	v_add_f32_e32 v50, v45, v149
	v_mul_f32_e32 v50, 0xbfb8aa3b, v50
	v_exp_f32_e32 v50, v50
	v_cndmask_b32_e32 v44, v44, v54, vcc
	v_add_f32_e32 v50, 1.0, v50
	v_rcp_f32_e32 v50, v50
	s_nop 0
	v_mul_f32_e32 v51, 0x3f1b4598, v50
	v_cndmask_b32_e64 v45, v45, v50, s[40:41]
	v_add_f32_e32 v50, v46, v150
	v_mul_f32_e32 v50, 0xbfb8aa3b, v50
	v_exp_f32_e32 v50, v50
	v_cndmask_b32_e32 v45, v45, v51, vcc
	v_cvt_pk_bf16_f32 v44, v44, v45
	v_add_f32_e32 v50, 1.0, v50
	v_rcp_f32_e32 v50, v50
	s_nop 0
	v_mul_f32_e32 v51, 0x3f1b4598, v50
	v_cndmask_b32_e64 v46, v46, v50, s[40:41]
	v_add_f32_e32 v50, v47, v151
	v_mul_f32_e32 v50, 0xbfb8aa3b, v50
	v_exp_f32_e32 v50, v50
	v_cndmask_b32_e32 v46, v46, v51, vcc
	v_add_f32_e32 v50, 1.0, v50
	v_rcp_f32_e32 v50, v50
	s_nop 0
	v_mul_f32_e32 v51, 0x3f1b4598, v50
	v_cndmask_b32_e64 v47, v47, v50, s[40:41]
	v_cndmask_b32_e32 v47, v47, v51, vcc
	v_cvt_pk_bf16_f32 v45, v46, v47
	v_add_f32_e32 v46, v40, v152
	v_mul_f32_e32 v46, 0xbfb8aa3b, v46
	v_exp_f32_e32 v46, v46
	s_nop 0
	v_add_f32_e32 v46, 1.0, v46
	v_rcp_f32_e32 v46, v46
	s_nop 0
	v_mul_f32_e32 v47, 0x3f1b4598, v46
	v_cndmask_b32_e64 v40, v40, v46, s[40:41]
	v_add_f32_e32 v46, v41, v153
	v_mul_f32_e32 v46, 0xbfb8aa3b, v46
	v_exp_f32_e32 v46, v46
	v_cndmask_b32_e32 v40, v40, v47, vcc
	v_add_f32_e32 v46, 1.0, v46
	v_rcp_f32_e32 v46, v46
	s_nop 0
	v_mul_f32_e32 v47, 0x3f1b4598, v46
	v_cndmask_b32_e64 v41, v41, v46, s[40:41]
	v_add_f32_e32 v46, v42, v154
	v_mul_f32_e32 v46, 0xbfb8aa3b, v46
	v_exp_f32_e32 v46, v46
	v_cndmask_b32_e32 v41, v41, v47, vcc
	v_add_f32_e32 v46, 1.0, v46
	v_rcp_f32_e32 v46, v46
	s_nop 0
	v_mul_f32_e32 v47, 0x3f1b4598, v46
	v_cndmask_b32_e64 v42, v42, v46, s[40:41]
	v_add_f32_e32 v46, v43, v155
	v_mul_f32_e32 v46, 0xbfb8aa3b, v46
	v_exp_f32_e32 v46, v46
	v_cndmask_b32_e32 v42, v42, v47, vcc
	v_add_f32_e32 v46, 1.0, v46
	v_rcp_f32_e32 v46, v46
	s_nop 0
	v_mul_f32_e32 v47, 0x3f1b4598, v46
	v_cndmask_b32_e64 v43, v43, v46, s[40:41]
	v_cvt_pk_bf16_f32 v46, v40, v41
	v_lshl_add_u64 v[40:41], v[48:49], 0, v[120:121]
	v_cndmask_b32_e32 v43, v43, v47, vcc
	v_cvt_pk_bf16_f32 v47, v42, v43
	flat_store_dwordx4 v[40:41], v[44:47]
	s_nop 1
	v_add_f32_e32 v42, v36, v156
	v_mul_f32_e32 v42, 0xbfb8aa3b, v42
	v_exp_f32_e32 v42, v42
	s_nop 0
	v_add_f32_e32 v42, 1.0, v42
	v_rcp_f32_e32 v42, v42
	s_nop 0
	v_mul_f32_e32 v46, 0x3f1b4598, v42
	v_cndmask_b32_e64 v36, v36, v42, s[40:41]
	v_add_f32_e32 v42, v37, v157
	v_mul_f32_e32 v42, 0xbfb8aa3b, v42
	v_exp_f32_e32 v42, v42
	v_cndmask_b32_e32 v36, v36, v46, vcc
	v_add_f32_e32 v42, 1.0, v42
	v_rcp_f32_e32 v42, v42
	s_nop 0
	v_mul_f32_e32 v43, 0x3f1b4598, v42
	v_cndmask_b32_e64 v37, v37, v42, s[40:41]
	v_add_f32_e32 v42, v38, v158
	v_mul_f32_e32 v42, 0xbfb8aa3b, v42
; __device__ __forceinline__ unsigned cvt_pk_bf16(float lo, float hi) { unsigned r; asm volatile("v_cvt_pk_bf16_f32 %0, %1, %2" : "=v"(r) : "v"(lo), "v"(hi)); return r; }
; __device__ __forceinline__ float sigmoidf_(float x) { return __builtin_amdgcn_rcpf(1.0f + __builtin_amdgcn_exp2f(-1.44269504088896f * x)); }
;     __device__ __forceinline__ void operator()(AccRef acc, int pm, int pn, int wr, int wc, int fr, int fq) const {
;     ...
;             for (int m = 0; m < 4; ++m) { bf16_t* rp = dst + (size_t)EPI_ROW(ai, m) * 1024;
; #pragma unroll
;                 for (int bj = 0; bj < 2; ++bj) { const int c0 = (pn & 3) * 256 + wc * 64 + bj * 32 + 8 * fq; u32x4 w; unsigned pk[4];
; #pragma unroll
;                     for (int n = 0; n < 2; ++n) { const f32x4 v = acc[ai][bj][m][n]; const f32x4 b = *(const f32x4*)(bias + c0 + 4 * n);
;                         f32x4 r;
; #pragma unroll
;                         for (int j = 0; j < 4; ++j) { const float z = b[j] + v[j]; const float sg = sigmoidf_(z);
;                             r[j] = sec == 0 ? sg * 0.60653065971f : (sec == 1 ? sg : v[j]); }
;                         pk[2 * n] = cvt_pk_bf16(r[0], r[1]); pk[2 * n + 1] = cvt_pk_bf16(r[2], r[3]); }
;                     w.x = pk[0]; w.y = pk[1]; w.z = pk[2]; w.w = pk[3]; *(u32x4*)(rp + c0) = w; } }
	v_exp_f32_e32 v42, v42
	v_cndmask_b32_e32 v37, v37, v43, vcc
	v_cvt_pk_bf16_f32 v36, v36, v37
	v_add_f32_e32 v42, 1.0, v42
	v_rcp_f32_e32 v42, v42
	s_nop 0
	v_mul_f32_e32 v43, 0x3f1b4598, v42
	v_cndmask_b32_e64 v38, v38, v42, s[40:41]
	v_add_f32_e32 v42, v39, v159
	v_mul_f32_e32 v42, 0xbfb8aa3b, v42
	v_exp_f32_e32 v42, v42
	v_cndmask_b32_e32 v38, v38, v43, vcc
	v_add_f32_e32 v42, 1.0, v42
	v_rcp_f32_e32 v42, v42
	s_nop 0
	v_mul_f32_e32 v43, 0x3f1b4598, v42
	v_cndmask_b32_e64 v39, v39, v42, s[40:41]
	v_cndmask_b32_e32 v39, v39, v43, vcc
	v_cvt_pk_bf16_f32 v37, v38, v39
	v_add_f32_e32 v38, v32, v160
	v_mul_f32_e32 v38, 0xbfb8aa3b, v38
	v_exp_f32_e32 v38, v38
	s_nop 0
	v_add_f32_e32 v38, 1.0, v38
	v_rcp_f32_e32 v38, v38
	s_nop 0
	v_mul_f32_e32 v39, 0x3f1b4598, v38
	v_cndmask_b32_e64 v32, v32, v38, s[40:41]
	v_add_f32_e32 v38, v33, v161
	v_mul_f32_e32 v38, 0xbfb8aa3b, v38
	v_exp_f32_e32 v38, v38
	v_cndmask_b32_e32 v32, v32, v39, vcc
	v_add_f32_e32 v38, 1.0, v38
	v_rcp_f32_e32 v38, v38
	s_nop 0
	v_mul_f32_e32 v39, 0x3f1b4598, v38
	v_cndmask_b32_e64 v33, v33, v38, s[40:41]
	v_add_f32_e32 v38, v34, v162
	v_mul_f32_e32 v38, 0xbfb8aa3b, v38
	v_exp_f32_e32 v38, v38
	v_cndmask_b32_e32 v33, v33, v39, vcc
	v_add_f32_e32 v38, 1.0, v38
	v_rcp_f32_e32 v38, v38
	s_nop 0
	v_mul_f32_e32 v39, 0x3f1b4598, v38
	v_cndmask_b32_e64 v34, v34, v38, s[40:41]
	v_add_f32_e32 v38, v35, v163
	v_mul_f32_e32 v38, 0xbfb8aa3b, v38
	v_exp_f32_e32 v38, v38
	v_cndmask_b32_e32 v34, v34, v39, vcc
	v_add_f32_e32 v38, 1.0, v38
	v_rcp_f32_e32 v38, v38
	s_nop 0
	v_mul_f32_e32 v39, 0x3f1b4598, v38
	v_cndmask_b32_e64 v35, v35, v38, s[40:41]
	v_cndmask_b32_e32 v35, v35, v39, vcc
	v_cvt_pk_bf16_f32 v38, v32, v33
	v_cvt_pk_bf16_f32 v39, v34, v35
	flat_store_dwordx4 v[40:41], v[36:39] offset:64
	s_nop 1
	v_add_u32_e32 v32, 0xa0, v132
	v_ashrrev_i32_e32 v33, 31, v32
	v_lshlrev_b64 v[32:33], 11, v[32:33]
	v_lshl_add_u64 v[32:33], s[20:21], 0, v[32:33]
	v_add_f32_e32 v34, v28, v148
	v_mul_f32_e32 v34, 0xbfb8aa3b, v34
	v_exp_f32_e32 v34, v34
	s_nop 0
	v_add_f32_e32 v34, 1.0, v34
	v_rcp_f32_e32 v34, v34
	s_nop 0
	v_mul_f32_e32 v38, 0x3f1b4598, v34
	v_cndmask_b32_e64 v28, v28, v34, s[40:41]
	v_add_f32_e32 v34, v29, v149
	v_mul_f32_e32 v34, 0xbfb8aa3b, v34
	v_exp_f32_e32 v34, v34
	v_cndmask_b32_e32 v28, v28, v38, vcc
	v_add_f32_e32 v34, 1.0, v34
	v_rcp_f32_e32 v34, v34
	s_nop 0
	v_mul_f32_e32 v35, 0x3f1b4598, v34
	v_cndmask_b32_e64 v29, v29, v34, s[40:41]
	v_add_f32_e32 v34, v30, v150
	v_mul_f32_e32 v34, 0xbfb8aa3b, v34
	v_exp_f32_e32 v34, v34
	v_cndmask_b32_e32 v29, v29, v35, vcc
	v_cvt_pk_bf16_f32 v28, v28, v29
	v_add_f32_e32 v34, 1.0, v34
	v_rcp_f32_e32 v34, v34
	s_nop 0
	v_mul_f32_e32 v35, 0x3f1b4598, v34
	v_cndmask_b32_e64 v30, v30, v34, s[40:41]
	v_add_f32_e32 v34, v31, v151
	v_mul_f32_e32 v34, 0xbfb8aa3b, v34
	v_exp_f32_e32 v34, v34
	v_cndmask_b32_e32 v30, v30, v35, vcc
	v_add_f32_e32 v34, 1.0, v34
	v_rcp_f32_e32 v34, v34
	s_nop 0
	v_mul_f32_e32 v35, 0x3f1b4598, v34
	v_cndmask_b32_e64 v31, v31, v34, s[40:41]
	v_cndmask_b32_e32 v31, v31, v35, vcc
	v_cvt_pk_bf16_f32 v29, v30, v31
	v_add_f32_e32 v30, v24, v152
	v_mul_f32_e32 v30, 0xbfb8aa3b, v30
	v_exp_f32_e32 v30, v30
	s_nop 0
	v_add_f32_e32 v30, 1.0, v30
	v_rcp_f32_e32 v30, v30
	s_nop 0
	v_mul_f32_e32 v31, 0x3f1b4598, v30
	v_cndmask_b32_e64 v24, v24, v30, s[40:41]
	v_add_f32_e32 v30, v25, v153
	v_mul_f32_e32 v30, 0xbfb8aa3b, v30
	v_exp_f32_e32 v30, v30
	v_cndmask_b32_e32 v24, v24, v31, vcc
	v_add_f32_e32 v30, 1.0, v30
	v_rcp_f32_e32 v30, v30
	s_nop 0
	v_mul_f32_e32 v31, 0x3f1b4598, v30
	v_cndmask_b32_e64 v25, v25, v30, s[40:41]
	v_add_f32_e32 v30, v26, v154
	v_mul_f32_e32 v30, 0xbfb8aa3b, v30
	v_exp_f32_e32 v30, v30
	v_cndmask_b32_e32 v25, v25, v31, vcc
	v_add_f32_e32 v30, 1.0, v30
	v_rcp_f32_e32 v30, v30
	s_nop 0
	v_mul_f32_e32 v31, 0x3f1b4598, v30
	v_cndmask_b32_e64 v26, v26, v30, s[40:41]
	v_add_f32_e32 v30, v27, v155
	v_mul_f32_e32 v30, 0xbfb8aa3b, v30
	v_exp_f32_e32 v30, v30
	v_cndmask_b32_e32 v26, v26, v31, vcc
	v_add_f32_e32 v30, 1.0, v30
	v_rcp_f32_e32 v30, v30
	s_nop 0
	v_mul_f32_e32 v31, 0x3f1b4598, v30
	v_cndmask_b32_e64 v27, v27, v30, s[40:41]
	v_cvt_pk_bf16_f32 v30, v24, v25
	v_lshl_add_u64 v[24:25], v[32:33], 0, v[120:121]
	v_cndmask_b32_e32 v27, v27, v31, vcc
	v_cvt_pk_bf16_f32 v31, v26, v27
	flat_store_dwordx4 v[24:25], v[28:31]
	s_nop 1
	v_add_f32_e32 v26, v20, v156
	v_mul_f32_e32 v26, 0xbfb8aa3b, v26
	v_exp_f32_e32 v26, v26
	s_nop 0
	v_add_f32_e32 v26, 1.0, v26
	v_rcp_f32_e32 v26, v26
	s_nop 0
	v_mul_f32_e32 v30, 0x3f1b4598, v26
	v_cndmask_b32_e64 v20, v20, v26, s[40:41]
	v_add_f32_e32 v26, v21, v157
	v_mul_f32_e32 v26, 0xbfb8aa3b, v26
	v_exp_f32_e32 v26, v26
	v_cndmask_b32_e32 v20, v20, v30, vcc
	v_add_f32_e32 v26, 1.0, v26
	v_rcp_f32_e32 v26, v26
	s_nop 0
	v_mul_f32_e32 v27, 0x3f1b4598, v26
	v_cndmask_b32_e64 v21, v21, v26, s[40:41]
	v_add_f32_e32 v26, v22, v158
	v_mul_f32_e32 v26, 0xbfb8aa3b, v26
	v_exp_f32_e32 v26, v26
	v_cndmask_b32_e32 v21, v21, v27, vcc
	v_cvt_pk_bf16_f32 v20, v20, v21
	v_add_f32_e32 v26, 1.0, v26
	v_rcp_f32_e32 v26, v26
	s_nop 0
	v_mul_f32_e32 v27, 0x3f1b4598, v26
	v_cndmask_b32_e64 v22, v22, v26, s[40:41]
	v_add_f32_e32 v26, v23, v159
	v_mul_f32_e32 v26, 0xbfb8aa3b, v26
	v_exp_f32_e32 v26, v26
	v_cndmask_b32_e32 v22, v22, v27, vcc
	v_add_f32_e32 v26, 1.0, v26
	v_rcp_f32_e32 v26, v26
	s_nop 0
	v_mul_f32_e32 v27, 0x3f1b4598, v26
	v_cndmask_b32_e64 v23, v23, v26, s[40:41]
	v_cndmask_b32_e32 v23, v23, v27, vcc
	v_cvt_pk_bf16_f32 v21, v22, v23
	v_add_f32_e32 v22, v16, v160
	v_mul_f32_e32 v22, 0xbfb8aa3b, v22
	v_exp_f32_e32 v22, v22
	s_nop 0
	v_add_f32_e32 v22, 1.0, v22
	v_rcp_f32_e32 v22, v22
; __device__ __forceinline__ unsigned cvt_pk_bf16(float lo, float hi) { unsigned r; asm volatile("v_cvt_pk_bf16_f32 %0, %1, %2" : "=v"(r) : "v"(lo), "v"(hi)); return r; }
; __device__ __forceinline__ float sigmoidf_(float x) { return __builtin_amdgcn_rcpf(1.0f + __builtin_amdgcn_exp2f(-1.44269504088896f * x)); }
; #define WAIT_V(n) asm volatile("s_waitcnt vmcnt(" #n ")" ::: "memory")
; #define BAR __builtin_amdgcn_s_barrier()
; template <class Epi>
; __device__ __forceinline__ void gemm_phase(const bf16_t* __restrict__ A, int lda, const bf16_t* __restrict__ Bt, int ldb, int K, int nM, int nN, const Epi& epi, LAS unsigned char* lds, int wv) {
;     ...
;         if (!has_next) break;
; #pragma unroll
;         for (int a = 0; a < 2; ++a)
; #pragma unroll
;             for (int b = 0; b < 2; ++b)
; #pragma unroll
;                 for (int m = 0; m < 4; ++m)
; #pragma unroll
;                     for (int n = 0; n < 2; ++n) acc[a][b][m][n] = (f32x4){0.f, 0.f, 0.f, 0.f};
;         pm = npm; pn = npn; cA = nA; cB = nB;
;     }
;     WAIT_V(0);
;     if (wr == 0) BAR;
;     BAR;
;     __device__ __forceinline__ void operator()(AccRef acc, int pm, int pn, int wr, int wc, int fr, int fq) const {
;     ...
;             for (int m = 0; m < 4; ++m) { bf16_t* rp = dst + (size_t)EPI_ROW(ai, m) * 1024;
; #pragma unroll
;                 for (int bj = 0; bj < 2; ++bj) { const int c0 = (pn & 3) * 256 + wc * 64 + bj * 32 + 8 * fq; u32x4 w; unsigned pk[4];
; #pragma unroll
;                     for (int n = 0; n < 2; ++n) { const f32x4 v = acc[ai][bj][m][n]; const f32x4 b = *(const f32x4*)(bias + c0 + 4 * n);
;                         f32x4 r;
; #pragma unroll
;                         for (int j = 0; j < 4; ++j) { const float z = b[j] + v[j]; const float sg = sigmoidf_(z);
;                             r[j] = sec == 0 ? sg * 0.60653065971f : (sec == 1 ? sg : v[j]); }
;                         pk[2 * n] = cvt_pk_bf16(r[0], r[1]); pk[2 * n + 1] = cvt_pk_bf16(r[2], r[3]); }
;                     w.x = pk[0]; w.y = pk[1]; w.z = pk[2]; w.w = pk[3]; *(u32x4*)(rp + c0) = w; } }
	s_nop 0
	v_mul_f32_e32 v23, 0x3f1b4598, v22
	v_cndmask_b32_e64 v16, v16, v22, s[40:41]
	v_add_f32_e32 v22, v17, v161
	v_mul_f32_e32 v22, 0xbfb8aa3b, v22
	v_exp_f32_e32 v22, v22
	v_cndmask_b32_e32 v16, v16, v23, vcc
	v_add_f32_e32 v22, 1.0, v22
	v_rcp_f32_e32 v22, v22
	s_nop 0
	v_mul_f32_e32 v23, 0x3f1b4598, v22
	v_cndmask_b32_e64 v17, v17, v22, s[40:41]
	v_add_f32_e32 v22, v18, v162
	v_mul_f32_e32 v22, 0xbfb8aa3b, v22
	v_exp_f32_e32 v22, v22
	v_cndmask_b32_e32 v17, v17, v23, vcc
	v_add_f32_e32 v22, 1.0, v22
	v_rcp_f32_e32 v22, v22
	s_nop 0
	v_mul_f32_e32 v23, 0x3f1b4598, v22
	v_cndmask_b32_e64 v18, v18, v22, s[40:41]
	v_add_f32_e32 v22, v19, v163
	v_mul_f32_e32 v22, 0xbfb8aa3b, v22
	v_exp_f32_e32 v22, v22
	v_cndmask_b32_e32 v18, v18, v23, vcc
	v_add_f32_e32 v22, 1.0, v22
	v_rcp_f32_e32 v22, v22
	s_nop 0
	v_mul_f32_e32 v23, 0x3f1b4598, v22
	v_cndmask_b32_e64 v19, v19, v22, s[40:41]
	v_cndmask_b32_e32 v19, v19, v23, vcc
	v_cvt_pk_bf16_f32 v22, v16, v17
	v_cvt_pk_bf16_f32 v23, v18, v19
	flat_store_dwordx4 v[24:25], v[20:23] offset:64
	s_nop 1
	v_add_u32_e32 v16, 0xb0, v132
	v_ashrrev_i32_e32 v17, 31, v16
	v_lshlrev_b64 v[16:17], 11, v[16:17]
	v_lshl_add_u64 v[16:17], s[20:21], 0, v[16:17]
	v_readlane_b32 s20, v254, 59
	v_readlane_b32 s21, v254, 60
	v_add_f32_e32 v18, v12, v148
	v_mul_f32_e32 v18, 0xbfb8aa3b, v18
	v_exp_f32_e32 v18, v18
	s_nop 0
	v_add_f32_e32 v18, 1.0, v18
	v_rcp_f32_e32 v18, v18
	s_nop 0
	v_mul_f32_e32 v22, 0x3f1b4598, v18
	v_cndmask_b32_e64 v12, v12, v18, s[40:41]
	v_add_f32_e32 v18, v13, v149
	v_mul_f32_e32 v18, 0xbfb8aa3b, v18
	v_exp_f32_e32 v18, v18
	v_cndmask_b32_e32 v12, v12, v22, vcc
	v_add_f32_e32 v18, 1.0, v18
	v_rcp_f32_e32 v18, v18
	s_nop 0
	v_mul_f32_e32 v19, 0x3f1b4598, v18
	v_cndmask_b32_e64 v13, v13, v18, s[40:41]
	v_add_f32_e32 v18, v14, v150
	v_mul_f32_e32 v18, 0xbfb8aa3b, v18
	v_exp_f32_e32 v18, v18
	v_cndmask_b32_e32 v13, v13, v19, vcc
	v_cvt_pk_bf16_f32 v12, v12, v13
	v_add_f32_e32 v18, 1.0, v18
	v_rcp_f32_e32 v18, v18
	s_nop 0
	v_mul_f32_e32 v19, 0x3f1b4598, v18
	v_cndmask_b32_e64 v14, v14, v18, s[40:41]
	v_add_f32_e32 v18, v15, v151
	v_mul_f32_e32 v18, 0xbfb8aa3b, v18
	v_exp_f32_e32 v18, v18
	v_cndmask_b32_e32 v14, v14, v19, vcc
	v_add_f32_e32 v18, 1.0, v18
	v_rcp_f32_e32 v18, v18
	s_nop 0
	v_mul_f32_e32 v19, 0x3f1b4598, v18
	v_cndmask_b32_e64 v15, v15, v18, s[40:41]
	v_cndmask_b32_e32 v15, v15, v19, vcc
	v_cvt_pk_bf16_f32 v13, v14, v15
	v_add_f32_e32 v14, v8, v152
	v_mul_f32_e32 v14, 0xbfb8aa3b, v14
	v_exp_f32_e32 v14, v14
	s_nop 0
	v_add_f32_e32 v14, 1.0, v14
	v_rcp_f32_e32 v14, v14
	s_nop 0
	v_mul_f32_e32 v15, 0x3f1b4598, v14
	v_cndmask_b32_e64 v8, v8, v14, s[40:41]
	v_add_f32_e32 v14, v9, v153
	v_mul_f32_e32 v14, 0xbfb8aa3b, v14
	v_exp_f32_e32 v14, v14
	v_cndmask_b32_e32 v8, v8, v15, vcc
	v_add_f32_e32 v14, 1.0, v14
	v_rcp_f32_e32 v14, v14
	s_nop 0
	v_mul_f32_e32 v15, 0x3f1b4598, v14
	v_cndmask_b32_e64 v9, v9, v14, s[40:41]
	v_add_f32_e32 v14, v10, v154
	v_mul_f32_e32 v14, 0xbfb8aa3b, v14
	v_exp_f32_e32 v14, v14
	v_cndmask_b32_e32 v9, v9, v15, vcc
	v_add_f32_e32 v14, 1.0, v14
	v_rcp_f32_e32 v14, v14
	s_nop 0
	v_mul_f32_e32 v15, 0x3f1b4598, v14
	v_cndmask_b32_e64 v10, v10, v14, s[40:41]
	v_add_f32_e32 v14, v11, v155
	v_mul_f32_e32 v14, 0xbfb8aa3b, v14
	v_exp_f32_e32 v14, v14
	v_cndmask_b32_e32 v10, v10, v15, vcc
	v_add_f32_e32 v14, 1.0, v14
	v_rcp_f32_e32 v14, v14
	s_nop 0
	v_mul_f32_e32 v15, 0x3f1b4598, v14
	v_cndmask_b32_e64 v11, v11, v14, s[40:41]
	v_cvt_pk_bf16_f32 v14, v8, v9
	v_lshl_add_u64 v[8:9], v[16:17], 0, v[120:121]
	v_cndmask_b32_e32 v11, v11, v15, vcc
	v_cvt_pk_bf16_f32 v15, v10, v11
	flat_store_dwordx4 v[8:9], v[12:15]
	s_nop 1
	v_add_f32_e32 v10, v4, v156
	v_mul_f32_e32 v10, 0xbfb8aa3b, v10
	v_exp_f32_e32 v10, v10
	s_nop 0
	v_add_f32_e32 v10, 1.0, v10
	v_rcp_f32_e32 v10, v10
	s_nop 0
	v_mul_f32_e32 v14, 0x3f1b4598, v10
	v_cndmask_b32_e64 v4, v4, v10, s[40:41]
	v_add_f32_e32 v10, v5, v157
	v_mul_f32_e32 v10, 0xbfb8aa3b, v10
	v_exp_f32_e32 v10, v10
	v_cndmask_b32_e32 v4, v4, v14, vcc
	v_add_f32_e32 v10, 1.0, v10
	v_rcp_f32_e32 v10, v10
	s_nop 0
	v_mul_f32_e32 v11, 0x3f1b4598, v10
	v_cndmask_b32_e64 v5, v5, v10, s[40:41]
	v_add_f32_e32 v10, v6, v158
	v_mul_f32_e32 v10, 0xbfb8aa3b, v10
	v_exp_f32_e32 v10, v10
	v_cndmask_b32_e32 v5, v5, v11, vcc
	v_cvt_pk_bf16_f32 v4, v4, v5
	v_add_f32_e32 v10, 1.0, v10
	v_rcp_f32_e32 v10, v10
	s_nop 0
	v_mul_f32_e32 v11, 0x3f1b4598, v10
	v_cndmask_b32_e64 v6, v6, v10, s[40:41]
	v_add_f32_e32 v10, v7, v159
	v_mul_f32_e32 v10, 0xbfb8aa3b, v10
	v_exp_f32_e32 v10, v10
	v_cndmask_b32_e32 v6, v6, v11, vcc
	v_add_f32_e32 v10, 1.0, v10
	v_rcp_f32_e32 v10, v10
	s_nop 0
	v_mul_f32_e32 v11, 0x3f1b4598, v10
	v_cndmask_b32_e64 v7, v7, v10, s[40:41]
	v_cndmask_b32_e32 v7, v7, v11, vcc
	v_cvt_pk_bf16_f32 v5, v6, v7
	v_add_f32_e32 v6, v0, v160
	v_mul_f32_e32 v6, 0xbfb8aa3b, v6
	v_exp_f32_e32 v6, v6
	s_nop 0
	v_add_f32_e32 v6, 1.0, v6
	v_rcp_f32_e32 v6, v6
	s_nop 0
	v_mul_f32_e32 v7, 0x3f1b4598, v6
	v_cndmask_b32_e64 v0, v0, v6, s[40:41]
	v_add_f32_e32 v6, v1, v161
	v_mul_f32_e32 v6, 0xbfb8aa3b, v6
	v_exp_f32_e32 v6, v6
	v_cndmask_b32_e32 v0, v0, v7, vcc
	v_add_f32_e32 v6, 1.0, v6
	v_rcp_f32_e32 v6, v6
	s_nop 0
	v_mul_f32_e32 v7, 0x3f1b4598, v6
	v_cndmask_b32_e64 v1, v1, v6, s[40:41]
	v_add_f32_e32 v6, v2, v162
	v_mul_f32_e32 v6, 0xbfb8aa3b, v6
	v_exp_f32_e32 v6, v6
	v_cndmask_b32_e32 v1, v1, v7, vcc
	v_add_f32_e32 v6, 1.0, v6
	v_rcp_f32_e32 v6, v6
	s_nop 0
	v_mul_f32_e32 v7, 0x3f1b4598, v6
	v_cndmask_b32_e64 v2, v2, v6, s[40:41]
	v_add_f32_e32 v6, v3, v163
	v_mul_f32_e32 v6, 0xbfb8aa3b, v6
	v_exp_f32_e32 v6, v6
	v_cndmask_b32_e32 v2, v2, v7, vcc
	v_add_f32_e32 v6, 1.0, v6
	v_rcp_f32_e32 v6, v6
	s_nop 0
	v_mul_f32_e32 v7, 0x3f1b4598, v6
	v_cndmask_b32_e64 v3, v3, v6, s[40:41]
	v_readlane_b32 s40, v254, 57
	v_cndmask_b32_e32 v3, v3, v7, vcc
	s_and_b64 vcc, exec, s[20:21]
	v_readlane_b32 s41, v254, 58
	s_mov_b64 s[20:21], s[48:49]
	v_cvt_pk_bf16_f32 v6, v0, v1
	v_cvt_pk_bf16_f32 v7, v2, v3
	flat_store_dwordx4 v[8:9], v[4:7] offset:64
	s_nop 1
	s_cbranch_vccz .LBB0_316
	v_readlane_b32 s8, v253, 10
	s_waitcnt vmcnt(0)
	v_readlane_b32 s9, v253, 11
	s_andn2_b64 vcc, exec, s[8:9]
	s_cbranch_vccnz .LBB0_323
	s_barrier

; #define LAS __attribute__((address_space(3)))
; template <int NDB, class MaskF> ...
;     ...
;     for (int ks = 0; ks < 2; ++ks)
; #pragma unroll
;         for (int kb = 0; kb < 4; ++kb)
; #pragma unroll
;             for (int qb = 0; qb < 2; ++qb)
;                 s[kb][qb] = __builtin_amdgcn_mfma_f32_16x16x32_bf16(kf[kb][ks], Qf[qb][ks], ks == 0 ? (f32x4){0.f, 0.f, 0.f, 0.f} : s[kb][qb], 0, 0, 0);
;     bf16x8 vf0[NDB], vf1[NDB];
; #pragma unroll
;     for (int db = 0; db < NDB; ++db) {
;         vf0[db] = *(const LAS bf16x8*)(Vl + (db * 16 + fr) * vstride + (8 * fq) * 2);
;     }
;     if (domask) {
; #pragma unroll
;         for (int kb = 0; kb < 4; ++kb)
; #pragma unroll
;             for (int qb = 0; qb < 2; ++qb)
; #pragma unroll
;                 for (int j = 0; j < 4; ++j) if (!mask(kb * 16 + 4 * fq + j, qb * 16 + fr)) s[kb][qb][j] = negbig;
;     }
;     ...
;     for (int db = 0; db < NDB; ++db) {
;         vf1[db] = *(const LAS bf16x8*)(Vl + (db * 16 + fr) * vstride + (32 + 8 * fq) * 2);
;     }
.LBB0_1959:
	s_waitcnt lgkmcnt(0)
	v_mfma_f32_16x16x32_bf16 v[128:131], v[32:35], v[0:3], 0
	v_add_u32_e32 v249, s81, v243
	v_mfma_f32_16x16x32_bf16 v[132:135], v[32:35], v[8:11], 0
	s_add_i32 s31, s82, 63
	v_xor_b32_e32 v244, 64, v249
	s_cmp_le_i32 s31, s72
	v_mfma_f32_16x16x32_bf16 v[140:143], v[40:43], v[8:11], 0
	s_mov_b32 s31, 0xfffffffff149f2ca
	v_mfma_f32_16x16x32_bf16 v[144:147], v[48:51], v[0:3], 0
	v_mfma_f32_16x16x32_bf16 v[148:151], v[48:51], v[8:11], 0
	v_mfma_f32_16x16x32_bf16 v[152:155], v[56:59], v[0:3], 0
	v_mfma_f32_16x16x32_bf16 v[160:163], v[56:59], v[8:11], 0
	v_mfma_f32_16x16x32_bf16 v[180:183], v[36:39], v[4:7], v[128:131]
	v_mfma_f32_16x16x32_bf16 v[156:159], v[36:39], v[12:15], v[132:135]
	v_mfma_f32_16x16x32_bf16 v[168:171], v[44:47], v[12:15], v[140:143]
	v_mfma_f32_16x16x32_bf16 v[188:191], v[52:55], v[4:7], v[144:147]
	v_mfma_f32_16x16x32_bf16 v[132:135], v[52:55], v[12:15], v[148:151]
	v_mfma_f32_16x16x32_bf16 v[184:187], v[60:63], v[4:7], v[152:155]
	v_mfma_f32_16x16x32_bf16 v[128:131], v[60:63], v[12:15], v[160:163]
	s_nop 2
	ds_read_b128 v[160:163], v249
	ds_read_b128 v[176:179], v249 offset:2048
	ds_read_b128 v[172:175], v249 offset:4096
	ds_read_b128 v[164:167], v249 offset:6144
	ds_read_b128 v[152:155], v249 offset:8192
	ds_read_b128 v[148:151], v249 offset:10240
	ds_read_b128 v[144:147], v249 offset:12288
	ds_read_b128 v[140:143], v249 offset:14336
	ds_read_b128 v[16:19], v244 offset:2048
	ds_read_b128 v[20:23], v244 offset:4096
	ds_read_b128 v[24:27], v244 offset:6144
	ds_read_b128 v[28:31], v244
	v_mfma_f32_16x16x32_bf16 v[136:139], v[40:43], v[0:3], 0
	v_mfma_f32_16x16x32_bf16 v[136:139], v[44:47], v[4:7], v[136:139]
	s_cbranch_scc1 .LBB0_1961
	v_add_u32_e32 v203, s82, v233
	v_cmp_gt_i32_e32 vcc, v203, v195
	v_mov_b32_e32 v202, s31
	v_cmp_lt_i32_e64 s[38:39], v203, v195
	v_cndmask_b32_e32 v202, v180, v202, vcc
	v_mov_b32_e32 v204, s31
	v_add_u32_e32 v205, 2, v203
	v_cndmask_b32_e64 v180, v202, v180, s[38:39]
	v_cndmask_b32_e64 v181, v204, v181, s[38:39]
	v_cmp_gt_i32_e64 s[38:39], v205, v195
	v_add_u32_e32 v206, 3, v203
	v_mov_b32_e32 v202, s31
	v_cndmask_b32_e64 v182, v182, v204, s[38:39]
	v_cmp_gt_i32_e64 s[38:39], v206, v195
	v_add_u32_e32 v207, 19, v203
	v_add_u32_e32 v208, 35, v203
	v_cndmask_b32_e64 v183, v183, v204, s[38:39]
	v_cmp_gt_i32_e64 s[38:39], v203, v197
	s_nop 1
	v_cndmask_b32_e64 v202, v156, v202, s[38:39]
	v_cmp_lt_i32_e64 s[38:39], v203, v197
	s_nop 1
	v_cndmask_b32_e64 v156, v202, v156, s[38:39]
	v_cndmask_b32_e64 v157, v204, v157, s[38:39]
	v_cmp_gt_i32_e64 s[38:39], v205, v197
	v_add_u32_e32 v202, 16, v203
	v_add_u32_e32 v205, 17, v203
	v_cndmask_b32_e64 v158, v158, v204, s[38:39]
	v_cmp_gt_i32_e64 s[38:39], v206, v197
	v_add_u32_e32 v206, 18, v203
	s_nop 0
	v_cndmask_b32_e64 v159, v159, v204, s[38:39]
	v_cmp_gt_i32_e64 s[38:39], v202, v195
	v_mov_b32_e32 v202, s31
	v_cndmask_b32_e32 v168, v168, v202, vcc
	v_cmp_gt_i32_e32 vcc, v205, v197
	v_cndmask_b32_e64 v136, v136, v202, s[38:39]
	v_cmp_gt_i32_e64 s[38:39], v205, v195
	v_cndmask_b32_e32 v169, v169, v204, vcc
	v_cmp_gt_i32_e32 vcc, v206, v197
	v_add_u32_e32 v205, 32, v203
	v_cndmask_b32_e64 v137, v137, v204, s[38:39]
	v_cndmask_b32_e32 v170, v170, v204, vcc
	v_cmp_gt_i32_e32 vcc, v207, v197
	v_cmp_gt_i32_e64 s[38:39], v206, v195
	v_add_u32_e32 v206, 33, v203
	v_cndmask_b32_e32 v171, v171, v204, vcc
	v_cmp_gt_i32_e32 vcc, v205, v195
	v_cndmask_b32_e64 v138, v138, v204, s[38:39]
	v_cmp_gt_i32_e64 s[38:39], v207, v195
	v_cndmask_b32_e32 v188, v188, v202, vcc
	v_cmp_gt_i32_e32 vcc, v206, v195
	v_add_u32_e32 v207, 34, v203
	v_cndmask_b32_e64 v139, v139, v204, s[38:39]
	v_cndmask_b32_e32 v189, v189, v204, vcc
	v_cmp_gt_i32_e32 vcc, v207, v195
	s_nop 1
	v_cndmask_b32_e32 v190, v190, v204, vcc
	v_cmp_gt_i32_e32 vcc, v208, v195
	s_nop 1
	v_cndmask_b32_e32 v191, v191, v204, vcc
	v_cmp_gt_i32_e32 vcc, v205, v197
	v_add_u32_e32 v205, 48, v203
	s_nop 0
	v_cndmask_b32_e32 v132, v132, v202, vcc
	v_cmp_gt_i32_e32 vcc, v206, v197
	v_add_u32_e32 v206, 49, v203
	s_nop 0
	v_cndmask_b32_e32 v133, v133, v204, vcc
	v_cmp_gt_i32_e32 vcc, v207, v197
	v_add_u32_e32 v207, 50, v203
	v_add_u32_e32 v203, 51, v203
	v_cndmask_b32_e32 v134, v134, v204, vcc
	v_cmp_gt_i32_e32 vcc, v208, v197
	s_nop 1
	v_cndmask_b32_e32 v135, v135, v204, vcc
	v_cmp_gt_i32_e32 vcc, v205, v195
	s_nop 1
	v_cndmask_b32_e32 v184, v184, v202, vcc
	v_cmp_gt_i32_e32 vcc, v206, v195
	s_nop 1
	v_cndmask_b32_e32 v185, v185, v204, vcc
	v_cmp_gt_i32_e32 vcc, v207, v195
	s_nop 1
	v_cndmask_b32_e32 v186, v186, v204, vcc
	v_cmp_gt_i32_e32 vcc, v203, v195
	s_nop 1
	v_cndmask_b32_e32 v187, v187, v204, vcc
	v_cmp_gt_i32_e32 vcc, v205, v197
	s_nop 1
	v_cndmask_b32_e32 v128, v128, v202, vcc
	v_cmp_gt_i32_e32 vcc, v206, v197
	s_nop 1
	v_cndmask_b32_e32 v129, v129, v204, vcc
	v_cmp_gt_i32_e32 vcc, v207, v197
	s_nop 1
	v_cndmask_b32_e32 v130, v130, v204, vcc
	v_cmp_gt_i32_e32 vcc, v203, v197
	s_nop 1
	v_cndmask_b32_e32 v131, v131, v204, vcc
; #define LAS __attribute__((address_space(3)))
; __device__ __forceinline__ unsigned cvt_pk_bf16(float lo, float hi) { unsigned r; asm volatile("v_cvt_pk_bf16_f32 %0, %1, %2" : "=v"(r) : "v"(lo), "v"(hi)); return r; }
; __device__ __forceinline__ float fexp2(float x) { return __builtin_amdgcn_exp2f(x); }
; template <int NDB, class MaskF> ...
;     ...
;     for (int qb = 0; qb < 2; ++qb) {
;         float ps = 0.f;
; #pragma unroll
;         for (int kb = 0; kb < 4; ++kb)
; #pragma unroll
;             for (int j = 0; j < 4; ++j) { const float p = fexp2(__builtin_fmaf(s[kb][qb][j], c2, -coff)); s[kb][qb][j] = p; ps += p; }
;         lrow[qb] += ps;
; #pragma unroll
;         for (int st = 0; st < 2; ++st) { u32x4 w;
;             w.x = cvt_pk_bf16(s[2 * st][qb][0], s[2 * st][qb][1]); w.y = cvt_pk_bf16(s[2 * st][qb][2], s[2 * st][qb][3]);
;             w.z = cvt_pk_bf16(s[2 * st + 1][qb][0], s[2 * st + 1][qb][1]); w.w = cvt_pk_bf16(s[2 * st + 1][qb][2], s[2 * st + 1][qb][3]);
;             Pf[qb][st] = __builtin_bit_cast(bf16x8, w); }
;     }
; #pragma unroll
;     for (int db = 0; db < NDB; ++db) {
; #pragma unroll
;         for (int qb = 0; qb < 2; ++qb) oacc[db][qb] = __builtin_amdgcn_mfma_f32_16x16x32_bf16(vf0[db], Pf[qb][0], oacc[db][qb], 0, 0, 0);
;     }
; #pragma unroll
;     for (int db = 0; db < NDB; ++db) {
;         vf1[db] = *(const LAS bf16x8*)(Vl + (db * 16 + fr) * vstride + (32 + 8 * fq) * 2);
;     }
;     if (has_next) {
; #pragma unroll
;         for (int kb = 0; kb < 4; ++kb) {
;             kf[kb][0] = *(const LAS bf16x8*)(Knext + (kb * 16 + fr) * kstride + fq * 16);
;             kf[kb][1] = *(const LAS bf16x8*)(Knext + (kb * 16 + fr) * kstride + 64 + fq * 16);
;         }
;     }
; #pragma unroll
;     for (int db = 0; db < NDB; ++db) {
; #pragma unroll
;         for (int qb = 0; qb < 2; ++qb) oacc[db][qb] = __builtin_amdgcn_mfma_f32_16x16x32_bf16(vf1[db], Pf[qb][1], oacc[db][qb], 0, 0, 0);
;     }
.LBB0_1961:
	v_mov_b32_e32 v223, s8
	s_nop 5
	v_fma_f32 v136, v136, s65, -v223
	v_exp_f32_e32 v207, v136
	v_fma_f32 v136, v137, s65, -v223
	v_fma_f32 v180, v180, s65, -v223
	v_exp_f32_e32 v209, v136
	v_fma_f32 v136, v138, s65, -v223
	v_exp_f32_e32 v203, v180
	v_fma_f32 v180, v181, s65, -v223
	v_exp_f32_e32 v211, v136
	v_fma_f32 v136, v139, s65, -v223
	v_exp_f32_e32 v181, v180
	v_fma_f32 v180, v182, s65, -v223
	v_exp_f32_e32 v213, v136
	v_fma_f32 v136, v188, s65, -v223
	v_fma_f32 v156, v156, s65, -v223
	v_exp_f32_e32 v205, v180
	v_fma_f32 v180, v183, s65, -v223
	v_exp_f32_e32 v215, v136
	v_fma_f32 v136, v189, s65, -v223
	v_exp_f32_e32 v202, v156
	v_fma_f32 v156, v157, s65, -v223
	v_exp_f32_e32 v183, v180
	v_exp_f32_e32 v189, v136
	v_fma_f32 v136, v190, s65, -v223
	v_exp_f32_e32 v180, v156
	v_fma_f32 v156, v158, s65, -v223
	v_exp_f32_e32 v217, v136
	v_fma_f32 v136, v191, s65, -v223
	v_exp_f32_e32 v204, v156
	v_fma_f32 v156, v159, s65, -v223
	v_exp_f32_e32 v191, v136
	v_fma_f32 v136, v184, s65, -v223
	v_exp_f32_e32 v182, v156
	v_fma_f32 v156, v168, s65, -v223
	v_fma_f32 v132, v132, s65, -v223
	v_fma_f32 v128, v128, s65, -v223
	v_exp_f32_e32 v219, v136
	v_fma_f32 v136, v185, s65, -v223
	v_exp_f32_e32 v206, v156
	v_fma_f32 v156, v169, s65, -v223
	v_exp_f32_e32 v214, v132
	v_fma_f32 v132, v133, s65, -v223
	v_exp_f32_e32 v218, v128
	v_fma_f32 v128, v129, s65, -v223
	v_exp_f32_e32 v185, v136
	v_fma_f32 v136, v186, s65, -v223
	v_exp_f32_e32 v208, v156
	v_fma_f32 v156, v170, s65, -v223
	v_exp_f32_e32 v188, v132
	v_fma_f32 v132, v134, s65, -v223
	v_exp_f32_e32 v184, v128
	v_fma_f32 v128, v130, s65, -v223
	v_exp_f32_e32 v221, v136
	v_fma_f32 v136, v187, s65, -v223
	v_exp_f32_e32 v210, v156
	v_fma_f32 v156, v171, s65, -v223
	v_exp_f32_e32 v216, v132
	v_fma_f32 v132, v135, s65, -v223
	v_exp_f32_e32 v220, v128
	v_fma_f32 v128, v131, s65, -v223
	v_exp_f32_e32 v187, v136
	v_cvt_pk_bf16_f32 v224, v203, v181
	v_cvt_pk_bf16_f32 v225, v205, v183
	v_cvt_pk_bf16_f32 v226, v207, v209
	v_cvt_pk_bf16_f32 v227, v211, v213
	v_cvt_pk_bf16_f32 v136, v215, v189
	v_cvt_pk_bf16_f32 v137, v217, v191
	v_cvt_pk_bf16_f32 v138, v219, v185
	v_cvt_pk_bf16_f32 v139, v221, v187
	v_exp_f32_e32 v212, v156
	v_cvt_pk_bf16_f32 v228, v202, v180
	s_waitcnt lgkmcnt(0)
	v_mfma_f32_16x16x32_bf16 v[124:127], v[160:163], v[224:227], v[124:127]
	v_cvt_pk_bf16_f32 v229, v204, v182
	v_cvt_pk_bf16_f32 v230, v206, v208
	v_cvt_pk_bf16_f32 v231, v210, v212
	v_mfma_f32_16x16x32_bf16 v[112:115], v[164:167], v[224:227], v[112:115]
	v_exp_f32_e32 v190, v132
	v_exp_f32_e32 v186, v128
	v_cvt_pk_bf16_f32 v128, v214, v188
	v_mfma_f32_16x16x32_bf16 v[96:99], v[160:163], v[228:231], v[96:99]
	v_cvt_pk_bf16_f32 v129, v216, v190
	v_cvt_pk_bf16_f32 v130, v218, v184
	v_cvt_pk_bf16_f32 v131, v220, v186
	v_mfma_f32_16x16x32_bf16 v[80:83], v[164:167], v[228:231], v[80:83]
	s_cmp_lt_u32 s30, s94
	s_cselect_b64 s[38:39], -1, 0
	s_add_i32 s31, s82, 64
	v_mfma_f32_16x16x32_bf16 v[108:111], v[152:155], v[224:227], v[108:111]
	s_cmp_le_i32 s31, s95
	s_cselect_b64 vcc, -1, 0
	s_and_b64 s[38:39], s[38:39], vcc
	v_mfma_f32_16x16x32_bf16 v[68:71], v[152:155], v[228:231], v[68:71]
	s_andn2_b64 vcc, exec, s[38:39]
	v_mfma_f32_16x16x32_bf16 v[104:107], v[148:151], v[224:227], v[104:107]
	v_mfma_f32_16x16x32_bf16 v[72:75], v[148:151], v[228:231], v[72:75]
	v_mfma_f32_16x16x32_bf16 v[92:95], v[144:147], v[224:227], v[92:95]
	v_mfma_f32_16x16x32_bf16 v[76:79], v[144:147], v[228:231], v[76:79]
	ds_read_b128 v[152:155], v244 offset:8192
	ds_read_b128 v[148:151], v244 offset:10240
	ds_read_b128 v[144:147], v244 offset:12288
	ds_read_b128 v[132:135], v244 offset:14336
	v_mfma_f32_16x16x32_bf16 v[120:123], v[176:179], v[224:227], v[120:123]
	v_mfma_f32_16x16x32_bf16 v[88:91], v[176:179], v[228:231], v[88:91]
	v_mfma_f32_16x16x32_bf16 v[116:119], v[172:175], v[224:227], v[116:119]
	v_mfma_f32_16x16x32_bf16 v[84:87], v[172:175], v[228:231], v[84:87]
	v_mfma_f32_16x16x32_bf16 v[100:103], v[140:143], v[224:227], v[100:103]
	v_mfma_f32_16x16x32_bf16 v[64:67], v[140:143], v[228:231], v[64:67]
.LBB0_1963:
	v_pk_add_f32 v[140:141], v[202:203], 0 op_sel_hi:[1,0]
	v_mfma_f32_16x16x32_bf16 v[124:127], v[28:31], v[136:139], v[124:127]
	v_add_f32_e64 v140, v180, v140
	v_add_f32_e64 v141, v181, v141
	v_pk_add_f32 v[140:141], v[204:205], v[140:141]
	v_mfma_f32_16x16x32_bf16 v[96:99], v[28:31], v[128:131], v[96:99]
	v_add_f32_e64 v140, v182, v140
	v_add_f32_e64 v141, v183, v141
	v_pk_add_f32 v[140:141], v[206:207], v[140:141]
	v_mfma_f32_16x16x32_bf16 v[120:123], v[16:19], v[136:139], v[120:123]
	v_add_f32_e64 v140, v208, v140
	v_add_f32_e64 v141, v209, v141
	v_pk_add_f32 v[140:141], v[210:211], v[140:141]
	v_mfma_f32_16x16x32_bf16 v[88:91], v[16:19], v[128:131], v[88:91]
	v_add_f32_e64 v140, v212, v140
	v_add_f32_e64 v141, v213, v141
	v_pk_add_f32 v[140:141], v[214:215], v[140:141]
	v_mfma_f32_16x16x32_bf16 v[116:119], v[20:23], v[136:139], v[116:119]
	v_add_f32_e64 v140, v188, v140
	v_add_f32_e64 v141, v189, v141
	v_pk_add_f32 v[140:141], v[216:217], v[140:141]
	v_mfma_f32_16x16x32_bf16 v[84:87], v[20:23], v[128:131], v[84:87]
	v_add_f32_e64 v140, v190, v140
	v_add_f32_e64 v141, v191, v141
	v_pk_add_f32 v[140:141], v[218:219], v[140:141]
	v_mfma_f32_16x16x32_bf16 v[112:115], v[24:27], v[136:139], v[112:115]
	v_add_f32_e64 v140, v184, v140
	v_add_f32_e64 v141, v185, v141
	v_pk_add_f32 v[140:141], v[220:221], v[140:141]
	v_mfma_f32_16x16x32_bf16 v[80:83], v[24:27], v[128:131], v[80:83]
	v_add_f32_e64 v140, v186, v140
	v_add_f32_e64 v141, v187, v141
	v_pk_add_f32 v[198:199], v[198:199], v[140:141]
	s_waitcnt lgkmcnt(0)
	v_mfma_f32_16x16x32_bf16 v[108:111], v[152:155], v[136:139], v[108:111]
	v_mfma_f32_16x16x32_bf16 v[68:71], v[152:155], v[128:131], v[68:71]
	v_mfma_f32_16x16x32_bf16 v[104:107], v[148:151], v[136:139], v[104:107]
	v_mfma_f32_16x16x32_bf16 v[72:75], v[148:151], v[128:131], v[72:75]
	v_mfma_f32_16x16x32_bf16 v[92:95], v[144:147], v[136:139], v[92:95]
	v_mfma_f32_16x16x32_bf16 v[76:79], v[144:147], v[128:131], v[76:79]
	v_mfma_f32_16x16x32_bf16 v[100:103], v[132:135], v[136:139], v[100:103]
	v_mfma_f32_16x16x32_bf16 v[64:67], v[132:135], v[128:131], v[64:67]
	s_cbranch_vccnz .Lat_end
	s_add_i32 s73, s81, 0x8000
	s_and_b32 s73, s73, 0x18000
	v_add_u32_e32 v245, s73, v242
	v_xor_b32_e32 v246, 64, v245
	ds_read_b128 v[32:35], v245
	ds_read_b128 v[36:39], v246
	ds_read_b128 v[40:43], v245 offset:4096
	ds_read_b128 v[44:47], v246 offset:4096
	ds_read_b128 v[48:51], v245 offset:8192
	ds_read_b128 v[52:55], v246 offset:8192
	ds_read_b128 v[56:59], v245 offset:12288
	ds_read_b128 v[60:63], v246 offset:12288
	s_branch .Lat_end

; #define A_LOAD(kt) do { const char* kb_ = kg0 + (size_t)(kt) * 16384; const char* vb_ = vg0 + (size_t)(kt) * 16384; \
;             _Pragma("unroll") for (int i = 0; i < 2; ++i) { kreg[i] = *(const u32x4*)(kb_ + i * 8192 + koff); vreg[i] = *(const u32x4*)(vb_ + i * 8192 + koff); } } while (0)
; #define A_STORE(buf) do { _Pragma("unroll") for (int i = 0; i < 2; ++i) { \
;             *(LAS u32x4*)(lds + (buf) * ABUF + i * (32 * AK_STR) + klo) = kreg[i]; \
;             *(LAS u32x4*)(lds + (buf) * ABUF + i * (64 * AV_STR) + vlo) = vreg[i]; } } while (0)
; __device__ __forceinline__ void phase_attn_a(const bf16_t* Qb, const bf16_t* Kb, const bf16_t* Vt, bf16_t* O, const float* lam, const float* subg, const float* qg, const float* kg, float lam_init, LAS unsigned char* lds, int wv) {
;     ...
;         for (int kt = 0; kt < ntile; ++kt) {
;             const int st3 = kt % 3, stn = (kt + 1) % 3, stw = (kt + 2) % 3;
;             if (kt + 2 < ntile) A_LOAD(kt + 2);
;             if (kt * 64 <= q0 + 31) {
;                 const bool domask = kt * 64 + 63 > q0;
;                 const bool has_next = (kt + 1 < ntile) && ((kt + 1) * 64 <= q0 + 31);
;                 const int kbase = kt * 64;
;                 attn_tile_pf<8>(kf, lds + stn * ABUF + cm * 128, has_next, AK_STR, lds + st3 * ABUF + AK_BYTES, AV_STR, Qf, oacc, coff, lrow, c2, domask,
;                                 [=](int ki, int qi) { return kbase + ki <= q0 + qi; }, fr, fq);
;             }
;             if (kt + 2 < ntile) A_STORE(stw);
;             __syncthreads();
.Lat_w1:
	s_cmp_eq_u32 s66, s30
	s_barrier
	s_cbranch_scc1 .LBB0_1964
	s_mov_b32 s31, s30
	s_branch .Lat_loop
